# cached instead of nt (streaming) accesses for the half-line tile patterns: final output stores, x / h1 tile loads in the GEMM epilogues
# speedup vs baseline: 1.0513x; 1.0174x over previous
;     __device__ __forceinline__ void operator()(const Acc& acc, const Unit& u, int wr, int wc, int fr, int fq) const {
;         const int col0 = u.pn * BM + wc * 32 + 4 * fq;
;         const float* gt = gate + (size_t)((u.pm * BM) >> 12) * NADA;
;         f32x4 gvv[2][2];
; #pragma unroll
;         for (int bj = 0; bj < 2; ++bj)
; #pragma unroll
;             for (int n = 0; n < 2; ++n) gvv[bj][n] = *(const f32x4*)(gt + col0 + bj * HALF + n * 16);
; #pragma unroll
;         for (int bj = 0; bj < 2; ++bj)
; #pragma unroll
;             for (int ai = 0; ai < 2; ++ai) {
;                 f32x4 bsv[4][2];
; #pragma unroll
;                 for (int m = 0; m < 4; ++m)
; #pragma unroll
;                     for (int n = 0; n < 2; ++n) { const size_t off = (size_t)(u.pm * BM + ai * HALF + wr * 64 + m * 16 + fr) * DMODEL + col0 + bj * HALF + n * 16; bsv[m][n] = __builtin_nontemporal_load((const f32x4*)(base + off)); }
; #pragma unroll
;                 for (int m = 0; m < 4; ++m)
; #pragma unroll
;                     for (int n = 0; n < 2; ++n) { const size_t off = (size_t)(u.pm * BM + ai * HALF + wr * 64 + m * 16 + fr) * DMODEL + col0 + bj * HALF + n * 16;
;                         *(f32x4*)(out + off) = bsv[m][n] * ALPHA + gvv[bj][n] * acc[ai][bj][m][n]; } }
.LBB0_906:
	v_lshl_or_b32 v130, s33, 8, v177
	v_lshl_add_u32 v194, s24, 8, v1
	s_ashr_i32 s17, s24, 4
	v_ashrrev_i32_e32 v131, 31, v130
	s_mul_hi_i32 s19, s17, 0xc000
	s_mul_i32 s17, s17, 0xc000
	v_lshlrev_b64 v[174:175], 2, v[130:131]
	s_add_u32 s26, s43, s17
	s_addc_u32 s27, s44, s19
	v_lshl_add_u64 v[218:219], s[6:7], 0, v[174:175]
	v_lshlrev_b32_e32 v220, 13, v194
	v_mov_b32_e32 v221, 0
	v_lshl_add_u64 v[158:159], v[218:219], 0, v[220:221]
	v_lshl_add_u64 v[160:161], s[4:5], 0, v[174:175]
	v_lshl_add_u64 v[160:161], v[160:161], 0, v[220:221]
	v_lshl_add_u64 v[166:167], s[26:27], 0, v[174:175]
	global_load_dwordx4 v[142:145], v[166:167], off
	global_load_dwordx4 v[138:141], v[166:167], off offset:64
	global_load_dwordx4 v[134:137], v[166:167], off offset:512
	global_load_dwordx4 v[130:133], v[166:167], off offset:576
	s_add_u32 s60, s43, 0x19c000
	s_addc_u32 s61, s44, 0
	global_load_dwordx4 v[198:201], v[158:159], off
	global_load_dwordx4 v[202:205], v[158:159], off offset:64
	global_load_dwordx4 v[206:209], v[158:159], off offset:512
	global_load_dwordx4 v[210:213], v[158:159], off offset:576
	s_mov_b64 s[56:57], 0x20000
	v_lshl_add_u64 v[162:163], v[158:159], 0, s[56:57]
	global_load_dwordx4 v[222:225], v[162:163], off
	global_load_dwordx4 v[226:229], v[162:163], off offset:64
	global_load_dwordx4 v[230:233], v[162:163], off offset:512
	global_load_dwordx4 v[234:237], v[162:163], off offset:576
	s_waitcnt vmcnt(4)
	v_pk_mul_f32 v[198:199], v[198:199], s[14:15] op_sel_hi:[1,0]
	v_pk_mul_f32 v[200:201], v[200:201], s[14:15] op_sel_hi:[1,0]
	v_pk_mul_f32 v[202:203], v[202:203], s[14:15] op_sel_hi:[1,0]
	v_pk_mul_f32 v[204:205], v[204:205], s[14:15] op_sel_hi:[1,0]
	v_pk_mul_f32 v[206:207], v[206:207], s[14:15] op_sel_hi:[1,0]
	v_pk_mul_f32 v[208:209], v[208:209], s[14:15] op_sel_hi:[1,0]
	v_pk_mul_f32 v[210:211], v[210:211], s[14:15] op_sel_hi:[1,0]
	v_pk_mul_f32 v[212:213], v[212:213], s[14:15] op_sel_hi:[1,0]
	v_pk_fma_f32 v[126:127], v[126:127], v[142:143], v[198:199]
	v_pk_fma_f32 v[128:129], v[128:129], v[144:145], v[200:201]
	v_pk_fma_f32 v[122:123], v[122:123], v[138:139], v[202:203]
	v_pk_fma_f32 v[124:125], v[124:125], v[140:141], v[204:205]
	v_pk_fma_f32 v[62:63], v[62:63], v[134:135], v[206:207]
	v_pk_fma_f32 v[64:65], v[64:65], v[136:137], v[208:209]
	v_pk_fma_f32 v[58:59], v[58:59], v[130:131], v[210:211]
	v_pk_fma_f32 v[60:61], v[60:61], v[132:133], v[212:213]
	global_store_dwordx4 v[160:161], v[126:129], off
	global_store_dwordx4 v[160:161], v[122:125], off offset:64
	global_store_dwordx4 v[160:161], v[62:65], off offset:512
	global_store_dwordx4 v[160:161], v[58:61], off offset:576
	s_mov_b64 s[56:57], 0x40000
	v_lshl_add_u64 v[162:163], v[158:159], 0, s[56:57]
	global_load_dwordx4 v[198:201], v[162:163], off
	global_load_dwordx4 v[202:205], v[162:163], off offset:64
	global_load_dwordx4 v[206:209], v[162:163], off offset:512
	global_load_dwordx4 v[210:213], v[162:163], off offset:576
	s_waitcnt vmcnt(8)
	v_pk_mul_f32 v[222:223], v[222:223], s[14:15] op_sel_hi:[1,0]
	v_pk_mul_f32 v[224:225], v[224:225], s[14:15] op_sel_hi:[1,0]
	v_pk_mul_f32 v[226:227], v[226:227], s[14:15] op_sel_hi:[1,0]
	v_pk_mul_f32 v[228:229], v[228:229], s[14:15] op_sel_hi:[1,0]
	v_pk_mul_f32 v[230:231], v[230:231], s[14:15] op_sel_hi:[1,0]
	v_pk_mul_f32 v[232:233], v[232:233], s[14:15] op_sel_hi:[1,0]
	v_pk_mul_f32 v[234:235], v[234:235], s[14:15] op_sel_hi:[1,0]
	v_pk_mul_f32 v[236:237], v[236:237], s[14:15] op_sel_hi:[1,0]
	v_pk_fma_f32 v[118:119], v[118:119], v[142:143], v[222:223]
	v_pk_fma_f32 v[120:121], v[120:121], v[144:145], v[224:225]
	v_pk_fma_f32 v[114:115], v[114:115], v[138:139], v[226:227]
	v_pk_fma_f32 v[116:117], v[116:117], v[140:141], v[228:229]
	v_pk_fma_f32 v[54:55], v[54:55], v[134:135], v[230:231]
	v_pk_fma_f32 v[56:57], v[56:57], v[136:137], v[232:233]
	v_pk_fma_f32 v[50:51], v[50:51], v[130:131], v[234:235]
	v_pk_fma_f32 v[52:53], v[52:53], v[132:133], v[236:237]
	s_mov_b64 s[58:59], 0x20000
	v_lshl_add_u64 v[164:165], v[160:161], 0, s[58:59]
	global_store_dwordx4 v[164:165], v[118:121], off
	global_store_dwordx4 v[164:165], v[114:117], off offset:64
	global_store_dwordx4 v[164:165], v[54:57], off offset:512
	global_store_dwordx4 v[164:165], v[50:53], off offset:576
	s_mov_b64 s[56:57], 0x60000
	v_lshl_add_u64 v[162:163], v[158:159], 0, s[56:57]
	global_load_dwordx4 v[222:225], v[162:163], off
	global_load_dwordx4 v[226:229], v[162:163], off offset:64
	global_load_dwordx4 v[230:233], v[162:163], off offset:512
	global_load_dwordx4 v[234:237], v[162:163], off offset:576
	s_waitcnt vmcnt(8)
	v_pk_mul_f32 v[198:199], v[198:199], s[14:15] op_sel_hi:[1,0]
	v_pk_mul_f32 v[200:201], v[200:201], s[14:15] op_sel_hi:[1,0]
	v_pk_mul_f32 v[202:203], v[202:203], s[14:15] op_sel_hi:[1,0]
	v_pk_mul_f32 v[204:205], v[204:205], s[14:15] op_sel_hi:[1,0]
	v_pk_mul_f32 v[206:207], v[206:207], s[14:15] op_sel_hi:[1,0]
	v_pk_mul_f32 v[208:209], v[208:209], s[14:15] op_sel_hi:[1,0]
	v_pk_mul_f32 v[210:211], v[210:211], s[14:15] op_sel_hi:[1,0]
	v_pk_mul_f32 v[212:213], v[212:213], s[14:15] op_sel_hi:[1,0]
	v_pk_fma_f32 v[110:111], v[110:111], v[142:143], v[198:199]
	v_pk_fma_f32 v[112:113], v[112:113], v[144:145], v[200:201]
	v_pk_fma_f32 v[106:107], v[106:107], v[138:139], v[202:203]
	v_pk_fma_f32 v[108:109], v[108:109], v[140:141], v[204:205]
	v_pk_fma_f32 v[46:47], v[46:47], v[134:135], v[206:207]
	v_pk_fma_f32 v[48:49], v[48:49], v[136:137], v[208:209]
	v_pk_fma_f32 v[42:43], v[42:43], v[130:131], v[210:211]
	v_pk_fma_f32 v[44:45], v[44:45], v[132:133], v[212:213]
	s_mov_b64 s[58:59], 0x40000
	v_lshl_add_u64 v[164:165], v[160:161], 0, s[58:59]
	global_store_dwordx4 v[164:165], v[110:113], off
	global_store_dwordx4 v[164:165], v[106:109], off offset:64
	global_store_dwordx4 v[164:165], v[46:49], off offset:512
	global_store_dwordx4 v[164:165], v[42:45], off offset:576
	s_mov_b64 s[56:57], 0x100000
	v_lshl_add_u64 v[162:163], v[158:159], 0, s[56:57]
	global_load_dwordx4 v[198:201], v[162:163], off
	global_load_dwordx4 v[202:205], v[162:163], off offset:64
	global_load_dwordx4 v[206:209], v[162:163], off offset:512
	global_load_dwordx4 v[210:213], v[162:163], off offset:576
	s_waitcnt vmcnt(8)
;     __device__ __forceinline__ void operator()(const Acc& acc, const Unit& u, int wr, int wc, int fr, int fq) const {
;     ...
;                 for (int m = 0; m < 4; ++m)
; #pragma unroll
;                     for (int n = 0; n < 2; ++n) { const size_t off = (size_t)(u.pm * BM + ai * HALF + wr * 64 + m * 16 + fr) * DMODEL + col0 + bj * HALF + n * 16; bsv[m][n] = __builtin_nontemporal_load((const f32x4*)(base + off)); }
; #pragma unroll
;                 for (int m = 0; m < 4; ++m)
; #pragma unroll
;                     for (int n = 0; n < 2; ++n) { const size_t off = (size_t)(u.pm * BM + ai * HALF + wr * 64 + m * 16 + fr) * DMODEL + col0 + bj * HALF + n * 16;
;                         *(f32x4*)(out + off) = bsv[m][n] * ALPHA + gvv[bj][n] * acc[ai][bj][m][n]; } }
	v_pk_mul_f32 v[222:223], v[222:223], s[14:15] op_sel_hi:[1,0]
	v_pk_mul_f32 v[224:225], v[224:225], s[14:15] op_sel_hi:[1,0]
	v_pk_mul_f32 v[226:227], v[226:227], s[14:15] op_sel_hi:[1,0]
	v_pk_mul_f32 v[228:229], v[228:229], s[14:15] op_sel_hi:[1,0]
	v_pk_mul_f32 v[230:231], v[230:231], s[14:15] op_sel_hi:[1,0]
	v_pk_mul_f32 v[232:233], v[232:233], s[14:15] op_sel_hi:[1,0]
	v_pk_mul_f32 v[234:235], v[234:235], s[14:15] op_sel_hi:[1,0]
	v_pk_mul_f32 v[236:237], v[236:237], s[14:15] op_sel_hi:[1,0]
	v_pk_fma_f32 v[102:103], v[102:103], v[142:143], v[222:223]
	v_pk_fma_f32 v[104:105], v[104:105], v[144:145], v[224:225]
	v_pk_fma_f32 v[98:99], v[98:99], v[138:139], v[226:227]
	v_pk_fma_f32 v[100:101], v[100:101], v[140:141], v[228:229]
	v_pk_fma_f32 v[38:39], v[38:39], v[134:135], v[230:231]
	v_pk_fma_f32 v[40:41], v[40:41], v[136:137], v[232:233]
	v_pk_fma_f32 v[34:35], v[34:35], v[130:131], v[234:235]
	v_pk_fma_f32 v[36:37], v[36:37], v[132:133], v[236:237]
	s_mov_b64 s[58:59], 0x60000
	v_lshl_add_u64 v[164:165], v[160:161], 0, s[58:59]
	global_store_dwordx4 v[164:165], v[102:105], off
	global_store_dwordx4 v[164:165], v[98:101], off offset:64
	global_store_dwordx4 v[164:165], v[38:41], off offset:512
	global_store_dwordx4 v[164:165], v[34:37], off offset:576
	s_mov_b64 s[56:57], 0x120000
	v_lshl_add_u64 v[162:163], v[158:159], 0, s[56:57]
	global_load_dwordx4 v[222:225], v[162:163], off
	global_load_dwordx4 v[226:229], v[162:163], off offset:64
	global_load_dwordx4 v[230:233], v[162:163], off offset:512
	global_load_dwordx4 v[234:237], v[162:163], off offset:576
	s_waitcnt vmcnt(8)
	v_pk_mul_f32 v[198:199], v[198:199], s[14:15] op_sel_hi:[1,0]
	v_pk_mul_f32 v[200:201], v[200:201], s[14:15] op_sel_hi:[1,0]
	v_pk_mul_f32 v[202:203], v[202:203], s[14:15] op_sel_hi:[1,0]
	v_pk_mul_f32 v[204:205], v[204:205], s[14:15] op_sel_hi:[1,0]
	v_pk_mul_f32 v[206:207], v[206:207], s[14:15] op_sel_hi:[1,0]
	v_pk_mul_f32 v[208:209], v[208:209], s[14:15] op_sel_hi:[1,0]
	v_pk_mul_f32 v[210:211], v[210:211], s[14:15] op_sel_hi:[1,0]
	v_pk_mul_f32 v[212:213], v[212:213], s[14:15] op_sel_hi:[1,0]
	v_pk_fma_f32 v[94:95], v[94:95], v[142:143], v[198:199]
	v_pk_fma_f32 v[96:97], v[96:97], v[144:145], v[200:201]
	v_pk_fma_f32 v[90:91], v[90:91], v[138:139], v[202:203]
	v_pk_fma_f32 v[92:93], v[92:93], v[140:141], v[204:205]
	v_pk_fma_f32 v[30:31], v[30:31], v[134:135], v[206:207]
	v_pk_fma_f32 v[32:33], v[32:33], v[136:137], v[208:209]
	v_pk_fma_f32 v[26:27], v[26:27], v[130:131], v[210:211]
	v_pk_fma_f32 v[28:29], v[28:29], v[132:133], v[212:213]
	s_mov_b64 s[58:59], 0x100000
	v_lshl_add_u64 v[164:165], v[160:161], 0, s[58:59]
	global_store_dwordx4 v[164:165], v[94:97], off
	global_store_dwordx4 v[164:165], v[90:93], off offset:64
	global_store_dwordx4 v[164:165], v[30:33], off offset:512
	global_store_dwordx4 v[164:165], v[26:29], off offset:576
	s_mov_b64 s[56:57], 0x140000
	v_lshl_add_u64 v[162:163], v[158:159], 0, s[56:57]
	global_load_dwordx4 v[198:201], v[162:163], off
	global_load_dwordx4 v[202:205], v[162:163], off offset:64
	global_load_dwordx4 v[206:209], v[162:163], off offset:512
	global_load_dwordx4 v[210:213], v[162:163], off offset:576
	s_waitcnt vmcnt(8)
	v_pk_mul_f32 v[222:223], v[222:223], s[14:15] op_sel_hi:[1,0]
	v_pk_mul_f32 v[224:225], v[224:225], s[14:15] op_sel_hi:[1,0]
	v_pk_mul_f32 v[226:227], v[226:227], s[14:15] op_sel_hi:[1,0]
	v_pk_mul_f32 v[228:229], v[228:229], s[14:15] op_sel_hi:[1,0]
	v_pk_mul_f32 v[230:231], v[230:231], s[14:15] op_sel_hi:[1,0]
	v_pk_mul_f32 v[232:233], v[232:233], s[14:15] op_sel_hi:[1,0]
	v_pk_mul_f32 v[234:235], v[234:235], s[14:15] op_sel_hi:[1,0]
	v_pk_mul_f32 v[236:237], v[236:237], s[14:15] op_sel_hi:[1,0]
	v_pk_fma_f32 v[86:87], v[86:87], v[142:143], v[222:223]
	v_pk_fma_f32 v[88:89], v[88:89], v[144:145], v[224:225]
	v_pk_fma_f32 v[82:83], v[82:83], v[138:139], v[226:227]
	v_pk_fma_f32 v[84:85], v[84:85], v[140:141], v[228:229]
	v_pk_fma_f32 v[22:23], v[22:23], v[134:135], v[230:231]
	v_pk_fma_f32 v[24:25], v[24:25], v[136:137], v[232:233]
	v_pk_fma_f32 v[18:19], v[18:19], v[130:131], v[234:235]
	v_pk_fma_f32 v[20:21], v[20:21], v[132:133], v[236:237]
	s_mov_b64 s[58:59], 0x120000
	v_lshl_add_u64 v[164:165], v[160:161], 0, s[58:59]
	global_store_dwordx4 v[164:165], v[86:89], off
	global_store_dwordx4 v[164:165], v[82:85], off offset:64
	global_store_dwordx4 v[164:165], v[22:25], off offset:512
	global_store_dwordx4 v[164:165], v[18:21], off offset:576
	s_mov_b64 s[56:57], 0x160000
	v_lshl_add_u64 v[162:163], v[158:159], 0, s[56:57]
	global_load_dwordx4 v[222:225], v[162:163], off
	global_load_dwordx4 v[226:229], v[162:163], off offset:64
	global_load_dwordx4 v[230:233], v[162:163], off offset:512
	global_load_dwordx4 v[234:237], v[162:163], off offset:576
	s_waitcnt vmcnt(8)
	v_pk_mul_f32 v[198:199], v[198:199], s[14:15] op_sel_hi:[1,0]
	v_pk_mul_f32 v[200:201], v[200:201], s[14:15] op_sel_hi:[1,0]
	v_pk_mul_f32 v[202:203], v[202:203], s[14:15] op_sel_hi:[1,0]
	v_pk_mul_f32 v[204:205], v[204:205], s[14:15] op_sel_hi:[1,0]
	v_pk_mul_f32 v[206:207], v[206:207], s[14:15] op_sel_hi:[1,0]
	v_pk_mul_f32 v[208:209], v[208:209], s[14:15] op_sel_hi:[1,0]
	v_pk_mul_f32 v[210:211], v[210:211], s[14:15] op_sel_hi:[1,0]
	v_pk_mul_f32 v[212:213], v[212:213], s[14:15] op_sel_hi:[1,0]
	v_pk_fma_f32 v[78:79], v[78:79], v[142:143], v[198:199]
	v_pk_fma_f32 v[80:81], v[80:81], v[144:145], v[200:201]
	v_pk_fma_f32 v[74:75], v[74:75], v[138:139], v[202:203]
	v_pk_fma_f32 v[76:77], v[76:77], v[140:141], v[204:205]
	v_pk_fma_f32 v[14:15], v[14:15], v[134:135], v[206:207]
	v_pk_fma_f32 v[16:17], v[16:17], v[136:137], v[208:209]
	v_pk_fma_f32 v[10:11], v[10:11], v[130:131], v[210:211]
	v_pk_fma_f32 v[12:13], v[12:13], v[132:133], v[212:213]
	s_mov_b64 s[58:59], 0x140000
	v_lshl_add_u64 v[164:165], v[160:161], 0, s[58:59]
	global_store_dwordx4 v[164:165], v[78:81], off
	global_store_dwordx4 v[164:165], v[74:77], off offset:64
	global_store_dwordx4 v[164:165], v[14:17], off offset:512
	global_store_dwordx4 v[164:165], v[10:13], off offset:576
	s_waitcnt vmcnt(4)
;     __device__ __forceinline__ void operator()(const Acc& acc, const Unit& u, int wr, int wc, int fr, int fq) const {
;     ...
;                 for (int m = 0; m < 4; ++m)
; #pragma unroll
;                     for (int n = 0; n < 2; ++n) { const size_t off = (size_t)(u.pm * BM + ai * HALF + wr * 64 + m * 16 + fr) * DMODEL + col0 + bj * HALF + n * 16;
;                         *(f32x4*)(out + off) = bsv[m][n] * ALPHA + gvv[bj][n] * acc[ai][bj][m][n]; } }
; __global__ void __launch_bounds__(512, 2) fwd_kernel(Args a) {
;     ...
;             for (int q = 0; q < 4; ++q) { float s_ = 0.f;
; #pragma unroll
;                 for (int j = 0; j < 8; ++j) s_ += (vr[q][j][0] + vr[q][j][1]) + (vr[q][j][2] + vr[q][j][3]);
;                 sm[q] = wave_sum(s_) * (1.0f / DMODEL); }
	v_pk_mul_f32 v[222:223], v[222:223], s[14:15] op_sel_hi:[1,0]
	v_pk_mul_f32 v[224:225], v[224:225], s[14:15] op_sel_hi:[1,0]
	v_pk_mul_f32 v[226:227], v[226:227], s[14:15] op_sel_hi:[1,0]
	v_pk_mul_f32 v[228:229], v[228:229], s[14:15] op_sel_hi:[1,0]
	v_pk_mul_f32 v[230:231], v[230:231], s[14:15] op_sel_hi:[1,0]
	v_pk_mul_f32 v[232:233], v[232:233], s[14:15] op_sel_hi:[1,0]
	v_pk_mul_f32 v[234:235], v[234:235], s[14:15] op_sel_hi:[1,0]
	v_pk_mul_f32 v[236:237], v[236:237], s[14:15] op_sel_hi:[1,0]
	v_pk_fma_f32 v[70:71], v[70:71], v[142:143], v[222:223]
	v_pk_fma_f32 v[72:73], v[72:73], v[144:145], v[224:225]
	v_pk_fma_f32 v[66:67], v[66:67], v[138:139], v[226:227]
	v_pk_fma_f32 v[68:69], v[68:69], v[140:141], v[228:229]
	v_pk_fma_f32 v[6:7], v[6:7], v[134:135], v[230:231]
	v_pk_fma_f32 v[8:9], v[8:9], v[136:137], v[232:233]
	v_pk_fma_f32 v[2:3], v[2:3], v[130:131], v[234:235]
	v_pk_fma_f32 v[4:5], v[4:5], v[132:133], v[236:237]
	s_mov_b64 s[58:59], 0x160000
	v_lshl_add_u64 v[164:165], v[160:161], 0, s[58:59]
	global_store_dwordx4 v[164:165], v[70:73], off
	global_store_dwordx4 v[164:165], v[66:69], off offset:64
	global_store_dwordx4 v[164:165], v[6:9], off offset:512
	global_store_dwordx4 v[164:165], v[2:5], off offset:576
	v_pk_add_f32 v[198:199], v[126:127], v[128:129]
	v_pk_add_f32 v[198:199], v[198:199], v[122:123]
	v_pk_add_f32 v[198:199], v[198:199], v[124:125]
	v_pk_add_f32 v[198:199], v[198:199], v[62:63]
	v_pk_add_f32 v[198:199], v[198:199], v[64:65]
	v_pk_add_f32 v[198:199], v[198:199], v[58:59]
	v_pk_add_f32 v[198:199], v[198:199], v[60:61]
	v_add_f32_e32 v146, v198, v199
	v_pk_add_f32 v[200:201], v[118:119], v[120:121]
	v_pk_add_f32 v[200:201], v[200:201], v[114:115]
	v_pk_add_f32 v[200:201], v[200:201], v[116:117]
	v_pk_add_f32 v[200:201], v[200:201], v[54:55]
	v_pk_add_f32 v[200:201], v[200:201], v[56:57]
	v_pk_add_f32 v[200:201], v[200:201], v[50:51]
	v_pk_add_f32 v[200:201], v[200:201], v[52:53]
	v_add_f32_e32 v147, v200, v201
	v_pk_add_f32 v[202:203], v[110:111], v[112:113]
	v_pk_add_f32 v[202:203], v[202:203], v[106:107]
	v_pk_add_f32 v[202:203], v[202:203], v[108:109]
	v_pk_add_f32 v[202:203], v[202:203], v[46:47]
	v_pk_add_f32 v[202:203], v[202:203], v[48:49]
	v_pk_add_f32 v[202:203], v[202:203], v[42:43]
	v_pk_add_f32 v[202:203], v[202:203], v[44:45]
	v_add_f32_e32 v148, v202, v203
	v_pk_add_f32 v[204:205], v[102:103], v[104:105]
	v_pk_add_f32 v[204:205], v[204:205], v[98:99]
	v_pk_add_f32 v[204:205], v[204:205], v[100:101]
	v_pk_add_f32 v[204:205], v[204:205], v[38:39]
	v_pk_add_f32 v[204:205], v[204:205], v[40:41]
	v_pk_add_f32 v[204:205], v[204:205], v[34:35]
	v_pk_add_f32 v[204:205], v[204:205], v[36:37]
	v_add_f32_e32 v149, v204, v205
	v_pk_add_f32 v[198:199], v[94:95], v[96:97]
	v_pk_add_f32 v[198:199], v[198:199], v[90:91]
	v_pk_add_f32 v[198:199], v[198:199], v[92:93]
	v_pk_add_f32 v[198:199], v[198:199], v[30:31]
	v_pk_add_f32 v[198:199], v[198:199], v[32:33]
	v_pk_add_f32 v[198:199], v[198:199], v[26:27]
	v_pk_add_f32 v[198:199], v[198:199], v[28:29]
	v_add_f32_e32 v150, v198, v199
	v_pk_add_f32 v[200:201], v[86:87], v[88:89]
	v_pk_add_f32 v[200:201], v[200:201], v[82:83]
	v_pk_add_f32 v[200:201], v[200:201], v[84:85]
	v_pk_add_f32 v[200:201], v[200:201], v[22:23]
	v_pk_add_f32 v[200:201], v[200:201], v[24:25]
	v_pk_add_f32 v[200:201], v[200:201], v[18:19]
	v_pk_add_f32 v[200:201], v[200:201], v[20:21]
	v_add_f32_e32 v151, v200, v201
	v_pk_add_f32 v[202:203], v[78:79], v[80:81]
	v_pk_add_f32 v[202:203], v[202:203], v[74:75]
	v_pk_add_f32 v[202:203], v[202:203], v[76:77]
	v_pk_add_f32 v[202:203], v[202:203], v[14:15]
	v_pk_add_f32 v[202:203], v[202:203], v[16:17]
	v_pk_add_f32 v[202:203], v[202:203], v[10:11]
	v_pk_add_f32 v[202:203], v[202:203], v[12:13]
	v_add_f32_e32 v152, v202, v203
	v_pk_add_f32 v[204:205], v[70:71], v[72:73]
	v_pk_add_f32 v[204:205], v[204:205], v[66:67]
	v_pk_add_f32 v[204:205], v[204:205], v[68:69]
	v_pk_add_f32 v[204:205], v[204:205], v[6:7]
	v_pk_add_f32 v[204:205], v[204:205], v[8:9]
	v_pk_add_f32 v[204:205], v[204:205], v[2:3]
	v_pk_add_f32 v[204:205], v[204:205], v[4:5]
	v_add_f32_e32 v153, v204, v205
	v_mov_b32_e32 v238, v146
	v_mov_b32_e32 v246, v146
	v_mov_b32_e32 v239, v147
	v_mov_b32_e32 v247, v147
	v_mov_b32_e32 v240, v148
	v_mov_b32_e32 v248, v148
	v_mov_b32_e32 v241, v149
	v_mov_b32_e32 v249, v149
	v_mov_b32_e32 v242, v150
	v_mov_b32_e32 v250, v150
	v_mov_b32_e32 v243, v151
	v_mov_b32_e32 v251, v151
	v_mov_b32_e32 v244, v152
	v_mov_b32_e32 v252, v152
	v_mov_b32_e32 v245, v153
	v_mov_b32_e32 v253, v153
	s_nop 1
	v_permlane16_swap_b32_e32 v238, v246
	v_permlane16_swap_b32_e32 v239, v247
	v_permlane16_swap_b32_e32 v240, v248
	v_permlane16_swap_b32_e32 v241, v249
	v_permlane16_swap_b32_e32 v242, v250
	v_permlane16_swap_b32_e32 v243, v251
	v_permlane16_swap_b32_e32 v244, v252
	v_permlane16_swap_b32_e32 v245, v253
	s_nop 1
	v_add_f32_e32 v146, v238, v246
	v_add_f32_e32 v147, v239, v247
	v_add_f32_e32 v148, v240, v248
	v_add_f32_e32 v149, v241, v249
	v_add_f32_e32 v150, v242, v250
	v_add_f32_e32 v151, v243, v251
	v_add_f32_e32 v152, v244, v252
	v_add_f32_e32 v153, v245, v253
	v_mov_b32_e32 v238, v146
	v_mov_b32_e32 v246, v146
	v_mov_b32_e32 v239, v147
	v_mov_b32_e32 v247, v147
	v_mov_b32_e32 v240, v148
	v_mov_b32_e32 v248, v148
	v_mov_b32_e32 v241, v149
	v_mov_b32_e32 v249, v149
	v_mov_b32_e32 v242, v150
	v_mov_b32_e32 v250, v150
	v_mov_b32_e32 v243, v151
	v_mov_b32_e32 v251, v151
	v_mov_b32_e32 v244, v152
	v_mov_b32_e32 v252, v152
	v_mov_b32_e32 v245, v153
	v_mov_b32_e32 v253, v153
	s_nop 1
	v_permlane32_swap_b32_e32 v238, v246
	v_permlane32_swap_b32_e32 v239, v247
	v_permlane32_swap_b32_e32 v240, v248
	v_permlane32_swap_b32_e32 v241, v249
	v_permlane32_swap_b32_e32 v242, v250
	v_permlane32_swap_b32_e32 v243, v251
	v_permlane32_swap_b32_e32 v244, v252
	v_permlane32_swap_b32_e32 v245, v253
	s_nop 1
	v_add_f32_e32 v146, v238, v246
	v_add_f32_e32 v147, v239, v247
	v_add_f32_e32 v148, v240, v248
	v_add_f32_e32 v149, v241, v249
	v_add_f32_e32 v150, v242, v250
	v_add_f32_e32 v151, v243, v251
	v_add_f32_e32 v152, v244, v252
	v_add_f32_e32 v153, v245, v253
	s_and_b32 s56, s96, 3
	s_lshl_b32 s56, s56, 2
	v_lshl_add_u32 v214, v1, 4, s56
	v_lshlrev_b32_e32 v215, 4, v1
	s_waitcnt lgkmcnt(0)
	s_barrier
; __global__ void __launch_bounds__(512, 2) fwd_kernel(Args a) {
;     ...
;             for (int q = 0; q < 4; ++q) { float s_ = 0.f;
; #pragma unroll
;                 for (int j = 0; j < 8; ++j) s_ += (vr[q][j][0] + vr[q][j][1]) + (vr[q][j][2] + vr[q][j][3]);
;                 sm[q] = wave_sum(s_) * (1.0f / DMODEL); }
; #pragma unroll
;             for (int q = 0; q < 4; ++q) { float s2 = 0.f;
; #pragma unroll
;                 for (int j = 0; j < 8; ++j) { vr[q][j] = vr[q][j] - sm[q]; s2 += (vr[q][j][0] * vr[q][j][0] + vr[q][j][1] * vr[q][j][1]) + (vr[q][j][2] * vr[q][j][2] + vr[q][j][3] * vr[q][j][3]); }
;                 qq[q] = wave_sum(s2); rs[q] = 1.0f / sqrtf(qq[q] * (1.0f / DMODEL) + LN_EPS); }
	ds_write_b32 v214, v146
	ds_write_b32 v214, v147 offset:256
	ds_write_b32 v214, v148 offset:512
	ds_write_b32 v214, v149 offset:768
	ds_write_b32 v214, v150 offset:2048
	ds_write_b32 v214, v151 offset:2304
	ds_write_b32 v214, v152 offset:2560
	ds_write_b32 v214, v153 offset:2816
	s_waitcnt lgkmcnt(0)
	s_barrier
	ds_read_b128 v[198:201], v215
	ds_read_b128 v[202:205], v215 offset:256
	ds_read_b128 v[206:209], v215 offset:512
	ds_read_b128 v[210:213], v215 offset:768
	ds_read_b128 v[222:225], v215 offset:2048
	ds_read_b128 v[226:229], v215 offset:2304
	ds_read_b128 v[230:233], v215 offset:2560
	ds_read_b128 v[234:237], v215 offset:2816
	s_waitcnt lgkmcnt(0)
	v_add_f32_e32 v130, v198, v199
	v_add_f32_e32 v130, v130, v200
	v_add_f32_e32 v130, v130, v201
	v_mul_f32_e32 v178, 0x3b800000, v130
	v_add_f32_e32 v132, v202, v203
	v_add_f32_e32 v132, v132, v204
	v_add_f32_e32 v132, v132, v205
	v_mul_f32_e32 v180, 0x3b800000, v132
	v_add_f32_e32 v134, v206, v207
	v_add_f32_e32 v134, v134, v208
	v_add_f32_e32 v134, v134, v209
	v_mul_f32_e32 v182, 0x3b800000, v134
	v_add_f32_e32 v136, v210, v211
	v_add_f32_e32 v136, v136, v212
	v_add_f32_e32 v136, v136, v213
	v_mul_f32_e32 v184, 0x3b800000, v136
	v_add_f32_e32 v138, v222, v223
	v_add_f32_e32 v138, v138, v224
	v_add_f32_e32 v138, v138, v225
	v_mul_f32_e32 v186, 0x3b800000, v138
	v_add_f32_e32 v140, v226, v227
	v_add_f32_e32 v140, v140, v228
	v_add_f32_e32 v140, v140, v229
	v_mul_f32_e32 v188, 0x3b800000, v140
	v_add_f32_e32 v142, v230, v231
	v_add_f32_e32 v142, v142, v232
	v_add_f32_e32 v142, v142, v233
	v_mul_f32_e32 v190, 0x3b800000, v142
	v_add_f32_e32 v144, v234, v235
	v_add_f32_e32 v144, v144, v236
	v_add_f32_e32 v144, v144, v237
	v_mul_f32_e32 v192, 0x3b800000, v144
	v_pk_add_f32 v[200:201], v[126:127], v[178:179] op_sel_hi:[1,0] neg_lo:[0,1] neg_hi:[0,1]
	v_pk_mul_f32 v[198:199], v[200:201], v[200:201]
	v_pk_add_f32 v[200:201], v[128:129], v[178:179] op_sel_hi:[1,0] neg_lo:[0,1] neg_hi:[0,1]
	v_pk_fma_f32 v[198:199], v[200:201], v[200:201], v[198:199]
	v_pk_add_f32 v[200:201], v[122:123], v[178:179] op_sel_hi:[1,0] neg_lo:[0,1] neg_hi:[0,1]
	v_pk_fma_f32 v[198:199], v[200:201], v[200:201], v[198:199]
	v_pk_add_f32 v[200:201], v[124:125], v[178:179] op_sel_hi:[1,0] neg_lo:[0,1] neg_hi:[0,1]
	v_pk_fma_f32 v[198:199], v[200:201], v[200:201], v[198:199]
	v_pk_add_f32 v[200:201], v[62:63], v[178:179] op_sel_hi:[1,0] neg_lo:[0,1] neg_hi:[0,1]
	v_pk_fma_f32 v[198:199], v[200:201], v[200:201], v[198:199]
	v_pk_add_f32 v[200:201], v[64:65], v[178:179] op_sel_hi:[1,0] neg_lo:[0,1] neg_hi:[0,1]
	v_pk_fma_f32 v[198:199], v[200:201], v[200:201], v[198:199]
	v_pk_add_f32 v[200:201], v[58:59], v[178:179] op_sel_hi:[1,0] neg_lo:[0,1] neg_hi:[0,1]
	v_pk_fma_f32 v[198:199], v[200:201], v[200:201], v[198:199]
	v_pk_add_f32 v[200:201], v[60:61], v[178:179] op_sel_hi:[1,0] neg_lo:[0,1] neg_hi:[0,1]
	v_pk_fma_f32 v[198:199], v[200:201], v[200:201], v[198:199]
	v_add_f32_e32 v146, v198, v199
	v_pk_add_f32 v[204:205], v[118:119], v[180:181] op_sel_hi:[1,0] neg_lo:[0,1] neg_hi:[0,1]
	v_pk_mul_f32 v[202:203], v[204:205], v[204:205]
	v_pk_add_f32 v[204:205], v[120:121], v[180:181] op_sel_hi:[1,0] neg_lo:[0,1] neg_hi:[0,1]
	v_pk_fma_f32 v[202:203], v[204:205], v[204:205], v[202:203]
	v_pk_add_f32 v[204:205], v[114:115], v[180:181] op_sel_hi:[1,0] neg_lo:[0,1] neg_hi:[0,1]
	v_pk_fma_f32 v[202:203], v[204:205], v[204:205], v[202:203]
	v_pk_add_f32 v[204:205], v[116:117], v[180:181] op_sel_hi:[1,0] neg_lo:[0,1] neg_hi:[0,1]
	v_pk_fma_f32 v[202:203], v[204:205], v[204:205], v[202:203]
	v_pk_add_f32 v[204:205], v[54:55], v[180:181] op_sel_hi:[1,0] neg_lo:[0,1] neg_hi:[0,1]
	v_pk_fma_f32 v[202:203], v[204:205], v[204:205], v[202:203]
	v_pk_add_f32 v[204:205], v[56:57], v[180:181] op_sel_hi:[1,0] neg_lo:[0,1] neg_hi:[0,1]
	v_pk_fma_f32 v[202:203], v[204:205], v[204:205], v[202:203]
	v_pk_add_f32 v[204:205], v[50:51], v[180:181] op_sel_hi:[1,0] neg_lo:[0,1] neg_hi:[0,1]
	v_pk_fma_f32 v[202:203], v[204:205], v[204:205], v[202:203]
	v_pk_add_f32 v[204:205], v[52:53], v[180:181] op_sel_hi:[1,0] neg_lo:[0,1] neg_hi:[0,1]
	v_pk_fma_f32 v[202:203], v[204:205], v[204:205], v[202:203]
	v_add_f32_e32 v147, v202, v203
	v_pk_add_f32 v[208:209], v[110:111], v[182:183] op_sel_hi:[1,0] neg_lo:[0,1] neg_hi:[0,1]
	v_pk_mul_f32 v[206:207], v[208:209], v[208:209]
	v_pk_add_f32 v[208:209], v[112:113], v[182:183] op_sel_hi:[1,0] neg_lo:[0,1] neg_hi:[0,1]
	v_pk_fma_f32 v[206:207], v[208:209], v[208:209], v[206:207]
	v_pk_add_f32 v[208:209], v[106:107], v[182:183] op_sel_hi:[1,0] neg_lo:[0,1] neg_hi:[0,1]
	v_pk_fma_f32 v[206:207], v[208:209], v[208:209], v[206:207]
	v_pk_add_f32 v[208:209], v[108:109], v[182:183] op_sel_hi:[1,0] neg_lo:[0,1] neg_hi:[0,1]
	v_pk_fma_f32 v[206:207], v[208:209], v[208:209], v[206:207]
	v_pk_add_f32 v[208:209], v[46:47], v[182:183] op_sel_hi:[1,0] neg_lo:[0,1] neg_hi:[0,1]
	v_pk_fma_f32 v[206:207], v[208:209], v[208:209], v[206:207]
	v_pk_add_f32 v[208:209], v[48:49], v[182:183] op_sel_hi:[1,0] neg_lo:[0,1] neg_hi:[0,1]
	v_pk_fma_f32 v[206:207], v[208:209], v[208:209], v[206:207]
	v_pk_add_f32 v[208:209], v[42:43], v[182:183] op_sel_hi:[1,0] neg_lo:[0,1] neg_hi:[0,1]
	v_pk_fma_f32 v[206:207], v[208:209], v[208:209], v[206:207]
	v_pk_add_f32 v[208:209], v[44:45], v[182:183] op_sel_hi:[1,0] neg_lo:[0,1] neg_hi:[0,1]
	v_pk_fma_f32 v[206:207], v[208:209], v[208:209], v[206:207]
	v_add_f32_e32 v148, v206, v207
	v_pk_add_f32 v[212:213], v[102:103], v[184:185] op_sel_hi:[1,0] neg_lo:[0,1] neg_hi:[0,1]
	v_pk_mul_f32 v[210:211], v[212:213], v[212:213]
	v_pk_add_f32 v[212:213], v[104:105], v[184:185] op_sel_hi:[1,0] neg_lo:[0,1] neg_hi:[0,1]
; __global__ void __launch_bounds__(512, 2) fwd_kernel(Args a) {
;     ...
;             for (int q = 0; q < 4; ++q) { float s2 = 0.f;
; #pragma unroll
;                 for (int j = 0; j < 8; ++j) { vr[q][j] = vr[q][j] - sm[q]; s2 += (vr[q][j][0] * vr[q][j][0] + vr[q][j][1] * vr[q][j][1]) + (vr[q][j][2] * vr[q][j][2] + vr[q][j][3] * vr[q][j][3]); }
;                 qq[q] = wave_sum(s2); rs[q] = 1.0f / sqrtf(qq[q] * (1.0f / DMODEL) + LN_EPS); }
	v_pk_fma_f32 v[210:211], v[212:213], v[212:213], v[210:211]
	v_pk_add_f32 v[212:213], v[98:99], v[184:185] op_sel_hi:[1,0] neg_lo:[0,1] neg_hi:[0,1]
	v_pk_fma_f32 v[210:211], v[212:213], v[212:213], v[210:211]
	v_pk_add_f32 v[212:213], v[100:101], v[184:185] op_sel_hi:[1,0] neg_lo:[0,1] neg_hi:[0,1]
	v_pk_fma_f32 v[210:211], v[212:213], v[212:213], v[210:211]
	v_pk_add_f32 v[212:213], v[38:39], v[184:185] op_sel_hi:[1,0] neg_lo:[0,1] neg_hi:[0,1]
	v_pk_fma_f32 v[210:211], v[212:213], v[212:213], v[210:211]
	v_pk_add_f32 v[212:213], v[40:41], v[184:185] op_sel_hi:[1,0] neg_lo:[0,1] neg_hi:[0,1]
	v_pk_fma_f32 v[210:211], v[212:213], v[212:213], v[210:211]
	v_pk_add_f32 v[212:213], v[34:35], v[184:185] op_sel_hi:[1,0] neg_lo:[0,1] neg_hi:[0,1]
	v_pk_fma_f32 v[210:211], v[212:213], v[212:213], v[210:211]
	v_pk_add_f32 v[212:213], v[36:37], v[184:185] op_sel_hi:[1,0] neg_lo:[0,1] neg_hi:[0,1]
	v_pk_fma_f32 v[210:211], v[212:213], v[212:213], v[210:211]
	v_add_f32_e32 v149, v210, v211
	v_pk_add_f32 v[200:201], v[94:95], v[186:187] op_sel_hi:[1,0] neg_lo:[0,1] neg_hi:[0,1]
	v_pk_mul_f32 v[198:199], v[200:201], v[200:201]
	v_pk_add_f32 v[200:201], v[96:97], v[186:187] op_sel_hi:[1,0] neg_lo:[0,1] neg_hi:[0,1]
	v_pk_fma_f32 v[198:199], v[200:201], v[200:201], v[198:199]
	v_pk_add_f32 v[200:201], v[90:91], v[186:187] op_sel_hi:[1,0] neg_lo:[0,1] neg_hi:[0,1]
	v_pk_fma_f32 v[198:199], v[200:201], v[200:201], v[198:199]
	v_pk_add_f32 v[200:201], v[92:93], v[186:187] op_sel_hi:[1,0] neg_lo:[0,1] neg_hi:[0,1]
	v_pk_fma_f32 v[198:199], v[200:201], v[200:201], v[198:199]
	v_pk_add_f32 v[200:201], v[30:31], v[186:187] op_sel_hi:[1,0] neg_lo:[0,1] neg_hi:[0,1]
	v_pk_fma_f32 v[198:199], v[200:201], v[200:201], v[198:199]
	v_pk_add_f32 v[200:201], v[32:33], v[186:187] op_sel_hi:[1,0] neg_lo:[0,1] neg_hi:[0,1]
	v_pk_fma_f32 v[198:199], v[200:201], v[200:201], v[198:199]
	v_pk_add_f32 v[200:201], v[26:27], v[186:187] op_sel_hi:[1,0] neg_lo:[0,1] neg_hi:[0,1]
	v_pk_fma_f32 v[198:199], v[200:201], v[200:201], v[198:199]
	v_pk_add_f32 v[200:201], v[28:29], v[186:187] op_sel_hi:[1,0] neg_lo:[0,1] neg_hi:[0,1]
	v_pk_fma_f32 v[198:199], v[200:201], v[200:201], v[198:199]
	v_add_f32_e32 v150, v198, v199
	v_pk_add_f32 v[204:205], v[86:87], v[188:189] op_sel_hi:[1,0] neg_lo:[0,1] neg_hi:[0,1]
	v_pk_mul_f32 v[202:203], v[204:205], v[204:205]
	v_pk_add_f32 v[204:205], v[88:89], v[188:189] op_sel_hi:[1,0] neg_lo:[0,1] neg_hi:[0,1]
	v_pk_fma_f32 v[202:203], v[204:205], v[204:205], v[202:203]
	v_pk_add_f32 v[204:205], v[82:83], v[188:189] op_sel_hi:[1,0] neg_lo:[0,1] neg_hi:[0,1]
	v_pk_fma_f32 v[202:203], v[204:205], v[204:205], v[202:203]
	v_pk_add_f32 v[204:205], v[84:85], v[188:189] op_sel_hi:[1,0] neg_lo:[0,1] neg_hi:[0,1]
	v_pk_fma_f32 v[202:203], v[204:205], v[204:205], v[202:203]
	v_pk_add_f32 v[204:205], v[22:23], v[188:189] op_sel_hi:[1,0] neg_lo:[0,1] neg_hi:[0,1]
	v_pk_fma_f32 v[202:203], v[204:205], v[204:205], v[202:203]
	v_pk_add_f32 v[204:205], v[24:25], v[188:189] op_sel_hi:[1,0] neg_lo:[0,1] neg_hi:[0,1]
	v_pk_fma_f32 v[202:203], v[204:205], v[204:205], v[202:203]
	v_pk_add_f32 v[204:205], v[18:19], v[188:189] op_sel_hi:[1,0] neg_lo:[0,1] neg_hi:[0,1]
	v_pk_fma_f32 v[202:203], v[204:205], v[204:205], v[202:203]
	v_pk_add_f32 v[204:205], v[20:21], v[188:189] op_sel_hi:[1,0] neg_lo:[0,1] neg_hi:[0,1]
	v_pk_fma_f32 v[202:203], v[204:205], v[204:205], v[202:203]
	v_add_f32_e32 v151, v202, v203
	v_pk_add_f32 v[208:209], v[78:79], v[190:191] op_sel_hi:[1,0] neg_lo:[0,1] neg_hi:[0,1]
	v_pk_mul_f32 v[206:207], v[208:209], v[208:209]
	v_pk_add_f32 v[208:209], v[80:81], v[190:191] op_sel_hi:[1,0] neg_lo:[0,1] neg_hi:[0,1]
	v_pk_fma_f32 v[206:207], v[208:209], v[208:209], v[206:207]
	v_pk_add_f32 v[208:209], v[74:75], v[190:191] op_sel_hi:[1,0] neg_lo:[0,1] neg_hi:[0,1]
	v_pk_fma_f32 v[206:207], v[208:209], v[208:209], v[206:207]
	v_pk_add_f32 v[208:209], v[76:77], v[190:191] op_sel_hi:[1,0] neg_lo:[0,1] neg_hi:[0,1]
	v_pk_fma_f32 v[206:207], v[208:209], v[208:209], v[206:207]
	v_pk_add_f32 v[208:209], v[14:15], v[190:191] op_sel_hi:[1,0] neg_lo:[0,1] neg_hi:[0,1]
	v_pk_fma_f32 v[206:207], v[208:209], v[208:209], v[206:207]
	v_pk_add_f32 v[208:209], v[16:17], v[190:191] op_sel_hi:[1,0] neg_lo:[0,1] neg_hi:[0,1]
	v_pk_fma_f32 v[206:207], v[208:209], v[208:209], v[206:207]
	v_pk_add_f32 v[208:209], v[10:11], v[190:191] op_sel_hi:[1,0] neg_lo:[0,1] neg_hi:[0,1]
	v_pk_fma_f32 v[206:207], v[208:209], v[208:209], v[206:207]
	v_pk_add_f32 v[208:209], v[12:13], v[190:191] op_sel_hi:[1,0] neg_lo:[0,1] neg_hi:[0,1]
	v_pk_fma_f32 v[206:207], v[208:209], v[208:209], v[206:207]
	v_add_f32_e32 v152, v206, v207
	v_pk_add_f32 v[212:213], v[70:71], v[192:193] op_sel_hi:[1,0] neg_lo:[0,1] neg_hi:[0,1]
	v_pk_mul_f32 v[210:211], v[212:213], v[212:213]
	v_pk_add_f32 v[212:213], v[72:73], v[192:193] op_sel_hi:[1,0] neg_lo:[0,1] neg_hi:[0,1]
	v_pk_fma_f32 v[210:211], v[212:213], v[212:213], v[210:211]
	v_pk_add_f32 v[212:213], v[66:67], v[192:193] op_sel_hi:[1,0] neg_lo:[0,1] neg_hi:[0,1]
	v_pk_fma_f32 v[210:211], v[212:213], v[212:213], v[210:211]
; __global__ void __launch_bounds__(512, 2) fwd_kernel(Args a) {
;     ...
;             for (int q = 0; q < 4; ++q) { float s2 = 0.f;
; #pragma unroll
;                 for (int j = 0; j < 8; ++j) { vr[q][j] = vr[q][j] - sm[q]; s2 += (vr[q][j][0] * vr[q][j][0] + vr[q][j][1] * vr[q][j][1]) + (vr[q][j][2] * vr[q][j][2] + vr[q][j][3] * vr[q][j][3]); }
;                 qq[q] = wave_sum(s2); rs[q] = 1.0f / sqrtf(qq[q] * (1.0f / DMODEL) + LN_EPS); }
	v_pk_add_f32 v[212:213], v[68:69], v[192:193] op_sel_hi:[1,0] neg_lo:[0,1] neg_hi:[0,1]
	v_pk_fma_f32 v[210:211], v[212:213], v[212:213], v[210:211]
	v_pk_add_f32 v[212:213], v[6:7], v[192:193] op_sel_hi:[1,0] neg_lo:[0,1] neg_hi:[0,1]
	v_pk_fma_f32 v[210:211], v[212:213], v[212:213], v[210:211]
	v_pk_add_f32 v[212:213], v[8:9], v[192:193] op_sel_hi:[1,0] neg_lo:[0,1] neg_hi:[0,1]
	v_pk_fma_f32 v[210:211], v[212:213], v[212:213], v[210:211]
	v_pk_add_f32 v[212:213], v[2:3], v[192:193] op_sel_hi:[1,0] neg_lo:[0,1] neg_hi:[0,1]
	v_pk_fma_f32 v[210:211], v[212:213], v[212:213], v[210:211]
	v_pk_add_f32 v[212:213], v[4:5], v[192:193] op_sel_hi:[1,0] neg_lo:[0,1] neg_hi:[0,1]
	v_pk_fma_f32 v[210:211], v[212:213], v[212:213], v[210:211]
	v_add_f32_e32 v153, v210, v211
	v_mov_b32_e32 v238, v146
	v_mov_b32_e32 v246, v146
	v_mov_b32_e32 v239, v147
	v_mov_b32_e32 v247, v147
	v_mov_b32_e32 v240, v148
	v_mov_b32_e32 v248, v148
	v_mov_b32_e32 v241, v149
	v_mov_b32_e32 v249, v149
	v_mov_b32_e32 v242, v150
	v_mov_b32_e32 v250, v150
	v_mov_b32_e32 v243, v151
	v_mov_b32_e32 v251, v151
	v_mov_b32_e32 v244, v152
	v_mov_b32_e32 v252, v152
	v_mov_b32_e32 v245, v153
	v_mov_b32_e32 v253, v153
	s_nop 1
	v_permlane16_swap_b32_e32 v238, v246
	v_permlane16_swap_b32_e32 v239, v247
	v_permlane16_swap_b32_e32 v240, v248
	v_permlane16_swap_b32_e32 v241, v249
	v_permlane16_swap_b32_e32 v242, v250
	v_permlane16_swap_b32_e32 v243, v251
	v_permlane16_swap_b32_e32 v244, v252
	v_permlane16_swap_b32_e32 v245, v253
	s_nop 1
	v_add_f32_e32 v146, v238, v246
	v_add_f32_e32 v147, v239, v247
	v_add_f32_e32 v148, v240, v248
	v_add_f32_e32 v149, v241, v249
	v_add_f32_e32 v150, v242, v250
	v_add_f32_e32 v151, v243, v251
	v_add_f32_e32 v152, v244, v252
	v_add_f32_e32 v153, v245, v253
	v_mov_b32_e32 v238, v146
	v_mov_b32_e32 v246, v146
	v_mov_b32_e32 v239, v147
	v_mov_b32_e32 v247, v147
	v_mov_b32_e32 v240, v148
	v_mov_b32_e32 v248, v148
	v_mov_b32_e32 v241, v149
	v_mov_b32_e32 v249, v149
	v_mov_b32_e32 v242, v150
	v_mov_b32_e32 v250, v150
	v_mov_b32_e32 v243, v151
	v_mov_b32_e32 v251, v151
	v_mov_b32_e32 v244, v152
	v_mov_b32_e32 v252, v152
	v_mov_b32_e32 v245, v153
	v_mov_b32_e32 v253, v153
	s_nop 1
	v_permlane32_swap_b32_e32 v238, v246
	v_permlane32_swap_b32_e32 v239, v247
	v_permlane32_swap_b32_e32 v240, v248
	v_permlane32_swap_b32_e32 v241, v249
	v_permlane32_swap_b32_e32 v242, v250
	v_permlane32_swap_b32_e32 v243, v251
	v_permlane32_swap_b32_e32 v244, v252
	v_permlane32_swap_b32_e32 v245, v253
	s_nop 1
	v_add_f32_e32 v146, v238, v246
	v_add_f32_e32 v147, v239, v247
	v_add_f32_e32 v148, v240, v248
	v_add_f32_e32 v149, v241, v249
	v_add_f32_e32 v150, v242, v250
	v_add_f32_e32 v151, v243, v251
	v_add_f32_e32 v152, v244, v252
	v_add_f32_e32 v153, v245, v253
	ds_write_b32 v214, v146 offset:4096
	ds_write_b32 v214, v147 offset:4352
	ds_write_b32 v214, v148 offset:4608
	ds_write_b32 v214, v149 offset:4864
	ds_write_b32 v214, v150 offset:6144
	ds_write_b32 v214, v151 offset:6400
	ds_write_b32 v214, v152 offset:6656
	ds_write_b32 v214, v153 offset:6912
	s_waitcnt lgkmcnt(0)
	s_barrier
	ds_read_b128 v[198:201], v215 offset:4096
	ds_read_b128 v[202:205], v215 offset:4352
	ds_read_b128 v[206:209], v215 offset:4608
	ds_read_b128 v[210:213], v215 offset:4864
	ds_read_b128 v[222:225], v215 offset:6144
	ds_read_b128 v[226:229], v215 offset:6400
	ds_read_b128 v[230:233], v215 offset:6656
	ds_read_b128 v[234:237], v215 offset:6912
	s_waitcnt lgkmcnt(0)
	v_add_f32_e32 v131, v198, v199
	v_add_f32_e32 v131, v131, v200
	v_add_f32_e32 v131, v131, v201
	v_add_f32_e32 v133, v202, v203
	v_add_f32_e32 v133, v133, v204
	v_add_f32_e32 v133, v133, v205
	v_add_f32_e32 v135, v206, v207
	v_add_f32_e32 v135, v135, v208
	v_add_f32_e32 v135, v135, v209
	v_add_f32_e32 v137, v210, v211
	v_add_f32_e32 v137, v137, v212
	v_add_f32_e32 v137, v137, v213
	v_add_f32_e32 v139, v222, v223
	v_add_f32_e32 v139, v139, v224
	v_add_f32_e32 v139, v139, v225
	v_add_f32_e32 v141, v226, v227
	v_add_f32_e32 v141, v141, v228
	v_add_f32_e32 v141, v141, v229
	v_add_f32_e32 v143, v230, v231
	v_add_f32_e32 v143, v143, v232
	v_add_f32_e32 v143, v143, v233
	v_add_f32_e32 v145, v234, v235
	v_add_f32_e32 v145, v145, v236
	v_add_f32_e32 v145, v145, v237
	s_and_b32 s56, s96, 3
	s_cmp_lg_u32 s56, 0
	s_cbranch_scc1 .Lln1_nostat
	s_mov_b64 s[58:59], exec
	s_mov_b64 exec, 0xffff
	v_lshlrev_b32_e32 v216, 6, v194
	v_lshrrev_b32_e32 v217, 10, v174
	v_lshl_add_u32 v216, v217, 3, v216
	v_add_u32_e32 v217, 0x0, v216
	global_store_dwordx2 v217, v[130:131], s[60:61]
	v_add_u32_e32 v217, 0x400, v216
	global_store_dwordx2 v217, v[132:133], s[60:61]
	v_add_u32_e32 v217, 0x800, v216
	global_store_dwordx2 v217, v[134:135], s[60:61]
	v_add_u32_e32 v217, 0xc00, v216
	global_store_dwordx2 v217, v[136:137], s[60:61]
	v_add_u32_e32 v217, 0x2000, v216
	global_store_dwordx2 v217, v[138:139], s[60:61]
	v_add_u32_e32 v217, 0x2400, v216
	global_store_dwordx2 v217, v[140:141], s[60:61]
	v_add_u32_e32 v217, 0x2800, v216
	global_store_dwordx2 v217, v[142:143], s[60:61]
	v_add_u32_e32 v217, 0x2c00, v216
	global_store_dwordx2 v217, v[144:145], s[60:61]
	s_mov_b64 exec, s[58:59]

;     __device__ __forceinline__ void operator()(const Acc& acc, const Unit& u, int wr, int wc, int fr, int fq) const {
;     ...
;         for (int bj = 0; bj < 2; ++bj)
; #pragma unroll
;             for (int ai = 0; ai < 2; ++ai) {
;                 f32x4 bsv[4][2];
; #pragma unroll
;                 for (int m = 0; m < 4; ++m)
; #pragma unroll
;                     for (int n = 0; n < 2; ++n) { const size_t off = (size_t)(u.pm * BM + ai * HALF + wr * 64 + m * 16 + fr) * DMODEL + col0 + bj * HALF + n * 16; bsv[m][n] = __builtin_nontemporal_load((const f32x4*)(base + off)); }
; #pragma unroll
;                 for (int m = 0; m < 4; ++m)
; #pragma unroll
;                     for (int n = 0; n < 2; ++n) { const size_t off = (size_t)(u.pm * BM + ai * HALF + wr * 64 + m * 16 + fr) * DMODEL + col0 + bj * HALF + n * 16;
;                         *(f32x4*)(out + off) = bsv[m][n] * ALPHA + gvv[bj][n] * acc[ai][bj][m][n]; } }
; __global__ void __launch_bounds__(512, 2) fwd_kernel(Args a) {
;     ...
;             for (int j = 0; j < 8; ++j) { const f32x4 gg = ggv[j], bb = bbv[j];
;                 const f32x4 ya = va[j] * rstd_a * gg + bb, yb = vb[j] * rstd_b * gg + bb; __builtin_nontemporal_store(ya, xr + 64 * j); __builtin_nontemporal_store(yb, xr + 512 + 64 * j);
.LBB0_1102:
	v_lshl_or_b32 v64, s23, 8, v172
	s_ashr_i32 s15, s22, 4
	s_mul_hi_i32 s17, s15, 0xc000
	s_mul_i32 s15, s15, 0xc000
	v_ashrrev_i32_e32 v65, 31, v64
	v_lshl_add_u32 v168, s22, 8, v170
	s_add_u32 s24, s42, s15
	v_lshlrev_b64 v[164:165], 2, v[64:65]
	v_ashrrev_i32_e32 v169, 31, v168
	s_addc_u32 s25, s43, s17
	v_lshl_add_u64 v[166:167], s[4:5], 0, v[164:165]
	v_lshlrev_b64 v[210:211], 13, v[168:169]
	v_lshl_add_u64 v[64:65], s[24:25], 0, v[164:165]
	s_add_i32 s56, 0, 0x22068
	v_mov_b32_e32 v218, s56
	ds_read2_b64 v[218:221], v218 offset1:1
	s_add_i32 s56, 0, 0x220a0
	v_mov_b32_e32 v222, s56
	ds_read_b64 v[222:223], v222
	s_waitcnt lgkmcnt(0)
	v_readfirstlane_b32 s56, v218
	v_readfirstlane_b32 s57, v219
	v_readfirstlane_b32 s58, v220
	v_readfirstlane_b32 s59, v221
	v_readfirstlane_b32 s60, v222
	v_readfirstlane_b32 s61, v223
	s_add_u32 s60, s60, 0x210000
	s_addc_u32 s61, s61, 0
	v_lshl_add_u64 v[218:219], s[56:57], 0, v[164:165]
	v_lshl_add_u64 v[220:221], s[58:59], 0, v[164:165]
	global_load_dwordx4 v[224:227], v[218:219], off
	global_load_dwordx4 v[228:231], v[218:219], off offset:64
	global_load_dwordx4 v[232:235], v[218:219], off offset:512
	global_load_dwordx4 v[236:239], v[218:219], off offset:576
	global_load_dwordx4 v[240:243], v[220:221], off
	global_load_dwordx4 v[244:247], v[220:221], off offset:64
	global_load_dwordx4 v[248:251], v[220:221], off offset:512
	global_load_dwordx4 v[144:147], v[220:221], off offset:576
	v_lshlrev_b32_e32 v171, 3, v168
	global_load_dwordx2 v[148:149], v171, s[60:61]
	global_load_dwordx2 v[150:151], v171, s[60:61] offset:128
	global_load_dwordx2 v[152:153], v171, s[60:61] offset:256
	global_load_dwordx2 v[154:155], v171, s[60:61] offset:384
	global_load_dwordx2 v[252:253], v171, s[60:61] offset:1024
	global_load_dwordx2 v[174:175], v171, s[60:61] offset:1152
	global_load_dwordx2 v[222:223], v171, s[60:61] offset:1280
	global_load_dwordx2 v[220:221], v171, s[60:61] offset:1408
	v_lshl_add_u64 v[162:163], v[166:167], 0, v[210:211]
	global_load_dwordx4 v[140:143], v[64:65], off
	global_load_dwordx4 v[136:139], v[64:65], off offset:64
	global_load_dwordx4 v[68:71], v[64:65], off offset:512
	s_nop 0
	global_load_dwordx4 v[64:67], v[64:65], off offset:576
	s_nop 0
	global_load_dwordx4 v[176:179], v[162:163], off
	global_load_dwordx4 v[180:183], v[162:163], off offset:64
	global_load_dwordx4 v[184:187], v[162:163], off offset:512
	global_load_dwordx4 v[188:191], v[162:163], off offset:576
	s_mov_b64 s[56:57], 0x20000
	v_lshl_add_u64 v[156:157], v[162:163], 0, s[56:57]
	global_load_dwordx4 v[198:201], v[156:157], off
	global_load_dwordx4 v[202:205], v[156:157], off offset:64
	global_load_dwordx4 v[206:209], v[156:157], off offset:512
	global_load_dwordx4 v[210:213], v[156:157], off offset:576
	v_mov_b32_e32 v173, 0xba000000
	s_waitcnt vmcnt(4)
	v_pk_fma_f32 v[176:177], v[148:149], v[172:173], v[176:177] op_sel:[0,1,0] op_sel_hi:[0,1,1]
	v_pk_mul_f32 v[176:177], v[176:177], v[148:149] op_sel:[0,1] op_sel_hi:[1,1]
	v_pk_fma_f32 v[176:177], v[224:225], v[176:177], v[240:241]
	v_pk_mul_f32 v[176:177], v[176:177], s[12:13] op_sel_hi:[1,0]
	v_pk_fma_f32 v[132:133], v[132:133], v[140:141], v[176:177]
	v_pk_fma_f32 v[178:179], v[148:149], v[172:173], v[178:179] op_sel:[0,1,0] op_sel_hi:[0,1,1]
	v_pk_mul_f32 v[178:179], v[178:179], v[148:149] op_sel:[0,1] op_sel_hi:[1,1]
	v_pk_fma_f32 v[178:179], v[226:227], v[178:179], v[242:243]
	v_pk_mul_f32 v[178:179], v[178:179], s[12:13] op_sel_hi:[1,0]
	v_pk_fma_f32 v[134:135], v[134:135], v[142:143], v[178:179]
	v_pk_fma_f32 v[180:181], v[148:149], v[172:173], v[180:181] op_sel:[0,1,0] op_sel_hi:[0,1,1]
	v_pk_mul_f32 v[180:181], v[180:181], v[148:149] op_sel:[0,1] op_sel_hi:[1,1]
	v_pk_fma_f32 v[180:181], v[228:229], v[180:181], v[244:245]
	v_pk_mul_f32 v[180:181], v[180:181], s[12:13] op_sel_hi:[1,0]
	v_pk_fma_f32 v[128:129], v[128:129], v[136:137], v[180:181]
	v_pk_fma_f32 v[182:183], v[148:149], v[172:173], v[182:183] op_sel:[0,1,0] op_sel_hi:[0,1,1]
	v_pk_mul_f32 v[182:183], v[182:183], v[148:149] op_sel:[0,1] op_sel_hi:[1,1]
	v_pk_fma_f32 v[182:183], v[230:231], v[182:183], v[246:247]
	v_pk_mul_f32 v[182:183], v[182:183], s[12:13] op_sel_hi:[1,0]
	v_pk_fma_f32 v[130:131], v[130:131], v[138:139], v[182:183]
	v_pk_fma_f32 v[184:185], v[148:149], v[172:173], v[184:185] op_sel:[0,1,0] op_sel_hi:[0,1,1]
	v_pk_mul_f32 v[184:185], v[184:185], v[148:149] op_sel:[0,1] op_sel_hi:[1,1]
	v_pk_fma_f32 v[184:185], v[232:233], v[184:185], v[248:249]
	v_pk_mul_f32 v[184:185], v[184:185], s[12:13] op_sel_hi:[1,0]
	v_pk_fma_f32 v[60:61], v[60:61], v[68:69], v[184:185]
	v_pk_fma_f32 v[186:187], v[148:149], v[172:173], v[186:187] op_sel:[0,1,0] op_sel_hi:[0,1,1]
	v_pk_mul_f32 v[186:187], v[186:187], v[148:149] op_sel:[0,1] op_sel_hi:[1,1]
	v_pk_fma_f32 v[186:187], v[234:235], v[186:187], v[250:251]
	v_pk_mul_f32 v[186:187], v[186:187], s[12:13] op_sel_hi:[1,0]
	v_pk_fma_f32 v[62:63], v[62:63], v[70:71], v[186:187]
	v_pk_fma_f32 v[188:189], v[148:149], v[172:173], v[188:189] op_sel:[0,1,0] op_sel_hi:[0,1,1]
	v_pk_mul_f32 v[188:189], v[188:189], v[148:149] op_sel:[0,1] op_sel_hi:[1,1]
	v_pk_fma_f32 v[188:189], v[236:237], v[188:189], v[144:145]
	v_pk_mul_f32 v[188:189], v[188:189], s[12:13] op_sel_hi:[1,0]
	v_pk_fma_f32 v[56:57], v[56:57], v[64:65], v[188:189]
	v_pk_fma_f32 v[190:191], v[148:149], v[172:173], v[190:191] op_sel:[0,1,0] op_sel_hi:[0,1,1]
	v_pk_mul_f32 v[190:191], v[190:191], v[148:149] op_sel:[0,1] op_sel_hi:[1,1]
	v_pk_fma_f32 v[190:191], v[238:239], v[190:191], v[146:147]
	v_pk_mul_f32 v[190:191], v[190:191], s[12:13] op_sel_hi:[1,0]
	v_pk_fma_f32 v[58:59], v[58:59], v[66:67], v[190:191]
	s_mov_b64 s[56:57], 0x40000
	v_lshl_add_u64 v[156:157], v[162:163], 0, s[56:57]
	global_load_dwordx4 v[176:179], v[156:157], off
	global_load_dwordx4 v[180:183], v[156:157], off offset:64
	global_load_dwordx4 v[184:187], v[156:157], off offset:512
	global_load_dwordx4 v[188:191], v[156:157], off offset:576
	s_waitcnt vmcnt(4)
;     __device__ __forceinline__ void operator()(const Acc& acc, const Unit& u, int wr, int wc, int fr, int fq) const {
;     ...
;         for (int bj = 0; bj < 2; ++bj)
; #pragma unroll
;             for (int ai = 0; ai < 2; ++ai) {
;                 f32x4 bsv[4][2];
; #pragma unroll
;                 for (int m = 0; m < 4; ++m)
; #pragma unroll
;                     for (int n = 0; n < 2; ++n) { const size_t off = (size_t)(u.pm * BM + ai * HALF + wr * 64 + m * 16 + fr) * DMODEL + col0 + bj * HALF + n * 16; bsv[m][n] = __builtin_nontemporal_load((const f32x4*)(base + off)); }
; #pragma unroll
;                 for (int m = 0; m < 4; ++m)
; #pragma unroll
;                     for (int n = 0; n < 2; ++n) { const size_t off = (size_t)(u.pm * BM + ai * HALF + wr * 64 + m * 16 + fr) * DMODEL + col0 + bj * HALF + n * 16;
;                         *(f32x4*)(out + off) = bsv[m][n] * ALPHA + gvv[bj][n] * acc[ai][bj][m][n]; } }
; __global__ void __launch_bounds__(512, 2) fwd_kernel(Args a) {
;     ...
;             for (int j = 0; j < 8; ++j) { const f32x4 gg = ggv[j], bb = bbv[j];
;                 const f32x4 ya = va[j] * rstd_a * gg + bb, yb = vb[j] * rstd_b * gg + bb; __builtin_nontemporal_store(ya, xr + 64 * j); __builtin_nontemporal_store(yb, xr + 512 + 64 * j);
	v_pk_fma_f32 v[198:199], v[150:151], v[172:173], v[198:199] op_sel:[0,1,0] op_sel_hi:[0,1,1]
	v_pk_mul_f32 v[198:199], v[198:199], v[150:151] op_sel:[0,1] op_sel_hi:[1,1]
	v_pk_fma_f32 v[198:199], v[224:225], v[198:199], v[240:241]
	v_pk_mul_f32 v[198:199], v[198:199], s[12:13] op_sel_hi:[1,0]
	v_pk_fma_f32 v[124:125], v[124:125], v[140:141], v[198:199]
	v_pk_fma_f32 v[200:201], v[150:151], v[172:173], v[200:201] op_sel:[0,1,0] op_sel_hi:[0,1,1]
	v_pk_mul_f32 v[200:201], v[200:201], v[150:151] op_sel:[0,1] op_sel_hi:[1,1]
	v_pk_fma_f32 v[200:201], v[226:227], v[200:201], v[242:243]
	v_pk_mul_f32 v[200:201], v[200:201], s[12:13] op_sel_hi:[1,0]
	v_pk_fma_f32 v[126:127], v[126:127], v[142:143], v[200:201]
	v_pk_fma_f32 v[202:203], v[150:151], v[172:173], v[202:203] op_sel:[0,1,0] op_sel_hi:[0,1,1]
	v_pk_mul_f32 v[202:203], v[202:203], v[150:151] op_sel:[0,1] op_sel_hi:[1,1]
	v_pk_fma_f32 v[202:203], v[228:229], v[202:203], v[244:245]
	v_pk_mul_f32 v[202:203], v[202:203], s[12:13] op_sel_hi:[1,0]
	v_pk_fma_f32 v[120:121], v[120:121], v[136:137], v[202:203]
	v_pk_fma_f32 v[204:205], v[150:151], v[172:173], v[204:205] op_sel:[0,1,0] op_sel_hi:[0,1,1]
	v_pk_mul_f32 v[204:205], v[204:205], v[150:151] op_sel:[0,1] op_sel_hi:[1,1]
	v_pk_fma_f32 v[204:205], v[230:231], v[204:205], v[246:247]
	v_pk_mul_f32 v[204:205], v[204:205], s[12:13] op_sel_hi:[1,0]
	v_pk_fma_f32 v[122:123], v[122:123], v[138:139], v[204:205]
	v_pk_fma_f32 v[206:207], v[150:151], v[172:173], v[206:207] op_sel:[0,1,0] op_sel_hi:[0,1,1]
	v_pk_mul_f32 v[206:207], v[206:207], v[150:151] op_sel:[0,1] op_sel_hi:[1,1]
	v_pk_fma_f32 v[206:207], v[232:233], v[206:207], v[248:249]
	v_pk_mul_f32 v[206:207], v[206:207], s[12:13] op_sel_hi:[1,0]
	v_pk_fma_f32 v[52:53], v[52:53], v[68:69], v[206:207]
	v_pk_fma_f32 v[208:209], v[150:151], v[172:173], v[208:209] op_sel:[0,1,0] op_sel_hi:[0,1,1]
	v_pk_mul_f32 v[208:209], v[208:209], v[150:151] op_sel:[0,1] op_sel_hi:[1,1]
	v_pk_fma_f32 v[208:209], v[234:235], v[208:209], v[250:251]
	v_pk_mul_f32 v[208:209], v[208:209], s[12:13] op_sel_hi:[1,0]
	v_pk_fma_f32 v[54:55], v[54:55], v[70:71], v[208:209]
	v_pk_fma_f32 v[210:211], v[150:151], v[172:173], v[210:211] op_sel:[0,1,0] op_sel_hi:[0,1,1]
	v_pk_mul_f32 v[210:211], v[210:211], v[150:151] op_sel:[0,1] op_sel_hi:[1,1]
	v_pk_fma_f32 v[210:211], v[236:237], v[210:211], v[144:145]
	v_pk_mul_f32 v[210:211], v[210:211], s[12:13] op_sel_hi:[1,0]
	v_pk_fma_f32 v[48:49], v[48:49], v[64:65], v[210:211]
	v_pk_fma_f32 v[212:213], v[150:151], v[172:173], v[212:213] op_sel:[0,1,0] op_sel_hi:[0,1,1]
	v_pk_mul_f32 v[212:213], v[212:213], v[150:151] op_sel:[0,1] op_sel_hi:[1,1]
	v_pk_fma_f32 v[212:213], v[238:239], v[212:213], v[146:147]
	v_pk_mul_f32 v[212:213], v[212:213], s[12:13] op_sel_hi:[1,0]
	v_pk_fma_f32 v[50:51], v[50:51], v[66:67], v[212:213]
	s_mov_b64 s[56:57], 0x60000
	v_lshl_add_u64 v[156:157], v[162:163], 0, s[56:57]
	global_load_dwordx4 v[198:201], v[156:157], off
	global_load_dwordx4 v[202:205], v[156:157], off offset:64
	global_load_dwordx4 v[206:209], v[156:157], off offset:512
	global_load_dwordx4 v[210:213], v[156:157], off offset:576
	s_waitcnt vmcnt(4)
	v_pk_fma_f32 v[176:177], v[152:153], v[172:173], v[176:177] op_sel:[0,1,0] op_sel_hi:[0,1,1]
	v_pk_mul_f32 v[176:177], v[176:177], v[152:153] op_sel:[0,1] op_sel_hi:[1,1]
	v_pk_fma_f32 v[176:177], v[224:225], v[176:177], v[240:241]
	v_pk_mul_f32 v[176:177], v[176:177], s[12:13] op_sel_hi:[1,0]
	v_pk_fma_f32 v[116:117], v[116:117], v[140:141], v[176:177]
	v_pk_fma_f32 v[178:179], v[152:153], v[172:173], v[178:179] op_sel:[0,1,0] op_sel_hi:[0,1,1]
	v_pk_mul_f32 v[178:179], v[178:179], v[152:153] op_sel:[0,1] op_sel_hi:[1,1]
	v_pk_fma_f32 v[178:179], v[226:227], v[178:179], v[242:243]
	v_pk_mul_f32 v[178:179], v[178:179], s[12:13] op_sel_hi:[1,0]
	v_pk_fma_f32 v[118:119], v[118:119], v[142:143], v[178:179]
	v_pk_fma_f32 v[180:181], v[152:153], v[172:173], v[180:181] op_sel:[0,1,0] op_sel_hi:[0,1,1]
	v_pk_mul_f32 v[180:181], v[180:181], v[152:153] op_sel:[0,1] op_sel_hi:[1,1]
	v_pk_fma_f32 v[180:181], v[228:229], v[180:181], v[244:245]
	v_pk_mul_f32 v[180:181], v[180:181], s[12:13] op_sel_hi:[1,0]
	v_pk_fma_f32 v[112:113], v[112:113], v[136:137], v[180:181]
	v_pk_fma_f32 v[182:183], v[152:153], v[172:173], v[182:183] op_sel:[0,1,0] op_sel_hi:[0,1,1]
	v_pk_mul_f32 v[182:183], v[182:183], v[152:153] op_sel:[0,1] op_sel_hi:[1,1]
	v_pk_fma_f32 v[182:183], v[230:231], v[182:183], v[246:247]
	v_pk_mul_f32 v[182:183], v[182:183], s[12:13] op_sel_hi:[1,0]
	v_pk_fma_f32 v[114:115], v[114:115], v[138:139], v[182:183]
	v_pk_fma_f32 v[184:185], v[152:153], v[172:173], v[184:185] op_sel:[0,1,0] op_sel_hi:[0,1,1]
	v_pk_mul_f32 v[184:185], v[184:185], v[152:153] op_sel:[0,1] op_sel_hi:[1,1]
	v_pk_fma_f32 v[184:185], v[232:233], v[184:185], v[248:249]
	v_pk_mul_f32 v[184:185], v[184:185], s[12:13] op_sel_hi:[1,0]
	v_pk_fma_f32 v[44:45], v[44:45], v[68:69], v[184:185]
	v_pk_fma_f32 v[186:187], v[152:153], v[172:173], v[186:187] op_sel:[0,1,0] op_sel_hi:[0,1,1]
	v_pk_mul_f32 v[186:187], v[186:187], v[152:153] op_sel:[0,1] op_sel_hi:[1,1]
	v_pk_fma_f32 v[186:187], v[234:235], v[186:187], v[250:251]
	v_pk_mul_f32 v[186:187], v[186:187], s[12:13] op_sel_hi:[1,0]
	v_pk_fma_f32 v[46:47], v[46:47], v[70:71], v[186:187]
	v_pk_fma_f32 v[188:189], v[152:153], v[172:173], v[188:189] op_sel:[0,1,0] op_sel_hi:[0,1,1]
	v_pk_mul_f32 v[188:189], v[188:189], v[152:153] op_sel:[0,1] op_sel_hi:[1,1]
	v_pk_fma_f32 v[188:189], v[236:237], v[188:189], v[144:145]
	v_pk_mul_f32 v[188:189], v[188:189], s[12:13] op_sel_hi:[1,0]
	v_pk_fma_f32 v[40:41], v[40:41], v[64:65], v[188:189]
	v_pk_fma_f32 v[190:191], v[152:153], v[172:173], v[190:191] op_sel:[0,1,0] op_sel_hi:[0,1,1]
	v_pk_mul_f32 v[190:191], v[190:191], v[152:153] op_sel:[0,1] op_sel_hi:[1,1]
	v_pk_fma_f32 v[190:191], v[238:239], v[190:191], v[146:147]
	v_pk_mul_f32 v[190:191], v[190:191], s[12:13] op_sel_hi:[1,0]
	v_pk_fma_f32 v[42:43], v[42:43], v[66:67], v[190:191]
	s_mov_b64 s[56:57], 0x100000
	v_lshl_add_u64 v[156:157], v[162:163], 0, s[56:57]
	global_load_dwordx4 v[176:179], v[156:157], off
	global_load_dwordx4 v[180:183], v[156:157], off offset:64
	global_load_dwordx4 v[184:187], v[156:157], off offset:512
	global_load_dwordx4 v[188:191], v[156:157], off offset:576
	s_waitcnt vmcnt(4)
;     __device__ __forceinline__ void operator()(const Acc& acc, const Unit& u, int wr, int wc, int fr, int fq) const {
;     ...
;         for (int bj = 0; bj < 2; ++bj)
; #pragma unroll
;             for (int ai = 0; ai < 2; ++ai) {
;                 f32x4 bsv[4][2];
; #pragma unroll
;                 for (int m = 0; m < 4; ++m)
; #pragma unroll
;                     for (int n = 0; n < 2; ++n) { const size_t off = (size_t)(u.pm * BM + ai * HALF + wr * 64 + m * 16 + fr) * DMODEL + col0 + bj * HALF + n * 16; bsv[m][n] = __builtin_nontemporal_load((const f32x4*)(base + off)); }
; #pragma unroll
;                 for (int m = 0; m < 4; ++m)
; #pragma unroll
;                     for (int n = 0; n < 2; ++n) { const size_t off = (size_t)(u.pm * BM + ai * HALF + wr * 64 + m * 16 + fr) * DMODEL + col0 + bj * HALF + n * 16;
;                         *(f32x4*)(out + off) = bsv[m][n] * ALPHA + gvv[bj][n] * acc[ai][bj][m][n]; } }
; __global__ void __launch_bounds__(512, 2) fwd_kernel(Args a) {
;     ...
;             for (int j = 0; j < 8; ++j) { const f32x4 gg = ggv[j], bb = bbv[j];
;                 const f32x4 ya = va[j] * rstd_a * gg + bb, yb = vb[j] * rstd_b * gg + bb; __builtin_nontemporal_store(ya, xr + 64 * j); __builtin_nontemporal_store(yb, xr + 512 + 64 * j);
	v_pk_fma_f32 v[198:199], v[154:155], v[172:173], v[198:199] op_sel:[0,1,0] op_sel_hi:[0,1,1]
	v_pk_mul_f32 v[198:199], v[198:199], v[154:155] op_sel:[0,1] op_sel_hi:[1,1]
	v_pk_fma_f32 v[198:199], v[224:225], v[198:199], v[240:241]
	v_pk_mul_f32 v[198:199], v[198:199], s[12:13] op_sel_hi:[1,0]
	v_pk_fma_f32 v[108:109], v[108:109], v[140:141], v[198:199]
	v_pk_fma_f32 v[200:201], v[154:155], v[172:173], v[200:201] op_sel:[0,1,0] op_sel_hi:[0,1,1]
	v_pk_mul_f32 v[200:201], v[200:201], v[154:155] op_sel:[0,1] op_sel_hi:[1,1]
	v_pk_fma_f32 v[200:201], v[226:227], v[200:201], v[242:243]
	v_pk_mul_f32 v[200:201], v[200:201], s[12:13] op_sel_hi:[1,0]
	v_pk_fma_f32 v[110:111], v[110:111], v[142:143], v[200:201]
	v_pk_fma_f32 v[202:203], v[154:155], v[172:173], v[202:203] op_sel:[0,1,0] op_sel_hi:[0,1,1]
	v_pk_mul_f32 v[202:203], v[202:203], v[154:155] op_sel:[0,1] op_sel_hi:[1,1]
	v_pk_fma_f32 v[202:203], v[228:229], v[202:203], v[244:245]
	v_pk_mul_f32 v[202:203], v[202:203], s[12:13] op_sel_hi:[1,0]
	v_pk_fma_f32 v[104:105], v[104:105], v[136:137], v[202:203]
	v_pk_fma_f32 v[204:205], v[154:155], v[172:173], v[204:205] op_sel:[0,1,0] op_sel_hi:[0,1,1]
	v_pk_mul_f32 v[204:205], v[204:205], v[154:155] op_sel:[0,1] op_sel_hi:[1,1]
	v_pk_fma_f32 v[204:205], v[230:231], v[204:205], v[246:247]
	v_pk_mul_f32 v[204:205], v[204:205], s[12:13] op_sel_hi:[1,0]
	v_pk_fma_f32 v[106:107], v[106:107], v[138:139], v[204:205]
	v_pk_fma_f32 v[206:207], v[154:155], v[172:173], v[206:207] op_sel:[0,1,0] op_sel_hi:[0,1,1]
	v_pk_mul_f32 v[206:207], v[206:207], v[154:155] op_sel:[0,1] op_sel_hi:[1,1]
	v_pk_fma_f32 v[206:207], v[232:233], v[206:207], v[248:249]
	v_pk_mul_f32 v[206:207], v[206:207], s[12:13] op_sel_hi:[1,0]
	v_pk_fma_f32 v[36:37], v[36:37], v[68:69], v[206:207]
	v_pk_fma_f32 v[208:209], v[154:155], v[172:173], v[208:209] op_sel:[0,1,0] op_sel_hi:[0,1,1]
	v_pk_mul_f32 v[208:209], v[208:209], v[154:155] op_sel:[0,1] op_sel_hi:[1,1]
	v_pk_fma_f32 v[208:209], v[234:235], v[208:209], v[250:251]
	v_pk_mul_f32 v[208:209], v[208:209], s[12:13] op_sel_hi:[1,0]
	v_pk_fma_f32 v[38:39], v[38:39], v[70:71], v[208:209]
	v_pk_fma_f32 v[210:211], v[154:155], v[172:173], v[210:211] op_sel:[0,1,0] op_sel_hi:[0,1,1]
	v_pk_mul_f32 v[210:211], v[210:211], v[154:155] op_sel:[0,1] op_sel_hi:[1,1]
	v_pk_fma_f32 v[210:211], v[236:237], v[210:211], v[144:145]
	v_pk_mul_f32 v[210:211], v[210:211], s[12:13] op_sel_hi:[1,0]
	v_pk_fma_f32 v[32:33], v[32:33], v[64:65], v[210:211]
	v_pk_fma_f32 v[212:213], v[154:155], v[172:173], v[212:213] op_sel:[0,1,0] op_sel_hi:[0,1,1]
	v_pk_mul_f32 v[212:213], v[212:213], v[154:155] op_sel:[0,1] op_sel_hi:[1,1]
	v_pk_fma_f32 v[212:213], v[238:239], v[212:213], v[146:147]
	v_pk_mul_f32 v[212:213], v[212:213], s[12:13] op_sel_hi:[1,0]
	v_pk_fma_f32 v[34:35], v[34:35], v[66:67], v[212:213]
	s_mov_b64 s[56:57], 0x120000
	v_lshl_add_u64 v[156:157], v[162:163], 0, s[56:57]
	global_load_dwordx4 v[198:201], v[156:157], off
	global_load_dwordx4 v[202:205], v[156:157], off offset:64
	global_load_dwordx4 v[206:209], v[156:157], off offset:512
	global_load_dwordx4 v[210:213], v[156:157], off offset:576
	s_waitcnt vmcnt(4)
	v_pk_fma_f32 v[176:177], v[252:253], v[172:173], v[176:177] op_sel:[0,1,0] op_sel_hi:[0,1,1]
	v_pk_mul_f32 v[176:177], v[176:177], v[252:253] op_sel:[0,1] op_sel_hi:[1,1]
	v_pk_fma_f32 v[176:177], v[224:225], v[176:177], v[240:241]
	v_pk_mul_f32 v[176:177], v[176:177], s[12:13] op_sel_hi:[1,0]
	v_pk_fma_f32 v[100:101], v[100:101], v[140:141], v[176:177]
	v_pk_fma_f32 v[178:179], v[252:253], v[172:173], v[178:179] op_sel:[0,1,0] op_sel_hi:[0,1,1]
	v_pk_mul_f32 v[178:179], v[178:179], v[252:253] op_sel:[0,1] op_sel_hi:[1,1]
	v_pk_fma_f32 v[178:179], v[226:227], v[178:179], v[242:243]
	v_pk_mul_f32 v[178:179], v[178:179], s[12:13] op_sel_hi:[1,0]
	v_pk_fma_f32 v[102:103], v[102:103], v[142:143], v[178:179]
	v_pk_fma_f32 v[180:181], v[252:253], v[172:173], v[180:181] op_sel:[0,1,0] op_sel_hi:[0,1,1]
	v_pk_mul_f32 v[180:181], v[180:181], v[252:253] op_sel:[0,1] op_sel_hi:[1,1]
	v_pk_fma_f32 v[180:181], v[228:229], v[180:181], v[244:245]
	v_pk_mul_f32 v[180:181], v[180:181], s[12:13] op_sel_hi:[1,0]
	v_pk_fma_f32 v[96:97], v[96:97], v[136:137], v[180:181]
	v_pk_fma_f32 v[182:183], v[252:253], v[172:173], v[182:183] op_sel:[0,1,0] op_sel_hi:[0,1,1]
	v_pk_mul_f32 v[182:183], v[182:183], v[252:253] op_sel:[0,1] op_sel_hi:[1,1]
	v_pk_fma_f32 v[182:183], v[230:231], v[182:183], v[246:247]
	v_pk_mul_f32 v[182:183], v[182:183], s[12:13] op_sel_hi:[1,0]
	v_pk_fma_f32 v[98:99], v[98:99], v[138:139], v[182:183]
	v_pk_fma_f32 v[184:185], v[252:253], v[172:173], v[184:185] op_sel:[0,1,0] op_sel_hi:[0,1,1]
	v_pk_mul_f32 v[184:185], v[184:185], v[252:253] op_sel:[0,1] op_sel_hi:[1,1]
	v_pk_fma_f32 v[184:185], v[232:233], v[184:185], v[248:249]
	v_pk_mul_f32 v[184:185], v[184:185], s[12:13] op_sel_hi:[1,0]
	v_pk_fma_f32 v[28:29], v[28:29], v[68:69], v[184:185]
	v_pk_fma_f32 v[186:187], v[252:253], v[172:173], v[186:187] op_sel:[0,1,0] op_sel_hi:[0,1,1]
	v_pk_mul_f32 v[186:187], v[186:187], v[252:253] op_sel:[0,1] op_sel_hi:[1,1]
	v_pk_fma_f32 v[186:187], v[234:235], v[186:187], v[250:251]
	v_pk_mul_f32 v[186:187], v[186:187], s[12:13] op_sel_hi:[1,0]
	v_pk_fma_f32 v[30:31], v[30:31], v[70:71], v[186:187]
	v_pk_fma_f32 v[188:189], v[252:253], v[172:173], v[188:189] op_sel:[0,1,0] op_sel_hi:[0,1,1]
	v_pk_mul_f32 v[188:189], v[188:189], v[252:253] op_sel:[0,1] op_sel_hi:[1,1]
	v_pk_fma_f32 v[188:189], v[236:237], v[188:189], v[144:145]
	v_pk_mul_f32 v[188:189], v[188:189], s[12:13] op_sel_hi:[1,0]
	v_pk_fma_f32 v[24:25], v[24:25], v[64:65], v[188:189]
	v_pk_fma_f32 v[190:191], v[252:253], v[172:173], v[190:191] op_sel:[0,1,0] op_sel_hi:[0,1,1]
	v_pk_mul_f32 v[190:191], v[190:191], v[252:253] op_sel:[0,1] op_sel_hi:[1,1]
	v_pk_fma_f32 v[190:191], v[238:239], v[190:191], v[146:147]
	v_pk_mul_f32 v[190:191], v[190:191], s[12:13] op_sel_hi:[1,0]
	v_pk_fma_f32 v[26:27], v[26:27], v[66:67], v[190:191]
	s_mov_b64 s[56:57], 0x140000
	v_lshl_add_u64 v[156:157], v[162:163], 0, s[56:57]
	global_load_dwordx4 v[176:179], v[156:157], off
	global_load_dwordx4 v[180:183], v[156:157], off offset:64
	global_load_dwordx4 v[184:187], v[156:157], off offset:512
	global_load_dwordx4 v[188:191], v[156:157], off offset:576
	s_waitcnt vmcnt(4)
;     __device__ __forceinline__ void operator()(const Acc& acc, const Unit& u, int wr, int wc, int fr, int fq) const {
;     ...
;         for (int bj = 0; bj < 2; ++bj)
; #pragma unroll
;             for (int ai = 0; ai < 2; ++ai) {
;                 f32x4 bsv[4][2];
; #pragma unroll
;                 for (int m = 0; m < 4; ++m)
; #pragma unroll
;                     for (int n = 0; n < 2; ++n) { const size_t off = (size_t)(u.pm * BM + ai * HALF + wr * 64 + m * 16 + fr) * DMODEL + col0 + bj * HALF + n * 16; bsv[m][n] = __builtin_nontemporal_load((const f32x4*)(base + off)); }
; #pragma unroll
;                 for (int m = 0; m < 4; ++m)
; #pragma unroll
;                     for (int n = 0; n < 2; ++n) { const size_t off = (size_t)(u.pm * BM + ai * HALF + wr * 64 + m * 16 + fr) * DMODEL + col0 + bj * HALF + n * 16;
;                         *(f32x4*)(out + off) = bsv[m][n] * ALPHA + gvv[bj][n] * acc[ai][bj][m][n]; } }
; __global__ void __launch_bounds__(512, 2) fwd_kernel(Args a) {
;     ...
;             for (int j = 0; j < 8; ++j) { const f32x4 gg = ggv[j], bb = bbv[j];
;                 const f32x4 ya = va[j] * rstd_a * gg + bb, yb = vb[j] * rstd_b * gg + bb; __builtin_nontemporal_store(ya, xr + 64 * j); __builtin_nontemporal_store(yb, xr + 512 + 64 * j);
	v_pk_fma_f32 v[198:199], v[174:175], v[172:173], v[198:199] op_sel:[0,1,0] op_sel_hi:[0,1,1]
	v_pk_mul_f32 v[198:199], v[198:199], v[174:175] op_sel:[0,1] op_sel_hi:[1,1]
	v_pk_fma_f32 v[198:199], v[224:225], v[198:199], v[240:241]
	v_pk_mul_f32 v[198:199], v[198:199], s[12:13] op_sel_hi:[1,0]
	v_pk_fma_f32 v[92:93], v[92:93], v[140:141], v[198:199]
	v_pk_fma_f32 v[200:201], v[174:175], v[172:173], v[200:201] op_sel:[0,1,0] op_sel_hi:[0,1,1]
	v_pk_mul_f32 v[200:201], v[200:201], v[174:175] op_sel:[0,1] op_sel_hi:[1,1]
	v_pk_fma_f32 v[200:201], v[226:227], v[200:201], v[242:243]
	v_pk_mul_f32 v[200:201], v[200:201], s[12:13] op_sel_hi:[1,0]
	v_pk_fma_f32 v[94:95], v[94:95], v[142:143], v[200:201]
	v_pk_fma_f32 v[202:203], v[174:175], v[172:173], v[202:203] op_sel:[0,1,0] op_sel_hi:[0,1,1]
	v_pk_mul_f32 v[202:203], v[202:203], v[174:175] op_sel:[0,1] op_sel_hi:[1,1]
	v_pk_fma_f32 v[202:203], v[228:229], v[202:203], v[244:245]
	v_pk_mul_f32 v[202:203], v[202:203], s[12:13] op_sel_hi:[1,0]
	v_pk_fma_f32 v[88:89], v[88:89], v[136:137], v[202:203]
	v_pk_fma_f32 v[204:205], v[174:175], v[172:173], v[204:205] op_sel:[0,1,0] op_sel_hi:[0,1,1]
	v_pk_mul_f32 v[204:205], v[204:205], v[174:175] op_sel:[0,1] op_sel_hi:[1,1]
	v_pk_fma_f32 v[204:205], v[230:231], v[204:205], v[246:247]
	v_pk_mul_f32 v[204:205], v[204:205], s[12:13] op_sel_hi:[1,0]
	v_pk_fma_f32 v[90:91], v[90:91], v[138:139], v[204:205]
	v_pk_fma_f32 v[206:207], v[174:175], v[172:173], v[206:207] op_sel:[0,1,0] op_sel_hi:[0,1,1]
	v_pk_mul_f32 v[206:207], v[206:207], v[174:175] op_sel:[0,1] op_sel_hi:[1,1]
	v_pk_fma_f32 v[206:207], v[232:233], v[206:207], v[248:249]
	v_pk_mul_f32 v[206:207], v[206:207], s[12:13] op_sel_hi:[1,0]
	v_pk_fma_f32 v[20:21], v[20:21], v[68:69], v[206:207]
	v_pk_fma_f32 v[208:209], v[174:175], v[172:173], v[208:209] op_sel:[0,1,0] op_sel_hi:[0,1,1]
	v_pk_mul_f32 v[208:209], v[208:209], v[174:175] op_sel:[0,1] op_sel_hi:[1,1]
	v_pk_fma_f32 v[208:209], v[234:235], v[208:209], v[250:251]
	v_pk_mul_f32 v[208:209], v[208:209], s[12:13] op_sel_hi:[1,0]
	v_pk_fma_f32 v[22:23], v[22:23], v[70:71], v[208:209]
	v_pk_fma_f32 v[210:211], v[174:175], v[172:173], v[210:211] op_sel:[0,1,0] op_sel_hi:[0,1,1]
	v_pk_mul_f32 v[210:211], v[210:211], v[174:175] op_sel:[0,1] op_sel_hi:[1,1]
	v_pk_fma_f32 v[210:211], v[236:237], v[210:211], v[144:145]
	v_pk_mul_f32 v[210:211], v[210:211], s[12:13] op_sel_hi:[1,0]
	v_pk_fma_f32 v[16:17], v[16:17], v[64:65], v[210:211]
	v_pk_fma_f32 v[212:213], v[174:175], v[172:173], v[212:213] op_sel:[0,1,0] op_sel_hi:[0,1,1]
	v_pk_mul_f32 v[212:213], v[212:213], v[174:175] op_sel:[0,1] op_sel_hi:[1,1]
	v_pk_fma_f32 v[212:213], v[238:239], v[212:213], v[146:147]
	v_pk_mul_f32 v[212:213], v[212:213], s[12:13] op_sel_hi:[1,0]
	v_pk_fma_f32 v[18:19], v[18:19], v[66:67], v[212:213]
	s_mov_b64 s[56:57], 0x160000
	v_lshl_add_u64 v[156:157], v[162:163], 0, s[56:57]
	global_load_dwordx4 v[198:201], v[156:157], off
	global_load_dwordx4 v[202:205], v[156:157], off offset:64
	global_load_dwordx4 v[206:209], v[156:157], off offset:512
	global_load_dwordx4 v[210:213], v[156:157], off offset:576
	s_waitcnt vmcnt(4)
	v_pk_fma_f32 v[176:177], v[222:223], v[172:173], v[176:177] op_sel:[0,1,0] op_sel_hi:[0,1,1]
	v_pk_mul_f32 v[176:177], v[176:177], v[222:223] op_sel:[0,1] op_sel_hi:[1,1]
	v_pk_fma_f32 v[176:177], v[224:225], v[176:177], v[240:241]
	v_pk_mul_f32 v[176:177], v[176:177], s[12:13] op_sel_hi:[1,0]
	v_pk_fma_f32 v[84:85], v[84:85], v[140:141], v[176:177]
	v_pk_fma_f32 v[178:179], v[222:223], v[172:173], v[178:179] op_sel:[0,1,0] op_sel_hi:[0,1,1]
	v_pk_mul_f32 v[178:179], v[178:179], v[222:223] op_sel:[0,1] op_sel_hi:[1,1]
	v_pk_fma_f32 v[178:179], v[226:227], v[178:179], v[242:243]
	v_pk_mul_f32 v[178:179], v[178:179], s[12:13] op_sel_hi:[1,0]
	v_pk_fma_f32 v[86:87], v[86:87], v[142:143], v[178:179]
	v_pk_fma_f32 v[180:181], v[222:223], v[172:173], v[180:181] op_sel:[0,1,0] op_sel_hi:[0,1,1]
	v_pk_mul_f32 v[180:181], v[180:181], v[222:223] op_sel:[0,1] op_sel_hi:[1,1]
	v_pk_fma_f32 v[180:181], v[228:229], v[180:181], v[244:245]
	v_pk_mul_f32 v[180:181], v[180:181], s[12:13] op_sel_hi:[1,0]
	v_pk_fma_f32 v[80:81], v[80:81], v[136:137], v[180:181]
	v_pk_fma_f32 v[182:183], v[222:223], v[172:173], v[182:183] op_sel:[0,1,0] op_sel_hi:[0,1,1]
	v_pk_mul_f32 v[182:183], v[182:183], v[222:223] op_sel:[0,1] op_sel_hi:[1,1]
	v_pk_fma_f32 v[182:183], v[230:231], v[182:183], v[246:247]
	v_pk_mul_f32 v[182:183], v[182:183], s[12:13] op_sel_hi:[1,0]
	v_pk_fma_f32 v[82:83], v[82:83], v[138:139], v[182:183]
	v_pk_fma_f32 v[184:185], v[222:223], v[172:173], v[184:185] op_sel:[0,1,0] op_sel_hi:[0,1,1]
	v_pk_mul_f32 v[184:185], v[184:185], v[222:223] op_sel:[0,1] op_sel_hi:[1,1]
	v_pk_fma_f32 v[184:185], v[232:233], v[184:185], v[248:249]
	v_pk_mul_f32 v[184:185], v[184:185], s[12:13] op_sel_hi:[1,0]
	v_pk_fma_f32 v[12:13], v[12:13], v[68:69], v[184:185]
	v_pk_fma_f32 v[186:187], v[222:223], v[172:173], v[186:187] op_sel:[0,1,0] op_sel_hi:[0,1,1]
	v_pk_mul_f32 v[186:187], v[186:187], v[222:223] op_sel:[0,1] op_sel_hi:[1,1]
	v_pk_fma_f32 v[186:187], v[234:235], v[186:187], v[250:251]
	v_pk_mul_f32 v[186:187], v[186:187], s[12:13] op_sel_hi:[1,0]
	v_pk_fma_f32 v[14:15], v[14:15], v[70:71], v[186:187]
	v_pk_fma_f32 v[188:189], v[222:223], v[172:173], v[188:189] op_sel:[0,1,0] op_sel_hi:[0,1,1]
	v_pk_mul_f32 v[188:189], v[188:189], v[222:223] op_sel:[0,1] op_sel_hi:[1,1]
	v_pk_fma_f32 v[188:189], v[236:237], v[188:189], v[144:145]
	v_pk_mul_f32 v[188:189], v[188:189], s[12:13] op_sel_hi:[1,0]
	v_pk_fma_f32 v[8:9], v[8:9], v[64:65], v[188:189]
	v_pk_fma_f32 v[190:191], v[222:223], v[172:173], v[190:191] op_sel:[0,1,0] op_sel_hi:[0,1,1]
	v_pk_mul_f32 v[190:191], v[190:191], v[222:223] op_sel:[0,1] op_sel_hi:[1,1]
	v_pk_fma_f32 v[190:191], v[238:239], v[190:191], v[146:147]
	v_pk_mul_f32 v[190:191], v[190:191], s[12:13] op_sel_hi:[1,0]
	v_pk_fma_f32 v[10:11], v[10:11], v[66:67], v[190:191]
	s_waitcnt vmcnt(0)
;     __device__ __forceinline__ void operator()(const Acc& acc, const Unit& u, int wr, int wc, int fr, int fq) const {
;     ...
;                 for (int m = 0; m < 4; ++m)
; #pragma unroll
;                     for (int n = 0; n < 2; ++n) { const size_t off = (size_t)(u.pm * BM + ai * HALF + wr * 64 + m * 16 + fr) * DMODEL + col0 + bj * HALF + n * 16;
;                         *(f32x4*)(out + off) = bsv[m][n] * ALPHA + gvv[bj][n] * acc[ai][bj][m][n]; } }
; __global__ void __launch_bounds__(512, 2) fwd_kernel(Args a) {
;     ...
;             for (int q = 0; q < 4; ++q) { float s_ = 0.f;
; #pragma unroll
;                 for (int j = 0; j < 8; ++j) s_ += (vr[q][j][0] + vr[q][j][1]) + (vr[q][j][2] + vr[q][j][3]);
;                 sm[q] = wave_sum(s_) * (1.0f / DMODEL); }
	v_pk_fma_f32 v[198:199], v[220:221], v[172:173], v[198:199] op_sel:[0,1,0] op_sel_hi:[0,1,1]
	v_pk_mul_f32 v[198:199], v[198:199], v[220:221] op_sel:[0,1] op_sel_hi:[1,1]
	v_pk_fma_f32 v[198:199], v[224:225], v[198:199], v[240:241]
	v_pk_mul_f32 v[198:199], v[198:199], s[12:13] op_sel_hi:[1,0]
	v_pk_fma_f32 v[76:77], v[76:77], v[140:141], v[198:199]
	v_pk_fma_f32 v[200:201], v[220:221], v[172:173], v[200:201] op_sel:[0,1,0] op_sel_hi:[0,1,1]
	v_pk_mul_f32 v[200:201], v[200:201], v[220:221] op_sel:[0,1] op_sel_hi:[1,1]
	v_pk_fma_f32 v[200:201], v[226:227], v[200:201], v[242:243]
	v_pk_mul_f32 v[200:201], v[200:201], s[12:13] op_sel_hi:[1,0]
	v_pk_fma_f32 v[78:79], v[78:79], v[142:143], v[200:201]
	v_pk_fma_f32 v[202:203], v[220:221], v[172:173], v[202:203] op_sel:[0,1,0] op_sel_hi:[0,1,1]
	v_pk_mul_f32 v[202:203], v[202:203], v[220:221] op_sel:[0,1] op_sel_hi:[1,1]
	v_pk_fma_f32 v[202:203], v[228:229], v[202:203], v[244:245]
	v_pk_mul_f32 v[202:203], v[202:203], s[12:13] op_sel_hi:[1,0]
	v_pk_fma_f32 v[72:73], v[72:73], v[136:137], v[202:203]
	v_pk_fma_f32 v[204:205], v[220:221], v[172:173], v[204:205] op_sel:[0,1,0] op_sel_hi:[0,1,1]
	v_pk_mul_f32 v[204:205], v[204:205], v[220:221] op_sel:[0,1] op_sel_hi:[1,1]
	v_pk_fma_f32 v[204:205], v[230:231], v[204:205], v[246:247]
	v_pk_mul_f32 v[204:205], v[204:205], s[12:13] op_sel_hi:[1,0]
	v_pk_fma_f32 v[74:75], v[74:75], v[138:139], v[204:205]
	v_pk_fma_f32 v[206:207], v[220:221], v[172:173], v[206:207] op_sel:[0,1,0] op_sel_hi:[0,1,1]
	v_pk_mul_f32 v[206:207], v[206:207], v[220:221] op_sel:[0,1] op_sel_hi:[1,1]
	v_pk_fma_f32 v[206:207], v[232:233], v[206:207], v[248:249]
	v_pk_mul_f32 v[206:207], v[206:207], s[12:13] op_sel_hi:[1,0]
	v_pk_fma_f32 v[4:5], v[4:5], v[68:69], v[206:207]
	v_pk_fma_f32 v[208:209], v[220:221], v[172:173], v[208:209] op_sel:[0,1,0] op_sel_hi:[0,1,1]
	v_pk_mul_f32 v[208:209], v[208:209], v[220:221] op_sel:[0,1] op_sel_hi:[1,1]
	v_pk_fma_f32 v[208:209], v[234:235], v[208:209], v[250:251]
	v_pk_mul_f32 v[208:209], v[208:209], s[12:13] op_sel_hi:[1,0]
	v_pk_fma_f32 v[6:7], v[6:7], v[70:71], v[208:209]
	v_pk_fma_f32 v[210:211], v[220:221], v[172:173], v[210:211] op_sel:[0,1,0] op_sel_hi:[0,1,1]
	v_pk_mul_f32 v[210:211], v[210:211], v[220:221] op_sel:[0,1] op_sel_hi:[1,1]
	v_pk_fma_f32 v[210:211], v[236:237], v[210:211], v[144:145]
	v_pk_mul_f32 v[210:211], v[210:211], s[12:13] op_sel_hi:[1,0]
	v_pk_fma_f32 v[0:1], v[0:1], v[64:65], v[210:211]
	v_pk_fma_f32 v[212:213], v[220:221], v[172:173], v[212:213] op_sel:[0,1,0] op_sel_hi:[0,1,1]
	v_pk_mul_f32 v[212:213], v[212:213], v[220:221] op_sel:[0,1] op_sel_hi:[1,1]
	v_pk_fma_f32 v[212:213], v[238:239], v[212:213], v[146:147]
	v_pk_mul_f32 v[212:213], v[212:213], s[12:13] op_sel_hi:[1,0]
	v_pk_fma_f32 v[2:3], v[2:3], v[66:67], v[212:213]
	v_pk_add_f32 v[176:177], v[132:133], v[134:135]
	v_pk_add_f32 v[176:177], v[176:177], v[128:129]
	v_pk_add_f32 v[176:177], v[176:177], v[130:131]
	v_pk_add_f32 v[176:177], v[176:177], v[60:61]
	v_pk_add_f32 v[176:177], v[176:177], v[62:63]
	v_pk_add_f32 v[176:177], v[176:177], v[56:57]
	v_pk_add_f32 v[176:177], v[176:177], v[58:59]
	v_add_f32_e32 v224, v176, v177
	v_pk_add_f32 v[178:179], v[124:125], v[126:127]
	v_pk_add_f32 v[178:179], v[178:179], v[120:121]
	v_pk_add_f32 v[178:179], v[178:179], v[122:123]
	v_pk_add_f32 v[178:179], v[178:179], v[52:53]
	v_pk_add_f32 v[178:179], v[178:179], v[54:55]
	v_pk_add_f32 v[178:179], v[178:179], v[48:49]
	v_pk_add_f32 v[178:179], v[178:179], v[50:51]
	v_add_f32_e32 v225, v178, v179
	v_pk_add_f32 v[180:181], v[116:117], v[118:119]
	v_pk_add_f32 v[180:181], v[180:181], v[112:113]
	v_pk_add_f32 v[180:181], v[180:181], v[114:115]
	v_pk_add_f32 v[180:181], v[180:181], v[44:45]
	v_pk_add_f32 v[180:181], v[180:181], v[46:47]
	v_pk_add_f32 v[180:181], v[180:181], v[40:41]
	v_pk_add_f32 v[180:181], v[180:181], v[42:43]
	v_add_f32_e32 v226, v180, v181
	v_pk_add_f32 v[182:183], v[108:109], v[110:111]
	v_pk_add_f32 v[182:183], v[182:183], v[104:105]
	v_pk_add_f32 v[182:183], v[182:183], v[106:107]
	v_pk_add_f32 v[182:183], v[182:183], v[36:37]
	v_pk_add_f32 v[182:183], v[182:183], v[38:39]
	v_pk_add_f32 v[182:183], v[182:183], v[32:33]
	v_pk_add_f32 v[182:183], v[182:183], v[34:35]
	v_add_f32_e32 v227, v182, v183
	v_pk_add_f32 v[176:177], v[100:101], v[102:103]
	v_pk_add_f32 v[176:177], v[176:177], v[96:97]
	v_pk_add_f32 v[176:177], v[176:177], v[98:99]
	v_pk_add_f32 v[176:177], v[176:177], v[28:29]
	v_pk_add_f32 v[176:177], v[176:177], v[30:31]
	v_pk_add_f32 v[176:177], v[176:177], v[24:25]
	v_pk_add_f32 v[176:177], v[176:177], v[26:27]
	v_add_f32_e32 v228, v176, v177
	v_pk_add_f32 v[178:179], v[92:93], v[94:95]
	v_pk_add_f32 v[178:179], v[178:179], v[88:89]
	v_pk_add_f32 v[178:179], v[178:179], v[90:91]
	v_pk_add_f32 v[178:179], v[178:179], v[20:21]
	v_pk_add_f32 v[178:179], v[178:179], v[22:23]
	v_pk_add_f32 v[178:179], v[178:179], v[16:17]
	v_pk_add_f32 v[178:179], v[178:179], v[18:19]
	v_add_f32_e32 v229, v178, v179
	v_pk_add_f32 v[180:181], v[84:85], v[86:87]
	v_pk_add_f32 v[180:181], v[180:181], v[80:81]
	v_pk_add_f32 v[180:181], v[180:181], v[82:83]
	v_pk_add_f32 v[180:181], v[180:181], v[12:13]
	v_pk_add_f32 v[180:181], v[180:181], v[14:15]
	v_pk_add_f32 v[180:181], v[180:181], v[8:9]
	v_pk_add_f32 v[180:181], v[180:181], v[10:11]
	v_add_f32_e32 v230, v180, v181
	v_pk_add_f32 v[182:183], v[76:77], v[78:79]
	v_pk_add_f32 v[182:183], v[182:183], v[72:73]
	v_pk_add_f32 v[182:183], v[182:183], v[74:75]
	v_pk_add_f32 v[182:183], v[182:183], v[4:5]
	v_pk_add_f32 v[182:183], v[182:183], v[6:7]
	v_pk_add_f32 v[182:183], v[182:183], v[0:1]
; __global__ void __launch_bounds__(512, 2) fwd_kernel(Args a) {
;     ...
;             for (int q = 0; q < 4; ++q) { float s_ = 0.f;
; #pragma unroll
;                 for (int j = 0; j < 8; ++j) s_ += (vr[q][j][0] + vr[q][j][1]) + (vr[q][j][2] + vr[q][j][3]);
;                 sm[q] = wave_sum(s_) * (1.0f / DMODEL); }
; #pragma unroll
;             for (int q = 0; q < 4; ++q) { float s2 = 0.f;
; #pragma unroll
;                 for (int j = 0; j < 8; ++j) { vr[q][j] = vr[q][j] - sm[q]; s2 += (vr[q][j][0] * vr[q][j][0] + vr[q][j][1] * vr[q][j][1]) + (vr[q][j][2] * vr[q][j][2] + vr[q][j][3] * vr[q][j][3]); }
;                 qq[q] = wave_sum(s2); rs[q] = 1.0f / sqrtf(qq[q] * (1.0f / DMODEL) + LN_EPS); }
	v_pk_add_f32 v[182:183], v[182:183], v[2:3]
	v_add_f32_e32 v231, v182, v183
	v_mov_b32_e32 v198, v224
	v_mov_b32_e32 v206, v224
	v_mov_b32_e32 v199, v225
	v_mov_b32_e32 v207, v225
	v_mov_b32_e32 v200, v226
	v_mov_b32_e32 v208, v226
	v_mov_b32_e32 v201, v227
	v_mov_b32_e32 v209, v227
	v_mov_b32_e32 v202, v228
	v_mov_b32_e32 v210, v228
	v_mov_b32_e32 v203, v229
	v_mov_b32_e32 v211, v229
	v_mov_b32_e32 v204, v230
	v_mov_b32_e32 v212, v230
	v_mov_b32_e32 v205, v231
	v_mov_b32_e32 v213, v231
	s_nop 1
	v_permlane16_swap_b32_e32 v198, v206
	v_permlane16_swap_b32_e32 v199, v207
	v_permlane16_swap_b32_e32 v200, v208
	v_permlane16_swap_b32_e32 v201, v209
	v_permlane16_swap_b32_e32 v202, v210
	v_permlane16_swap_b32_e32 v203, v211
	v_permlane16_swap_b32_e32 v204, v212
	v_permlane16_swap_b32_e32 v205, v213
	s_nop 1
	v_add_f32_e32 v224, v198, v206
	v_add_f32_e32 v225, v199, v207
	v_add_f32_e32 v226, v200, v208
	v_add_f32_e32 v227, v201, v209
	v_add_f32_e32 v228, v202, v210
	v_add_f32_e32 v229, v203, v211
	v_add_f32_e32 v230, v204, v212
	v_add_f32_e32 v231, v205, v213
	v_mov_b32_e32 v198, v224
	v_mov_b32_e32 v206, v224
	v_mov_b32_e32 v199, v225
	v_mov_b32_e32 v207, v225
	v_mov_b32_e32 v200, v226
	v_mov_b32_e32 v208, v226
	v_mov_b32_e32 v201, v227
	v_mov_b32_e32 v209, v227
	v_mov_b32_e32 v202, v228
	v_mov_b32_e32 v210, v228
	v_mov_b32_e32 v203, v229
	v_mov_b32_e32 v211, v229
	v_mov_b32_e32 v204, v230
	v_mov_b32_e32 v212, v230
	v_mov_b32_e32 v205, v231
	v_mov_b32_e32 v213, v231
	s_nop 1
	v_permlane32_swap_b32_e32 v198, v206
	v_permlane32_swap_b32_e32 v199, v207
	v_permlane32_swap_b32_e32 v200, v208
	v_permlane32_swap_b32_e32 v201, v209
	v_permlane32_swap_b32_e32 v202, v210
	v_permlane32_swap_b32_e32 v203, v211
	v_permlane32_swap_b32_e32 v204, v212
	v_permlane32_swap_b32_e32 v205, v213
	s_nop 1
	v_add_f32_e32 v224, v198, v206
	v_add_f32_e32 v225, v199, v207
	v_add_f32_e32 v226, v200, v208
	v_add_f32_e32 v227, v201, v209
	v_add_f32_e32 v228, v202, v210
	v_add_f32_e32 v229, v203, v211
	v_add_f32_e32 v230, v204, v212
	v_add_f32_e32 v231, v205, v213
	s_and_b32 s56, s96, 3
	s_lshl_b32 s56, s56, 2
	v_lshl_add_u32 v214, v170, 4, s56
	v_lshlrev_b32_e32 v215, 4, v170
	s_waitcnt vmcnt(0) lgkmcnt(0)
	s_barrier
	ds_write_b32 v214, v224
	ds_write_b32 v214, v225 offset:256
	ds_write_b32 v214, v226 offset:512
	ds_write_b32 v214, v227 offset:768
	ds_write_b32 v214, v228 offset:2048
	ds_write_b32 v214, v229 offset:2304
	ds_write_b32 v214, v230 offset:2560
	ds_write_b32 v214, v231 offset:2816
	s_waitcnt lgkmcnt(0)
	s_barrier
	ds_read_b128 v[176:179], v215
	ds_read_b128 v[180:183], v215 offset:256
	ds_read_b128 v[184:187], v215 offset:512
	ds_read_b128 v[188:191], v215 offset:768
	ds_read_b128 v[198:201], v215 offset:2048
	ds_read_b128 v[202:205], v215 offset:2304
	ds_read_b128 v[206:209], v215 offset:2560
	ds_read_b128 v[210:213], v215 offset:2816
	s_waitcnt lgkmcnt(0)
	v_add_f32_e32 v144, v176, v177
	v_add_f32_e32 v144, v144, v178
	v_add_f32_e32 v144, v144, v179
	v_mul_f32_e32 v136, 0x3b800000, v144
	v_add_f32_e32 v146, v180, v181
	v_add_f32_e32 v146, v146, v182
	v_add_f32_e32 v146, v146, v183
	v_mul_f32_e32 v138, 0x3b800000, v146
	v_add_f32_e32 v148, v184, v185
	v_add_f32_e32 v148, v148, v186
	v_add_f32_e32 v148, v148, v187
	v_mul_f32_e32 v140, 0x3b800000, v148
	v_add_f32_e32 v150, v188, v189
	v_add_f32_e32 v150, v150, v190
	v_add_f32_e32 v150, v150, v191
	v_mul_f32_e32 v142, 0x3b800000, v150
	v_add_f32_e32 v152, v198, v199
	v_add_f32_e32 v152, v152, v200
	v_add_f32_e32 v152, v152, v201
	v_mul_f32_e32 v64, 0x3b800000, v152
	v_add_f32_e32 v154, v202, v203
	v_add_f32_e32 v154, v154, v204
	v_add_f32_e32 v154, v154, v205
	v_mul_f32_e32 v66, 0x3b800000, v154
	v_add_f32_e32 v156, v206, v207
	v_add_f32_e32 v156, v156, v208
	v_add_f32_e32 v156, v156, v209
	v_mul_f32_e32 v68, 0x3b800000, v156
	v_add_f32_e32 v158, v210, v211
	v_add_f32_e32 v158, v158, v212
	v_add_f32_e32 v158, v158, v213
	v_mul_f32_e32 v70, 0x3b800000, v158
	v_pk_add_f32 v[178:179], v[132:133], v[136:137] op_sel_hi:[1,0] neg_lo:[0,1] neg_hi:[0,1]
	v_pk_mul_f32 v[176:177], v[178:179], v[178:179]
	v_pk_add_f32 v[178:179], v[134:135], v[136:137] op_sel_hi:[1,0] neg_lo:[0,1] neg_hi:[0,1]
	v_pk_fma_f32 v[176:177], v[178:179], v[178:179], v[176:177]
	v_pk_add_f32 v[178:179], v[128:129], v[136:137] op_sel_hi:[1,0] neg_lo:[0,1] neg_hi:[0,1]
	v_pk_fma_f32 v[176:177], v[178:179], v[178:179], v[176:177]
	v_pk_add_f32 v[178:179], v[130:131], v[136:137] op_sel_hi:[1,0] neg_lo:[0,1] neg_hi:[0,1]
	v_pk_fma_f32 v[176:177], v[178:179], v[178:179], v[176:177]
	v_pk_add_f32 v[178:179], v[60:61], v[136:137] op_sel_hi:[1,0] neg_lo:[0,1] neg_hi:[0,1]
	v_pk_fma_f32 v[176:177], v[178:179], v[178:179], v[176:177]
	v_pk_add_f32 v[178:179], v[62:63], v[136:137] op_sel_hi:[1,0] neg_lo:[0,1] neg_hi:[0,1]
	v_pk_fma_f32 v[176:177], v[178:179], v[178:179], v[176:177]
	v_pk_add_f32 v[178:179], v[56:57], v[136:137] op_sel_hi:[1,0] neg_lo:[0,1] neg_hi:[0,1]
	v_pk_fma_f32 v[176:177], v[178:179], v[178:179], v[176:177]
	v_pk_add_f32 v[178:179], v[58:59], v[136:137] op_sel_hi:[1,0] neg_lo:[0,1] neg_hi:[0,1]
	v_pk_fma_f32 v[176:177], v[178:179], v[178:179], v[176:177]
	v_add_f32_e32 v224, v176, v177
	v_pk_add_f32 v[182:183], v[124:125], v[138:139] op_sel_hi:[1,0] neg_lo:[0,1] neg_hi:[0,1]
	v_pk_mul_f32 v[180:181], v[182:183], v[182:183]
	v_pk_add_f32 v[182:183], v[126:127], v[138:139] op_sel_hi:[1,0] neg_lo:[0,1] neg_hi:[0,1]
	v_pk_fma_f32 v[180:181], v[182:183], v[182:183], v[180:181]
	v_pk_add_f32 v[182:183], v[120:121], v[138:139] op_sel_hi:[1,0] neg_lo:[0,1] neg_hi:[0,1]
	v_pk_fma_f32 v[180:181], v[182:183], v[182:183], v[180:181]
; __global__ void __launch_bounds__(512, 2) fwd_kernel(Args a) {
;     ...
;             for (int q = 0; q < 4; ++q) { float s2 = 0.f;
; #pragma unroll
;                 for (int j = 0; j < 8; ++j) { vr[q][j] = vr[q][j] - sm[q]; s2 += (vr[q][j][0] * vr[q][j][0] + vr[q][j][1] * vr[q][j][1]) + (vr[q][j][2] * vr[q][j][2] + vr[q][j][3] * vr[q][j][3]); }
;                 qq[q] = wave_sum(s2); rs[q] = 1.0f / sqrtf(qq[q] * (1.0f / DMODEL) + LN_EPS); }
	v_pk_add_f32 v[182:183], v[122:123], v[138:139] op_sel_hi:[1,0] neg_lo:[0,1] neg_hi:[0,1]
	v_pk_fma_f32 v[180:181], v[182:183], v[182:183], v[180:181]
	v_pk_add_f32 v[182:183], v[52:53], v[138:139] op_sel_hi:[1,0] neg_lo:[0,1] neg_hi:[0,1]
	v_pk_fma_f32 v[180:181], v[182:183], v[182:183], v[180:181]
	v_pk_add_f32 v[182:183], v[54:55], v[138:139] op_sel_hi:[1,0] neg_lo:[0,1] neg_hi:[0,1]
	v_pk_fma_f32 v[180:181], v[182:183], v[182:183], v[180:181]
	v_pk_add_f32 v[182:183], v[48:49], v[138:139] op_sel_hi:[1,0] neg_lo:[0,1] neg_hi:[0,1]
	v_pk_fma_f32 v[180:181], v[182:183], v[182:183], v[180:181]
	v_pk_add_f32 v[182:183], v[50:51], v[138:139] op_sel_hi:[1,0] neg_lo:[0,1] neg_hi:[0,1]
	v_pk_fma_f32 v[180:181], v[182:183], v[182:183], v[180:181]
	v_add_f32_e32 v225, v180, v181
	v_pk_add_f32 v[186:187], v[116:117], v[140:141] op_sel_hi:[1,0] neg_lo:[0,1] neg_hi:[0,1]
	v_pk_mul_f32 v[184:185], v[186:187], v[186:187]
	v_pk_add_f32 v[186:187], v[118:119], v[140:141] op_sel_hi:[1,0] neg_lo:[0,1] neg_hi:[0,1]
	v_pk_fma_f32 v[184:185], v[186:187], v[186:187], v[184:185]
	v_pk_add_f32 v[186:187], v[112:113], v[140:141] op_sel_hi:[1,0] neg_lo:[0,1] neg_hi:[0,1]
	v_pk_fma_f32 v[184:185], v[186:187], v[186:187], v[184:185]
	v_pk_add_f32 v[186:187], v[114:115], v[140:141] op_sel_hi:[1,0] neg_lo:[0,1] neg_hi:[0,1]
	v_pk_fma_f32 v[184:185], v[186:187], v[186:187], v[184:185]
	v_pk_add_f32 v[186:187], v[44:45], v[140:141] op_sel_hi:[1,0] neg_lo:[0,1] neg_hi:[0,1]
	v_pk_fma_f32 v[184:185], v[186:187], v[186:187], v[184:185]
	v_pk_add_f32 v[186:187], v[46:47], v[140:141] op_sel_hi:[1,0] neg_lo:[0,1] neg_hi:[0,1]
	v_pk_fma_f32 v[184:185], v[186:187], v[186:187], v[184:185]
	v_pk_add_f32 v[186:187], v[40:41], v[140:141] op_sel_hi:[1,0] neg_lo:[0,1] neg_hi:[0,1]
	v_pk_fma_f32 v[184:185], v[186:187], v[186:187], v[184:185]
	v_pk_add_f32 v[186:187], v[42:43], v[140:141] op_sel_hi:[1,0] neg_lo:[0,1] neg_hi:[0,1]
	v_pk_fma_f32 v[184:185], v[186:187], v[186:187], v[184:185]
	v_add_f32_e32 v226, v184, v185
	v_pk_add_f32 v[190:191], v[108:109], v[142:143] op_sel_hi:[1,0] neg_lo:[0,1] neg_hi:[0,1]
	v_pk_mul_f32 v[188:189], v[190:191], v[190:191]
	v_pk_add_f32 v[190:191], v[110:111], v[142:143] op_sel_hi:[1,0] neg_lo:[0,1] neg_hi:[0,1]
	v_pk_fma_f32 v[188:189], v[190:191], v[190:191], v[188:189]
	v_pk_add_f32 v[190:191], v[104:105], v[142:143] op_sel_hi:[1,0] neg_lo:[0,1] neg_hi:[0,1]
	v_pk_fma_f32 v[188:189], v[190:191], v[190:191], v[188:189]
	v_pk_add_f32 v[190:191], v[106:107], v[142:143] op_sel_hi:[1,0] neg_lo:[0,1] neg_hi:[0,1]
	v_pk_fma_f32 v[188:189], v[190:191], v[190:191], v[188:189]
	v_pk_add_f32 v[190:191], v[36:37], v[142:143] op_sel_hi:[1,0] neg_lo:[0,1] neg_hi:[0,1]
	v_pk_fma_f32 v[188:189], v[190:191], v[190:191], v[188:189]
	v_pk_add_f32 v[190:191], v[38:39], v[142:143] op_sel_hi:[1,0] neg_lo:[0,1] neg_hi:[0,1]
	v_pk_fma_f32 v[188:189], v[190:191], v[190:191], v[188:189]
	v_pk_add_f32 v[190:191], v[32:33], v[142:143] op_sel_hi:[1,0] neg_lo:[0,1] neg_hi:[0,1]
	v_pk_fma_f32 v[188:189], v[190:191], v[190:191], v[188:189]
	v_pk_add_f32 v[190:191], v[34:35], v[142:143] op_sel_hi:[1,0] neg_lo:[0,1] neg_hi:[0,1]
	v_pk_fma_f32 v[188:189], v[190:191], v[190:191], v[188:189]
	v_add_f32_e32 v227, v188, v189
	v_pk_add_f32 v[178:179], v[100:101], v[64:65] op_sel_hi:[1,0] neg_lo:[0,1] neg_hi:[0,1]
	v_pk_mul_f32 v[176:177], v[178:179], v[178:179]
	v_pk_add_f32 v[178:179], v[102:103], v[64:65] op_sel_hi:[1,0] neg_lo:[0,1] neg_hi:[0,1]
	v_pk_fma_f32 v[176:177], v[178:179], v[178:179], v[176:177]
	v_pk_add_f32 v[178:179], v[96:97], v[64:65] op_sel_hi:[1,0] neg_lo:[0,1] neg_hi:[0,1]
	v_pk_fma_f32 v[176:177], v[178:179], v[178:179], v[176:177]
	v_pk_add_f32 v[178:179], v[98:99], v[64:65] op_sel_hi:[1,0] neg_lo:[0,1] neg_hi:[0,1]
	v_pk_fma_f32 v[176:177], v[178:179], v[178:179], v[176:177]
	v_pk_add_f32 v[178:179], v[28:29], v[64:65] op_sel_hi:[1,0] neg_lo:[0,1] neg_hi:[0,1]
	v_pk_fma_f32 v[176:177], v[178:179], v[178:179], v[176:177]
	v_pk_add_f32 v[178:179], v[30:31], v[64:65] op_sel_hi:[1,0] neg_lo:[0,1] neg_hi:[0,1]
	v_pk_fma_f32 v[176:177], v[178:179], v[178:179], v[176:177]
	v_pk_add_f32 v[178:179], v[24:25], v[64:65] op_sel_hi:[1,0] neg_lo:[0,1] neg_hi:[0,1]
	v_pk_fma_f32 v[176:177], v[178:179], v[178:179], v[176:177]
	v_pk_add_f32 v[178:179], v[26:27], v[64:65] op_sel_hi:[1,0] neg_lo:[0,1] neg_hi:[0,1]
	v_pk_fma_f32 v[176:177], v[178:179], v[178:179], v[176:177]
	v_add_f32_e32 v228, v176, v177
	v_pk_add_f32 v[182:183], v[92:93], v[66:67] op_sel_hi:[1,0] neg_lo:[0,1] neg_hi:[0,1]
	v_pk_mul_f32 v[180:181], v[182:183], v[182:183]
	v_pk_add_f32 v[182:183], v[94:95], v[66:67] op_sel_hi:[1,0] neg_lo:[0,1] neg_hi:[0,1]
	v_pk_fma_f32 v[180:181], v[182:183], v[182:183], v[180:181]
	v_pk_add_f32 v[182:183], v[88:89], v[66:67] op_sel_hi:[1,0] neg_lo:[0,1] neg_hi:[0,1]
	v_pk_fma_f32 v[180:181], v[182:183], v[182:183], v[180:181]
	v_pk_add_f32 v[182:183], v[90:91], v[66:67] op_sel_hi:[1,0] neg_lo:[0,1] neg_hi:[0,1]
	v_pk_fma_f32 v[180:181], v[182:183], v[182:183], v[180:181]
	v_pk_add_f32 v[182:183], v[20:21], v[66:67] op_sel_hi:[1,0] neg_lo:[0,1] neg_hi:[0,1]
	v_pk_fma_f32 v[180:181], v[182:183], v[182:183], v[180:181]
	v_pk_add_f32 v[182:183], v[22:23], v[66:67] op_sel_hi:[1,0] neg_lo:[0,1] neg_hi:[0,1]
	v_pk_fma_f32 v[180:181], v[182:183], v[182:183], v[180:181]
	v_pk_add_f32 v[182:183], v[16:17], v[66:67] op_sel_hi:[1,0] neg_lo:[0,1] neg_hi:[0,1]
	v_pk_fma_f32 v[180:181], v[182:183], v[182:183], v[180:181]
	v_pk_add_f32 v[182:183], v[18:19], v[66:67] op_sel_hi:[1,0] neg_lo:[0,1] neg_hi:[0,1]
	v_pk_fma_f32 v[180:181], v[182:183], v[182:183], v[180:181]
	v_add_f32_e32 v229, v180, v181
; __global__ void __launch_bounds__(512, 2) fwd_kernel(Args a) {
;     ...
;             for (int q = 0; q < 4; ++q) { float s2 = 0.f;
; #pragma unroll
;                 for (int j = 0; j < 8; ++j) { vr[q][j] = vr[q][j] - sm[q]; s2 += (vr[q][j][0] * vr[q][j][0] + vr[q][j][1] * vr[q][j][1]) + (vr[q][j][2] * vr[q][j][2] + vr[q][j][3] * vr[q][j][3]); }
;                 qq[q] = wave_sum(s2); rs[q] = 1.0f / sqrtf(qq[q] * (1.0f / DMODEL) + LN_EPS); }
	v_pk_add_f32 v[186:187], v[84:85], v[68:69] op_sel_hi:[1,0] neg_lo:[0,1] neg_hi:[0,1]
	v_pk_mul_f32 v[184:185], v[186:187], v[186:187]
	v_pk_add_f32 v[186:187], v[86:87], v[68:69] op_sel_hi:[1,0] neg_lo:[0,1] neg_hi:[0,1]
	v_pk_fma_f32 v[184:185], v[186:187], v[186:187], v[184:185]
	v_pk_add_f32 v[186:187], v[80:81], v[68:69] op_sel_hi:[1,0] neg_lo:[0,1] neg_hi:[0,1]
	v_pk_fma_f32 v[184:185], v[186:187], v[186:187], v[184:185]
	v_pk_add_f32 v[186:187], v[82:83], v[68:69] op_sel_hi:[1,0] neg_lo:[0,1] neg_hi:[0,1]
	v_pk_fma_f32 v[184:185], v[186:187], v[186:187], v[184:185]
	v_pk_add_f32 v[186:187], v[12:13], v[68:69] op_sel_hi:[1,0] neg_lo:[0,1] neg_hi:[0,1]
	v_pk_fma_f32 v[184:185], v[186:187], v[186:187], v[184:185]
	v_pk_add_f32 v[186:187], v[14:15], v[68:69] op_sel_hi:[1,0] neg_lo:[0,1] neg_hi:[0,1]
	v_pk_fma_f32 v[184:185], v[186:187], v[186:187], v[184:185]
	v_pk_add_f32 v[186:187], v[8:9], v[68:69] op_sel_hi:[1,0] neg_lo:[0,1] neg_hi:[0,1]
	v_pk_fma_f32 v[184:185], v[186:187], v[186:187], v[184:185]
	v_pk_add_f32 v[186:187], v[10:11], v[68:69] op_sel_hi:[1,0] neg_lo:[0,1] neg_hi:[0,1]
	v_pk_fma_f32 v[184:185], v[186:187], v[186:187], v[184:185]
	v_add_f32_e32 v230, v184, v185
	v_pk_add_f32 v[190:191], v[76:77], v[70:71] op_sel_hi:[1,0] neg_lo:[0,1] neg_hi:[0,1]
	v_pk_mul_f32 v[188:189], v[190:191], v[190:191]
	v_pk_add_f32 v[190:191], v[78:79], v[70:71] op_sel_hi:[1,0] neg_lo:[0,1] neg_hi:[0,1]
	v_pk_fma_f32 v[188:189], v[190:191], v[190:191], v[188:189]
	v_pk_add_f32 v[190:191], v[72:73], v[70:71] op_sel_hi:[1,0] neg_lo:[0,1] neg_hi:[0,1]
	v_pk_fma_f32 v[188:189], v[190:191], v[190:191], v[188:189]
	v_pk_add_f32 v[190:191], v[74:75], v[70:71] op_sel_hi:[1,0] neg_lo:[0,1] neg_hi:[0,1]
	v_pk_fma_f32 v[188:189], v[190:191], v[190:191], v[188:189]
	v_pk_add_f32 v[190:191], v[4:5], v[70:71] op_sel_hi:[1,0] neg_lo:[0,1] neg_hi:[0,1]
	v_pk_fma_f32 v[188:189], v[190:191], v[190:191], v[188:189]
	v_pk_add_f32 v[190:191], v[6:7], v[70:71] op_sel_hi:[1,0] neg_lo:[0,1] neg_hi:[0,1]
	v_pk_fma_f32 v[188:189], v[190:191], v[190:191], v[188:189]
	v_pk_add_f32 v[190:191], v[0:1], v[70:71] op_sel_hi:[1,0] neg_lo:[0,1] neg_hi:[0,1]
	v_pk_fma_f32 v[188:189], v[190:191], v[190:191], v[188:189]
	v_pk_add_f32 v[190:191], v[2:3], v[70:71] op_sel_hi:[1,0] neg_lo:[0,1] neg_hi:[0,1]
	v_pk_fma_f32 v[188:189], v[190:191], v[190:191], v[188:189]
	v_add_f32_e32 v231, v188, v189
	v_mov_b32_e32 v198, v224
	v_mov_b32_e32 v206, v224
	v_mov_b32_e32 v199, v225
	v_mov_b32_e32 v207, v225
	v_mov_b32_e32 v200, v226
	v_mov_b32_e32 v208, v226
	v_mov_b32_e32 v201, v227
	v_mov_b32_e32 v209, v227
	v_mov_b32_e32 v202, v228
	v_mov_b32_e32 v210, v228
	v_mov_b32_e32 v203, v229
	v_mov_b32_e32 v211, v229
	v_mov_b32_e32 v204, v230
	v_mov_b32_e32 v212, v230
	v_mov_b32_e32 v205, v231
	v_mov_b32_e32 v213, v231
	s_nop 1
	v_permlane16_swap_b32_e32 v198, v206
	v_permlane16_swap_b32_e32 v199, v207
	v_permlane16_swap_b32_e32 v200, v208
	v_permlane16_swap_b32_e32 v201, v209
	v_permlane16_swap_b32_e32 v202, v210
	v_permlane16_swap_b32_e32 v203, v211
	v_permlane16_swap_b32_e32 v204, v212
	v_permlane16_swap_b32_e32 v205, v213
	s_nop 1
	v_add_f32_e32 v224, v198, v206
	v_add_f32_e32 v225, v199, v207
	v_add_f32_e32 v226, v200, v208
	v_add_f32_e32 v227, v201, v209
	v_add_f32_e32 v228, v202, v210
	v_add_f32_e32 v229, v203, v211
	v_add_f32_e32 v230, v204, v212
	v_add_f32_e32 v231, v205, v213
	v_mov_b32_e32 v198, v224
	v_mov_b32_e32 v206, v224
	v_mov_b32_e32 v199, v225
	v_mov_b32_e32 v207, v225
	v_mov_b32_e32 v200, v226
	v_mov_b32_e32 v208, v226
	v_mov_b32_e32 v201, v227
	v_mov_b32_e32 v209, v227
	v_mov_b32_e32 v202, v228
	v_mov_b32_e32 v210, v228
	v_mov_b32_e32 v203, v229
	v_mov_b32_e32 v211, v229
	v_mov_b32_e32 v204, v230
	v_mov_b32_e32 v212, v230
	v_mov_b32_e32 v205, v231
	v_mov_b32_e32 v213, v231
	s_nop 1
	v_permlane32_swap_b32_e32 v198, v206
	v_permlane32_swap_b32_e32 v199, v207
	v_permlane32_swap_b32_e32 v200, v208
	v_permlane32_swap_b32_e32 v201, v209
	v_permlane32_swap_b32_e32 v202, v210
	v_permlane32_swap_b32_e32 v203, v211
	v_permlane32_swap_b32_e32 v204, v212
	v_permlane32_swap_b32_e32 v205, v213
	s_nop 1
	v_add_f32_e32 v224, v198, v206
	v_add_f32_e32 v225, v199, v207
	v_add_f32_e32 v226, v200, v208
	v_add_f32_e32 v227, v201, v209
	v_add_f32_e32 v228, v202, v210
	v_add_f32_e32 v229, v203, v211
	v_add_f32_e32 v230, v204, v212
	v_add_f32_e32 v231, v205, v213
	ds_write_b32 v214, v224 offset:4096
	ds_write_b32 v214, v225 offset:4352
	ds_write_b32 v214, v226 offset:4608
	ds_write_b32 v214, v227 offset:4864
	ds_write_b32 v214, v228 offset:6144
	ds_write_b32 v214, v229 offset:6400
	ds_write_b32 v214, v230 offset:6656
	ds_write_b32 v214, v231 offset:6912
	s_waitcnt lgkmcnt(0)
	s_barrier
	ds_read_b128 v[176:179], v215 offset:4096
	ds_read_b128 v[180:183], v215 offset:4352
	ds_read_b128 v[184:187], v215 offset:4608
	ds_read_b128 v[188:191], v215 offset:4864
	ds_read_b128 v[198:201], v215 offset:6144
	ds_read_b128 v[202:205], v215 offset:6400
	ds_read_b128 v[206:209], v215 offset:6656
	ds_read_b128 v[210:213], v215 offset:6912
	s_waitcnt lgkmcnt(0)
	v_add_f32_e32 v145, v176, v177
	v_add_f32_e32 v145, v145, v178
	v_add_f32_e32 v145, v145, v179
	v_add_f32_e32 v147, v180, v181
	v_add_f32_e32 v147, v147, v182
	v_add_f32_e32 v147, v147, v183
	v_add_f32_e32 v149, v184, v185
	v_add_f32_e32 v149, v149, v186
	v_add_f32_e32 v149, v149, v187
	v_add_f32_e32 v151, v188, v189
	v_add_f32_e32 v151, v151, v190
	v_add_f32_e32 v151, v151, v191
	v_add_f32_e32 v153, v198, v199
	v_add_f32_e32 v153, v153, v200
	v_add_f32_e32 v153, v153, v201
	v_add_f32_e32 v155, v202, v203
	v_add_f32_e32 v155, v155, v204
	v_add_f32_e32 v155, v155, v205
	v_add_f32_e32 v157, v206, v207
	v_add_f32_e32 v157, v157, v208
	v_add_f32_e32 v157, v157, v209
	v_add_f32_e32 v159, v210, v211
	v_add_f32_e32 v159, v159, v212
	v_add_f32_e32 v159, v159, v213
	s_and_b32 s56, s96, 3
	s_cmp_lg_u32 s56, 0
	s_cbranch_scc1 .Lln2_nostat
	s_mov_b64 s[58:59], exec
	s_mov_b64 exec, 0xffff
	v_lshlrev_b32_e32 v216, 6, v168
	v_lshrrev_b32_e32 v217, 10, v164
	v_lshl_add_u32 v216, v217, 3, v216
	v_add_u32_e32 v216, 0x10000, v216
	v_add_u32_e32 v217, 0x0, v216
	global_store_dwordx2 v217, v[144:145], s[60:61]
	v_add_u32_e32 v217, 0x400, v216
	global_store_dwordx2 v217, v[146:147], s[60:61]
	v_add_u32_e32 v217, 0x800, v216
	global_store_dwordx2 v217, v[148:149], s[60:61]
	v_add_u32_e32 v217, 0xc00, v216
	global_store_dwordx2 v217, v[150:151], s[60:61]
	v_add_u32_e32 v217, 0x2000, v216
	global_store_dwordx2 v217, v[152:153], s[60:61]
	v_add_u32_e32 v217, 0x2400, v216
	global_store_dwordx2 v217, v[154:155], s[60:61]
	v_add_u32_e32 v217, 0x2800, v216
	global_store_dwordx2 v217, v[156:157], s[60:61]
	v_add_u32_e32 v217, 0x2c00, v216
	global_store_dwordx2 v217, v[158:159], s[60:61]
	s_mov_b64 exec, s[58:59]

; __global__ void __launch_bounds__(512, 2) fwd_kernel(Args a) {
;     ...
;             for (int q = 0; q < 4; ++q) { float s_ = 0.f;
; #pragma unroll
;                 for (int j = 0; j < 8; ++j) s_ += (vr[q][j][0] + vr[q][j][1]) + (vr[q][j][2] + vr[q][j][3]);
;                 sm[q] = wave_sum(s_) * (1.0f / DMODEL); }
; #pragma unroll
;             for (int q = 0; q < 4; ++q) { float s2 = 0.f;
; #pragma unroll
;                 for (int j = 0; j < 8; ++j) { vr[q][j] = vr[q][j] - sm[q]; s2 += (vr[q][j][0] * vr[q][j][0] + vr[q][j][1] * vr[q][j][1]) + (vr[q][j][2] * vr[q][j][2] + vr[q][j][3] * vr[q][j][3]); }
;                 qq[q] = wave_sum(s2); rs[q] = 1.0f / sqrtf(qq[q] * (1.0f / DMODEL) + LN_EPS); }
; #pragma unroll
;             for (int q = 0; q < 4; ++q)
; #pragma unroll
;                 for (int j = 0; j < 8; ++j) __builtin_nontemporal_store(vr[q][j] * rs[q] * ggv[j] + bbv[j], xr + 512 * q + 64 * j); }
.LBB0_1156:
	s_cmp_lt_i32 s90, 13
	s_cselect_b64 s[0:1], -1, 0
	s_and_b64 s[0:1], s[0:1], s[2:3]
	s_andn2_b64 vcc, exec, s[0:1]
	s_cbranch_vccnz .LBB0_1160
	s_add_i32 s0, 0, 0x22098
	s_add_i32 s1, 0, 0x22088
	v_mov_b32_e32 v0, s0
	ds_read_b64 v[4:5], v0
	v_mov_b32_e32 v0, s1
	ds_read2_b64 v[0:3], v0 offset1:1
	s_cmpk_gt_i32 s96, 0x7ff
	s_waitcnt lgkmcnt(0)
	v_readfirstlane_b32 s3, v4
	v_readfirstlane_b32 s8, v5
	v_readfirstlane_b32 s0, v0
	v_readfirstlane_b32 s1, v1
	v_readfirstlane_b32 s6, v2
	v_readfirstlane_b32 s7, v3
	s_cbranch_scc1 .LBB0_1160
	s_add_i32 s2, 0, 0x220a0
	v_mov_b32_e32 v0, s2
	ds_read_b64 v[0:1], v0
	s_mov_b32 s4, s3
	s_mov_b32 s5, s8
	s_mov_b32 s3, 0xf800000
	s_mov_b32 s9, 0x3b800000
	v_lshl_add_u64 v[2:3], s[0:1], 0, v[164:165]
	v_lshl_add_u64 v[4:5], s[6:7], 0, v[164:165]
	global_load_dwordx4 v[224:227], v[2:3], off
	global_load_dwordx4 v[228:231], v[2:3], off offset:64
	global_load_dwordx4 v[232:235], v[2:3], off offset:512
	global_load_dwordx4 v[236:239], v[2:3], off offset:576
	global_load_dwordx4 v[136:139], v[4:5], off
	global_load_dwordx4 v[140:143], v[4:5], off offset:64
	global_load_dwordx4 v[144:147], v[4:5], off offset:512
	global_load_dwordx4 v[148:151], v[4:5], off offset:576
	s_waitcnt lgkmcnt(0)
	v_readfirstlane_b32 s10, v0
	v_readfirstlane_b32 s11, v1
	s_add_u32 s10, s10, 0x220000
	s_addc_u32 s11, s11, 0
	v_lshlrev_b32_e32 v154, 13, v168
	v_mov_b32_e32 v155, 0
	v_lshl_add_u64 v[152:153], s[4:5], 0, v[154:155]
	v_lshl_add_u64 v[152:153], v[152:153], 0, v[164:165]
	v_lshlrev_b32_e32 v156, 6, v168
	v_mov_b32_e32 v157, 0x3727c5ac
	v_mov_b32_e32 v158, 0x260
	v_add_u32_e32 v159, 0x0, v156
	global_load_dwordx4 v[198:201], v159, s[10:11]
	global_load_dwordx4 v[202:205], v159, s[10:11] offset:16
	global_load_dwordx4 v[206:209], v159, s[10:11] offset:32
	global_load_dwordx4 v[210:213], v159, s[10:11] offset:48
	v_add_u32_e32 v159, 0x400, v156
	global_load_dwordx4 v[0:3], v159, s[10:11]
	global_load_dwordx4 v[4:7], v159, s[10:11] offset:16
	global_load_dwordx4 v[8:11], v159, s[10:11] offset:32
	global_load_dwordx4 v[12:15], v159, s[10:11] offset:48
	s_waitcnt vmcnt(4)
	v_add_f32_e32 v16, v198, v200
	v_add_f32_e32 v16, v16, v202
	v_add_f32_e32 v16, v16, v204
	v_add_f32_e32 v16, v16, v206
	v_add_f32_e32 v16, v16, v208
	v_add_f32_e32 v16, v16, v210
	v_add_f32_e32 v16, v16, v212
	v_mul_f32_e32 v16, 0x3a000000, v16
	v_add_f32_e32 v17, v199, v201
	v_add_f32_e32 v17, v17, v203
	v_add_f32_e32 v17, v17, v205
	v_add_f32_e32 v17, v17, v207
	v_add_f32_e32 v17, v17, v209
	v_add_f32_e32 v17, v17, v211
	v_add_f32_e32 v17, v17, v213
	v_fma_f32 v18, v198, s9, -v16
	v_mul_f32_e32 v18, v18, v18
	v_fmac_f32_e32 v17, 0x43800000, v18
	v_fma_f32 v18, v200, s9, -v16
	v_mul_f32_e32 v18, v18, v18
	v_fmac_f32_e32 v17, 0x43800000, v18
	v_fma_f32 v18, v202, s9, -v16
	v_mul_f32_e32 v18, v18, v18
	v_fmac_f32_e32 v17, 0x43800000, v18
	v_fma_f32 v18, v204, s9, -v16
	v_mul_f32_e32 v18, v18, v18
	v_fmac_f32_e32 v17, 0x43800000, v18
	v_fma_f32 v18, v206, s9, -v16
	v_mul_f32_e32 v18, v18, v18
	v_fmac_f32_e32 v17, 0x43800000, v18
	v_fma_f32 v18, v208, s9, -v16
	v_mul_f32_e32 v18, v18, v18
	v_fmac_f32_e32 v17, 0x43800000, v18
	v_fma_f32 v18, v210, s9, -v16
	v_mul_f32_e32 v18, v18, v18
	v_fmac_f32_e32 v17, 0x43800000, v18
	v_fma_f32 v18, v212, s9, -v16
	v_mul_f32_e32 v18, v18, v18
	v_fmac_f32_e32 v17, 0x43800000, v18
	v_fmamk_f32 v17, v17, 0x3a000000, v157
	v_mul_f32_e32 v18, 0x4f800000, v17
	v_cmp_gt_f32_e32 vcc, s3, v17
	s_nop 1
	v_cndmask_b32_e32 v214, v17, v18, vcc
	v_sqrt_f32_e32 v215, v214
	s_nop 1
	v_add_u32_e32 v216, -1, v215
	v_fma_f32 v217, -v216, v215, v214
	v_cmp_ge_f32_e64 s[14:15], 0, v217
	v_add_u32_e32 v217, 1, v215
	v_fma_f32 v218, -v217, v215, v214
	s_nop 0
	v_cndmask_b32_e64 v216, v215, v216, s[14:15]
	v_cmp_lt_f32_e64 s[14:15], 0, v218
	s_nop 1
	v_cndmask_b32_e64 v216, v216, v217, s[14:15]
	v_mul_f32_e32 v217, 0x37800000, v216
	v_cndmask_b32_e32 v216, v216, v217, vcc
	v_cmp_class_f32_e32 vcc, v214, v158
	s_nop 1
	v_cndmask_b32_e32 v214, v216, v214, vcc
	v_div_scale_f32 v215, s[14:15], v214, v214, 1.0
	v_rcp_f32_e32 v216, v215
	s_nop 1
	v_fma_f32 v217, -v215, v216, 1.0
	v_fmac_f32_e32 v216, v217, v216
	v_div_scale_f32 v217, vcc, 1.0, v214, 1.0
	v_mul_f32_e32 v218, v217, v216
	v_fma_f32 v219, -v215, v218, v217
	v_fmac_f32_e32 v218, v219, v216
	v_fma_f32 v217, -v215, v218, v217
	s_nop 1
	v_div_fmas_f32 v215, v217, v216, v218
	v_div_fixup_f32 v214, v215, v214, 1.0
	s_mov_b64 s[12:13], 0x0
	v_lshl_add_u64 v[160:161], v[152:153], 0, s[12:13]
	v_pk_add_f32 v[132:133], v[132:133], v[16:17] op_sel_hi:[1,0] neg_lo:[0,1] neg_hi:[0,1]
	v_pk_mul_f32 v[132:133], v[132:133], v[214:215] op_sel_hi:[1,0]
	v_pk_fma_f32 v[132:133], v[224:225], v[132:133], v[136:137]
	v_pk_add_f32 v[134:135], v[134:135], v[16:17] op_sel_hi:[1,0] neg_lo:[0,1] neg_hi:[0,1]
	v_pk_mul_f32 v[134:135], v[134:135], v[214:215] op_sel_hi:[1,0]
	v_pk_fma_f32 v[134:135], v[226:227], v[134:135], v[138:139]
	global_store_dwordx4 v[160:161], v[132:135], off
	v_pk_add_f32 v[128:129], v[128:129], v[16:17] op_sel_hi:[1,0] neg_lo:[0,1] neg_hi:[0,1]
	v_pk_mul_f32 v[128:129], v[128:129], v[214:215] op_sel_hi:[1,0]
	v_pk_fma_f32 v[128:129], v[228:229], v[128:129], v[140:141]
	v_pk_add_f32 v[130:131], v[130:131], v[16:17] op_sel_hi:[1,0] neg_lo:[0,1] neg_hi:[0,1]
	v_pk_mul_f32 v[130:131], v[130:131], v[214:215] op_sel_hi:[1,0]
	v_pk_fma_f32 v[130:131], v[230:231], v[130:131], v[142:143]
	global_store_dwordx4 v[160:161], v[128:131], off offset:64
	v_pk_add_f32 v[60:61], v[60:61], v[16:17] op_sel_hi:[1,0] neg_lo:[0,1] neg_hi:[0,1]
	v_pk_mul_f32 v[60:61], v[60:61], v[214:215] op_sel_hi:[1,0]
	v_pk_fma_f32 v[60:61], v[232:233], v[60:61], v[144:145]
	v_pk_add_f32 v[62:63], v[62:63], v[16:17] op_sel_hi:[1,0] neg_lo:[0,1] neg_hi:[0,1]
	v_pk_mul_f32 v[62:63], v[62:63], v[214:215] op_sel_hi:[1,0]
	v_pk_fma_f32 v[62:63], v[234:235], v[62:63], v[146:147]
	global_store_dwordx4 v[160:161], v[60:63], off offset:512
	v_pk_add_f32 v[56:57], v[56:57], v[16:17] op_sel_hi:[1,0] neg_lo:[0,1] neg_hi:[0,1]
	v_pk_mul_f32 v[56:57], v[56:57], v[214:215] op_sel_hi:[1,0]
	v_pk_fma_f32 v[56:57], v[236:237], v[56:57], v[148:149]
	v_pk_add_f32 v[58:59], v[58:59], v[16:17] op_sel_hi:[1,0] neg_lo:[0,1] neg_hi:[0,1]
	v_pk_mul_f32 v[58:59], v[58:59], v[214:215] op_sel_hi:[1,0]
	v_pk_fma_f32 v[58:59], v[238:239], v[58:59], v[150:151]
	global_store_dwordx4 v[160:161], v[56:59], off offset:576
	v_add_u32_e32 v159, 0x800, v156
	global_load_dwordx4 v[198:201], v159, s[10:11]
	global_load_dwordx4 v[202:205], v159, s[10:11] offset:16
	global_load_dwordx4 v[206:209], v159, s[10:11] offset:32
	global_load_dwordx4 v[210:213], v159, s[10:11] offset:48
	s_waitcnt vmcnt(8)
; __global__ void __launch_bounds__(512, 2) fwd_kernel(Args a) {
;     ...
;             for (int q = 0; q < 4; ++q) { float s_ = 0.f;
; #pragma unroll
;                 for (int j = 0; j < 8; ++j) s_ += (vr[q][j][0] + vr[q][j][1]) + (vr[q][j][2] + vr[q][j][3]);
;                 sm[q] = wave_sum(s_) * (1.0f / DMODEL); }
; #pragma unroll
;             for (int q = 0; q < 4; ++q) { float s2 = 0.f;
; #pragma unroll
;                 for (int j = 0; j < 8; ++j) { vr[q][j] = vr[q][j] - sm[q]; s2 += (vr[q][j][0] * vr[q][j][0] + vr[q][j][1] * vr[q][j][1]) + (vr[q][j][2] * vr[q][j][2] + vr[q][j][3] * vr[q][j][3]); }
;                 qq[q] = wave_sum(s2); rs[q] = 1.0f / sqrtf(qq[q] * (1.0f / DMODEL) + LN_EPS); }
; #pragma unroll
;             for (int q = 0; q < 4; ++q)
; #pragma unroll
;                 for (int j = 0; j < 8; ++j) __builtin_nontemporal_store(vr[q][j] * rs[q] * ggv[j] + bbv[j], xr + 512 * q + 64 * j); }
	v_add_f32_e32 v16, v0, v2
	v_add_f32_e32 v16, v16, v4
	v_add_f32_e32 v16, v16, v6
	v_add_f32_e32 v16, v16, v8
	v_add_f32_e32 v16, v16, v10
	v_add_f32_e32 v16, v16, v12
	v_add_f32_e32 v16, v16, v14
	v_mul_f32_e32 v16, 0x3a000000, v16
	v_add_f32_e32 v17, v1, v3
	v_add_f32_e32 v17, v17, v5
	v_add_f32_e32 v17, v17, v7
	v_add_f32_e32 v17, v17, v9
	v_add_f32_e32 v17, v17, v11
	v_add_f32_e32 v17, v17, v13
	v_add_f32_e32 v17, v17, v15
	v_fma_f32 v18, v0, s9, -v16
	v_mul_f32_e32 v18, v18, v18
	v_fmac_f32_e32 v17, 0x43800000, v18
	v_fma_f32 v18, v2, s9, -v16
	v_mul_f32_e32 v18, v18, v18
	v_fmac_f32_e32 v17, 0x43800000, v18
	v_fma_f32 v18, v4, s9, -v16
	v_mul_f32_e32 v18, v18, v18
	v_fmac_f32_e32 v17, 0x43800000, v18
	v_fma_f32 v18, v6, s9, -v16
	v_mul_f32_e32 v18, v18, v18
	v_fmac_f32_e32 v17, 0x43800000, v18
	v_fma_f32 v18, v8, s9, -v16
	v_mul_f32_e32 v18, v18, v18
	v_fmac_f32_e32 v17, 0x43800000, v18
	v_fma_f32 v18, v10, s9, -v16
	v_mul_f32_e32 v18, v18, v18
	v_fmac_f32_e32 v17, 0x43800000, v18
	v_fma_f32 v18, v12, s9, -v16
	v_mul_f32_e32 v18, v18, v18
	v_fmac_f32_e32 v17, 0x43800000, v18
	v_fma_f32 v18, v14, s9, -v16
	v_mul_f32_e32 v18, v18, v18
	v_fmac_f32_e32 v17, 0x43800000, v18
	v_fmamk_f32 v17, v17, 0x3a000000, v157
	v_mul_f32_e32 v18, 0x4f800000, v17
	v_cmp_gt_f32_e32 vcc, s3, v17
	s_nop 1
	v_cndmask_b32_e32 v214, v17, v18, vcc
	v_sqrt_f32_e32 v215, v214
	s_nop 1
	v_add_u32_e32 v216, -1, v215
	v_fma_f32 v217, -v216, v215, v214
	v_cmp_ge_f32_e64 s[14:15], 0, v217
	v_add_u32_e32 v217, 1, v215
	v_fma_f32 v218, -v217, v215, v214
	s_nop 0
	v_cndmask_b32_e64 v216, v215, v216, s[14:15]
	v_cmp_lt_f32_e64 s[14:15], 0, v218
	s_nop 1
	v_cndmask_b32_e64 v216, v216, v217, s[14:15]
	v_mul_f32_e32 v217, 0x37800000, v216
	v_cndmask_b32_e32 v216, v216, v217, vcc
	v_cmp_class_f32_e32 vcc, v214, v158
	s_nop 1
	v_cndmask_b32_e32 v214, v216, v214, vcc
	v_div_scale_f32 v215, s[14:15], v214, v214, 1.0
	v_rcp_f32_e32 v216, v215
	s_nop 1
	v_fma_f32 v217, -v215, v216, 1.0
	v_fmac_f32_e32 v216, v217, v216
	v_div_scale_f32 v217, vcc, 1.0, v214, 1.0
	v_mul_f32_e32 v218, v217, v216
	v_fma_f32 v219, -v215, v218, v217
	v_fmac_f32_e32 v218, v219, v216
	v_fma_f32 v217, -v215, v218, v217
	s_nop 1
	v_div_fmas_f32 v215, v217, v216, v218
	v_div_fixup_f32 v214, v215, v214, 1.0
	s_mov_b64 s[12:13], 0x20000
	v_lshl_add_u64 v[160:161], v[152:153], 0, s[12:13]
	v_pk_add_f32 v[124:125], v[124:125], v[16:17] op_sel_hi:[1,0] neg_lo:[0,1] neg_hi:[0,1]
	v_pk_mul_f32 v[124:125], v[124:125], v[214:215] op_sel_hi:[1,0]
	v_pk_fma_f32 v[124:125], v[224:225], v[124:125], v[136:137]
	v_pk_add_f32 v[126:127], v[126:127], v[16:17] op_sel_hi:[1,0] neg_lo:[0,1] neg_hi:[0,1]
	v_pk_mul_f32 v[126:127], v[126:127], v[214:215] op_sel_hi:[1,0]
	v_pk_fma_f32 v[126:127], v[226:227], v[126:127], v[138:139]
	global_store_dwordx4 v[160:161], v[124:127], off
	v_pk_add_f32 v[120:121], v[120:121], v[16:17] op_sel_hi:[1,0] neg_lo:[0,1] neg_hi:[0,1]
	v_pk_mul_f32 v[120:121], v[120:121], v[214:215] op_sel_hi:[1,0]
	v_pk_fma_f32 v[120:121], v[228:229], v[120:121], v[140:141]
	v_pk_add_f32 v[122:123], v[122:123], v[16:17] op_sel_hi:[1,0] neg_lo:[0,1] neg_hi:[0,1]
	v_pk_mul_f32 v[122:123], v[122:123], v[214:215] op_sel_hi:[1,0]
	v_pk_fma_f32 v[122:123], v[230:231], v[122:123], v[142:143]
	global_store_dwordx4 v[160:161], v[120:123], off offset:64
	v_pk_add_f32 v[52:53], v[52:53], v[16:17] op_sel_hi:[1,0] neg_lo:[0,1] neg_hi:[0,1]
	v_pk_mul_f32 v[52:53], v[52:53], v[214:215] op_sel_hi:[1,0]
	v_pk_fma_f32 v[52:53], v[232:233], v[52:53], v[144:145]
	v_pk_add_f32 v[54:55], v[54:55], v[16:17] op_sel_hi:[1,0] neg_lo:[0,1] neg_hi:[0,1]
	v_pk_mul_f32 v[54:55], v[54:55], v[214:215] op_sel_hi:[1,0]
	v_pk_fma_f32 v[54:55], v[234:235], v[54:55], v[146:147]
	global_store_dwordx4 v[160:161], v[52:55], off offset:512
	v_pk_add_f32 v[48:49], v[48:49], v[16:17] op_sel_hi:[1,0] neg_lo:[0,1] neg_hi:[0,1]
	v_pk_mul_f32 v[48:49], v[48:49], v[214:215] op_sel_hi:[1,0]
	v_pk_fma_f32 v[48:49], v[236:237], v[48:49], v[148:149]
	v_pk_add_f32 v[50:51], v[50:51], v[16:17] op_sel_hi:[1,0] neg_lo:[0,1] neg_hi:[0,1]
	v_pk_mul_f32 v[50:51], v[50:51], v[214:215] op_sel_hi:[1,0]
	v_pk_fma_f32 v[50:51], v[238:239], v[50:51], v[150:151]
	global_store_dwordx4 v[160:161], v[48:51], off offset:576
	v_add_u32_e32 v159, 0xc00, v156
	global_load_dwordx4 v[0:3], v159, s[10:11]
	global_load_dwordx4 v[4:7], v159, s[10:11] offset:16
	global_load_dwordx4 v[8:11], v159, s[10:11] offset:32
	global_load_dwordx4 v[12:15], v159, s[10:11] offset:48
	s_waitcnt vmcnt(8)
; __global__ void __launch_bounds__(512, 2) fwd_kernel(Args a) {
;     ...
;             for (int q = 0; q < 4; ++q) { float s_ = 0.f;
; #pragma unroll
;                 for (int j = 0; j < 8; ++j) s_ += (vr[q][j][0] + vr[q][j][1]) + (vr[q][j][2] + vr[q][j][3]);
;                 sm[q] = wave_sum(s_) * (1.0f / DMODEL); }
; #pragma unroll
;             for (int q = 0; q < 4; ++q) { float s2 = 0.f;
; #pragma unroll
;                 for (int j = 0; j < 8; ++j) { vr[q][j] = vr[q][j] - sm[q]; s2 += (vr[q][j][0] * vr[q][j][0] + vr[q][j][1] * vr[q][j][1]) + (vr[q][j][2] * vr[q][j][2] + vr[q][j][3] * vr[q][j][3]); }
;                 qq[q] = wave_sum(s2); rs[q] = 1.0f / sqrtf(qq[q] * (1.0f / DMODEL) + LN_EPS); }
; #pragma unroll
;             for (int q = 0; q < 4; ++q)
; #pragma unroll
;                 for (int j = 0; j < 8; ++j) __builtin_nontemporal_store(vr[q][j] * rs[q] * ggv[j] + bbv[j], xr + 512 * q + 64 * j); }
	v_add_f32_e32 v16, v198, v200
	v_add_f32_e32 v16, v16, v202
	v_add_f32_e32 v16, v16, v204
	v_add_f32_e32 v16, v16, v206
	v_add_f32_e32 v16, v16, v208
	v_add_f32_e32 v16, v16, v210
	v_add_f32_e32 v16, v16, v212
	v_mul_f32_e32 v16, 0x3a000000, v16
	v_add_f32_e32 v17, v199, v201
	v_add_f32_e32 v17, v17, v203
	v_add_f32_e32 v17, v17, v205
	v_add_f32_e32 v17, v17, v207
	v_add_f32_e32 v17, v17, v209
	v_add_f32_e32 v17, v17, v211
	v_add_f32_e32 v17, v17, v213
	v_fma_f32 v18, v198, s9, -v16
	v_mul_f32_e32 v18, v18, v18
	v_fmac_f32_e32 v17, 0x43800000, v18
	v_fma_f32 v18, v200, s9, -v16
	v_mul_f32_e32 v18, v18, v18
	v_fmac_f32_e32 v17, 0x43800000, v18
	v_fma_f32 v18, v202, s9, -v16
	v_mul_f32_e32 v18, v18, v18
	v_fmac_f32_e32 v17, 0x43800000, v18
	v_fma_f32 v18, v204, s9, -v16
	v_mul_f32_e32 v18, v18, v18
	v_fmac_f32_e32 v17, 0x43800000, v18
	v_fma_f32 v18, v206, s9, -v16
	v_mul_f32_e32 v18, v18, v18
	v_fmac_f32_e32 v17, 0x43800000, v18
	v_fma_f32 v18, v208, s9, -v16
	v_mul_f32_e32 v18, v18, v18
	v_fmac_f32_e32 v17, 0x43800000, v18
	v_fma_f32 v18, v210, s9, -v16
	v_mul_f32_e32 v18, v18, v18
	v_fmac_f32_e32 v17, 0x43800000, v18
	v_fma_f32 v18, v212, s9, -v16
	v_mul_f32_e32 v18, v18, v18
	v_fmac_f32_e32 v17, 0x43800000, v18
	v_fmamk_f32 v17, v17, 0x3a000000, v157
	v_mul_f32_e32 v18, 0x4f800000, v17
	v_cmp_gt_f32_e32 vcc, s3, v17
	s_nop 1
	v_cndmask_b32_e32 v214, v17, v18, vcc
	v_sqrt_f32_e32 v215, v214
	s_nop 1
	v_add_u32_e32 v216, -1, v215
	v_fma_f32 v217, -v216, v215, v214
	v_cmp_ge_f32_e64 s[14:15], 0, v217
	v_add_u32_e32 v217, 1, v215
	v_fma_f32 v218, -v217, v215, v214
	s_nop 0
	v_cndmask_b32_e64 v216, v215, v216, s[14:15]
	v_cmp_lt_f32_e64 s[14:15], 0, v218
	s_nop 1
	v_cndmask_b32_e64 v216, v216, v217, s[14:15]
	v_mul_f32_e32 v217, 0x37800000, v216
	v_cndmask_b32_e32 v216, v216, v217, vcc
	v_cmp_class_f32_e32 vcc, v214, v158
	s_nop 1
	v_cndmask_b32_e32 v214, v216, v214, vcc
	v_div_scale_f32 v215, s[14:15], v214, v214, 1.0
	v_rcp_f32_e32 v216, v215
	s_nop 1
	v_fma_f32 v217, -v215, v216, 1.0
	v_fmac_f32_e32 v216, v217, v216
	v_div_scale_f32 v217, vcc, 1.0, v214, 1.0
	v_mul_f32_e32 v218, v217, v216
	v_fma_f32 v219, -v215, v218, v217
	v_fmac_f32_e32 v218, v219, v216
	v_fma_f32 v217, -v215, v218, v217
	s_nop 1
	v_div_fmas_f32 v215, v217, v216, v218
	v_div_fixup_f32 v214, v215, v214, 1.0
	s_mov_b64 s[12:13], 0x40000
	v_lshl_add_u64 v[160:161], v[152:153], 0, s[12:13]
	v_pk_add_f32 v[116:117], v[116:117], v[16:17] op_sel_hi:[1,0] neg_lo:[0,1] neg_hi:[0,1]
	v_pk_mul_f32 v[116:117], v[116:117], v[214:215] op_sel_hi:[1,0]
	v_pk_fma_f32 v[116:117], v[224:225], v[116:117], v[136:137]
	v_pk_add_f32 v[118:119], v[118:119], v[16:17] op_sel_hi:[1,0] neg_lo:[0,1] neg_hi:[0,1]
	v_pk_mul_f32 v[118:119], v[118:119], v[214:215] op_sel_hi:[1,0]
	v_pk_fma_f32 v[118:119], v[226:227], v[118:119], v[138:139]
	global_store_dwordx4 v[160:161], v[116:119], off
	v_pk_add_f32 v[112:113], v[112:113], v[16:17] op_sel_hi:[1,0] neg_lo:[0,1] neg_hi:[0,1]
	v_pk_mul_f32 v[112:113], v[112:113], v[214:215] op_sel_hi:[1,0]
	v_pk_fma_f32 v[112:113], v[228:229], v[112:113], v[140:141]
	v_pk_add_f32 v[114:115], v[114:115], v[16:17] op_sel_hi:[1,0] neg_lo:[0,1] neg_hi:[0,1]
	v_pk_mul_f32 v[114:115], v[114:115], v[214:215] op_sel_hi:[1,0]
	v_pk_fma_f32 v[114:115], v[230:231], v[114:115], v[142:143]
	global_store_dwordx4 v[160:161], v[112:115], off offset:64
	v_pk_add_f32 v[44:45], v[44:45], v[16:17] op_sel_hi:[1,0] neg_lo:[0,1] neg_hi:[0,1]
	v_pk_mul_f32 v[44:45], v[44:45], v[214:215] op_sel_hi:[1,0]
	v_pk_fma_f32 v[44:45], v[232:233], v[44:45], v[144:145]
	v_pk_add_f32 v[46:47], v[46:47], v[16:17] op_sel_hi:[1,0] neg_lo:[0,1] neg_hi:[0,1]
	v_pk_mul_f32 v[46:47], v[46:47], v[214:215] op_sel_hi:[1,0]
	v_pk_fma_f32 v[46:47], v[234:235], v[46:47], v[146:147]
	global_store_dwordx4 v[160:161], v[44:47], off offset:512
	v_pk_add_f32 v[40:41], v[40:41], v[16:17] op_sel_hi:[1,0] neg_lo:[0,1] neg_hi:[0,1]
	v_pk_mul_f32 v[40:41], v[40:41], v[214:215] op_sel_hi:[1,0]
	v_pk_fma_f32 v[40:41], v[236:237], v[40:41], v[148:149]
	v_pk_add_f32 v[42:43], v[42:43], v[16:17] op_sel_hi:[1,0] neg_lo:[0,1] neg_hi:[0,1]
	v_pk_mul_f32 v[42:43], v[42:43], v[214:215] op_sel_hi:[1,0]
	v_pk_fma_f32 v[42:43], v[238:239], v[42:43], v[150:151]
	global_store_dwordx4 v[160:161], v[40:43], off offset:576
	v_add_u32_e32 v159, 0x2000, v156
	global_load_dwordx4 v[198:201], v159, s[10:11]
	global_load_dwordx4 v[202:205], v159, s[10:11] offset:16
	global_load_dwordx4 v[206:209], v159, s[10:11] offset:32
	global_load_dwordx4 v[210:213], v159, s[10:11] offset:48
	s_waitcnt vmcnt(8)
; __global__ void __launch_bounds__(512, 2) fwd_kernel(Args a) {
;     ...
;             for (int q = 0; q < 4; ++q) { float s_ = 0.f;
; #pragma unroll
;                 for (int j = 0; j < 8; ++j) s_ += (vr[q][j][0] + vr[q][j][1]) + (vr[q][j][2] + vr[q][j][3]);
;                 sm[q] = wave_sum(s_) * (1.0f / DMODEL); }
; #pragma unroll
;             for (int q = 0; q < 4; ++q) { float s2 = 0.f;
; #pragma unroll
;                 for (int j = 0; j < 8; ++j) { vr[q][j] = vr[q][j] - sm[q]; s2 += (vr[q][j][0] * vr[q][j][0] + vr[q][j][1] * vr[q][j][1]) + (vr[q][j][2] * vr[q][j][2] + vr[q][j][3] * vr[q][j][3]); }
;                 qq[q] = wave_sum(s2); rs[q] = 1.0f / sqrtf(qq[q] * (1.0f / DMODEL) + LN_EPS); }
; #pragma unroll
;             for (int q = 0; q < 4; ++q)
; #pragma unroll
;                 for (int j = 0; j < 8; ++j) __builtin_nontemporal_store(vr[q][j] * rs[q] * ggv[j] + bbv[j], xr + 512 * q + 64 * j); }
	v_add_f32_e32 v16, v0, v2
	v_add_f32_e32 v16, v16, v4
	v_add_f32_e32 v16, v16, v6
	v_add_f32_e32 v16, v16, v8
	v_add_f32_e32 v16, v16, v10
	v_add_f32_e32 v16, v16, v12
	v_add_f32_e32 v16, v16, v14
	v_mul_f32_e32 v16, 0x3a000000, v16
	v_add_f32_e32 v17, v1, v3
	v_add_f32_e32 v17, v17, v5
	v_add_f32_e32 v17, v17, v7
	v_add_f32_e32 v17, v17, v9
	v_add_f32_e32 v17, v17, v11
	v_add_f32_e32 v17, v17, v13
	v_add_f32_e32 v17, v17, v15
	v_fma_f32 v18, v0, s9, -v16
	v_mul_f32_e32 v18, v18, v18
	v_fmac_f32_e32 v17, 0x43800000, v18
	v_fma_f32 v18, v2, s9, -v16
	v_mul_f32_e32 v18, v18, v18
	v_fmac_f32_e32 v17, 0x43800000, v18
	v_fma_f32 v18, v4, s9, -v16
	v_mul_f32_e32 v18, v18, v18
	v_fmac_f32_e32 v17, 0x43800000, v18
	v_fma_f32 v18, v6, s9, -v16
	v_mul_f32_e32 v18, v18, v18
	v_fmac_f32_e32 v17, 0x43800000, v18
	v_fma_f32 v18, v8, s9, -v16
	v_mul_f32_e32 v18, v18, v18
	v_fmac_f32_e32 v17, 0x43800000, v18
	v_fma_f32 v18, v10, s9, -v16
	v_mul_f32_e32 v18, v18, v18
	v_fmac_f32_e32 v17, 0x43800000, v18
	v_fma_f32 v18, v12, s9, -v16
	v_mul_f32_e32 v18, v18, v18
	v_fmac_f32_e32 v17, 0x43800000, v18
	v_fma_f32 v18, v14, s9, -v16
	v_mul_f32_e32 v18, v18, v18
	v_fmac_f32_e32 v17, 0x43800000, v18
	v_fmamk_f32 v17, v17, 0x3a000000, v157
	v_mul_f32_e32 v18, 0x4f800000, v17
	v_cmp_gt_f32_e32 vcc, s3, v17
	s_nop 1
	v_cndmask_b32_e32 v214, v17, v18, vcc
	v_sqrt_f32_e32 v215, v214
	s_nop 1
	v_add_u32_e32 v216, -1, v215
	v_fma_f32 v217, -v216, v215, v214
	v_cmp_ge_f32_e64 s[14:15], 0, v217
	v_add_u32_e32 v217, 1, v215
	v_fma_f32 v218, -v217, v215, v214
	s_nop 0
	v_cndmask_b32_e64 v216, v215, v216, s[14:15]
	v_cmp_lt_f32_e64 s[14:15], 0, v218
	s_nop 1
	v_cndmask_b32_e64 v216, v216, v217, s[14:15]
	v_mul_f32_e32 v217, 0x37800000, v216
	v_cndmask_b32_e32 v216, v216, v217, vcc
	v_cmp_class_f32_e32 vcc, v214, v158
	s_nop 1
	v_cndmask_b32_e32 v214, v216, v214, vcc
	v_div_scale_f32 v215, s[14:15], v214, v214, 1.0
	v_rcp_f32_e32 v216, v215
	s_nop 1
	v_fma_f32 v217, -v215, v216, 1.0
	v_fmac_f32_e32 v216, v217, v216
	v_div_scale_f32 v217, vcc, 1.0, v214, 1.0
	v_mul_f32_e32 v218, v217, v216
	v_fma_f32 v219, -v215, v218, v217
	v_fmac_f32_e32 v218, v219, v216
	v_fma_f32 v217, -v215, v218, v217
	s_nop 1
	v_div_fmas_f32 v215, v217, v216, v218
	v_div_fixup_f32 v214, v215, v214, 1.0
	s_mov_b64 s[12:13], 0x60000
	v_lshl_add_u64 v[160:161], v[152:153], 0, s[12:13]
	v_pk_add_f32 v[108:109], v[108:109], v[16:17] op_sel_hi:[1,0] neg_lo:[0,1] neg_hi:[0,1]
	v_pk_mul_f32 v[108:109], v[108:109], v[214:215] op_sel_hi:[1,0]
	v_pk_fma_f32 v[108:109], v[224:225], v[108:109], v[136:137]
	v_pk_add_f32 v[110:111], v[110:111], v[16:17] op_sel_hi:[1,0] neg_lo:[0,1] neg_hi:[0,1]
	v_pk_mul_f32 v[110:111], v[110:111], v[214:215] op_sel_hi:[1,0]
	v_pk_fma_f32 v[110:111], v[226:227], v[110:111], v[138:139]
	global_store_dwordx4 v[160:161], v[108:111], off
	v_pk_add_f32 v[104:105], v[104:105], v[16:17] op_sel_hi:[1,0] neg_lo:[0,1] neg_hi:[0,1]
	v_pk_mul_f32 v[104:105], v[104:105], v[214:215] op_sel_hi:[1,0]
	v_pk_fma_f32 v[104:105], v[228:229], v[104:105], v[140:141]
	v_pk_add_f32 v[106:107], v[106:107], v[16:17] op_sel_hi:[1,0] neg_lo:[0,1] neg_hi:[0,1]
	v_pk_mul_f32 v[106:107], v[106:107], v[214:215] op_sel_hi:[1,0]
	v_pk_fma_f32 v[106:107], v[230:231], v[106:107], v[142:143]
	global_store_dwordx4 v[160:161], v[104:107], off offset:64
	v_pk_add_f32 v[36:37], v[36:37], v[16:17] op_sel_hi:[1,0] neg_lo:[0,1] neg_hi:[0,1]
	v_pk_mul_f32 v[36:37], v[36:37], v[214:215] op_sel_hi:[1,0]
	v_pk_fma_f32 v[36:37], v[232:233], v[36:37], v[144:145]
	v_pk_add_f32 v[38:39], v[38:39], v[16:17] op_sel_hi:[1,0] neg_lo:[0,1] neg_hi:[0,1]
	v_pk_mul_f32 v[38:39], v[38:39], v[214:215] op_sel_hi:[1,0]
	v_pk_fma_f32 v[38:39], v[234:235], v[38:39], v[146:147]
	global_store_dwordx4 v[160:161], v[36:39], off offset:512
	v_pk_add_f32 v[32:33], v[32:33], v[16:17] op_sel_hi:[1,0] neg_lo:[0,1] neg_hi:[0,1]
	v_pk_mul_f32 v[32:33], v[32:33], v[214:215] op_sel_hi:[1,0]
	v_pk_fma_f32 v[32:33], v[236:237], v[32:33], v[148:149]
	v_pk_add_f32 v[34:35], v[34:35], v[16:17] op_sel_hi:[1,0] neg_lo:[0,1] neg_hi:[0,1]
	v_pk_mul_f32 v[34:35], v[34:35], v[214:215] op_sel_hi:[1,0]
	v_pk_fma_f32 v[34:35], v[238:239], v[34:35], v[150:151]
	global_store_dwordx4 v[160:161], v[32:35], off offset:576
	v_add_u32_e32 v159, 0x2400, v156
	global_load_dwordx4 v[0:3], v159, s[10:11]
	global_load_dwordx4 v[4:7], v159, s[10:11] offset:16
	global_load_dwordx4 v[8:11], v159, s[10:11] offset:32
	global_load_dwordx4 v[12:15], v159, s[10:11] offset:48
	s_waitcnt vmcnt(8)
; __global__ void __launch_bounds__(512, 2) fwd_kernel(Args a) {
;     ...
;             for (int q = 0; q < 4; ++q) { float s_ = 0.f;
; #pragma unroll
;                 for (int j = 0; j < 8; ++j) s_ += (vr[q][j][0] + vr[q][j][1]) + (vr[q][j][2] + vr[q][j][3]);
;                 sm[q] = wave_sum(s_) * (1.0f / DMODEL); }
; #pragma unroll
;             for (int q = 0; q < 4; ++q) { float s2 = 0.f;
; #pragma unroll
;                 for (int j = 0; j < 8; ++j) { vr[q][j] = vr[q][j] - sm[q]; s2 += (vr[q][j][0] * vr[q][j][0] + vr[q][j][1] * vr[q][j][1]) + (vr[q][j][2] * vr[q][j][2] + vr[q][j][3] * vr[q][j][3]); }
;                 qq[q] = wave_sum(s2); rs[q] = 1.0f / sqrtf(qq[q] * (1.0f / DMODEL) + LN_EPS); }
; #pragma unroll
;             for (int q = 0; q < 4; ++q)
; #pragma unroll
;                 for (int j = 0; j < 8; ++j) __builtin_nontemporal_store(vr[q][j] * rs[q] * ggv[j] + bbv[j], xr + 512 * q + 64 * j); }
	v_add_f32_e32 v16, v198, v200
	v_add_f32_e32 v16, v16, v202
	v_add_f32_e32 v16, v16, v204
	v_add_f32_e32 v16, v16, v206
	v_add_f32_e32 v16, v16, v208
	v_add_f32_e32 v16, v16, v210
	v_add_f32_e32 v16, v16, v212
	v_mul_f32_e32 v16, 0x3a000000, v16
	v_add_f32_e32 v17, v199, v201
	v_add_f32_e32 v17, v17, v203
	v_add_f32_e32 v17, v17, v205
	v_add_f32_e32 v17, v17, v207
	v_add_f32_e32 v17, v17, v209
	v_add_f32_e32 v17, v17, v211
	v_add_f32_e32 v17, v17, v213
	v_fma_f32 v18, v198, s9, -v16
	v_mul_f32_e32 v18, v18, v18
	v_fmac_f32_e32 v17, 0x43800000, v18
	v_fma_f32 v18, v200, s9, -v16
	v_mul_f32_e32 v18, v18, v18
	v_fmac_f32_e32 v17, 0x43800000, v18
	v_fma_f32 v18, v202, s9, -v16
	v_mul_f32_e32 v18, v18, v18
	v_fmac_f32_e32 v17, 0x43800000, v18
	v_fma_f32 v18, v204, s9, -v16
	v_mul_f32_e32 v18, v18, v18
	v_fmac_f32_e32 v17, 0x43800000, v18
	v_fma_f32 v18, v206, s9, -v16
	v_mul_f32_e32 v18, v18, v18
	v_fmac_f32_e32 v17, 0x43800000, v18
	v_fma_f32 v18, v208, s9, -v16
	v_mul_f32_e32 v18, v18, v18
	v_fmac_f32_e32 v17, 0x43800000, v18
	v_fma_f32 v18, v210, s9, -v16
	v_mul_f32_e32 v18, v18, v18
	v_fmac_f32_e32 v17, 0x43800000, v18
	v_fma_f32 v18, v212, s9, -v16
	v_mul_f32_e32 v18, v18, v18
	v_fmac_f32_e32 v17, 0x43800000, v18
	v_fmamk_f32 v17, v17, 0x3a000000, v157
	v_mul_f32_e32 v18, 0x4f800000, v17
	v_cmp_gt_f32_e32 vcc, s3, v17
	s_nop 1
	v_cndmask_b32_e32 v214, v17, v18, vcc
	v_sqrt_f32_e32 v215, v214
	s_nop 1
	v_add_u32_e32 v216, -1, v215
	v_fma_f32 v217, -v216, v215, v214
	v_cmp_ge_f32_e64 s[14:15], 0, v217
	v_add_u32_e32 v217, 1, v215
	v_fma_f32 v218, -v217, v215, v214
	s_nop 0
	v_cndmask_b32_e64 v216, v215, v216, s[14:15]
	v_cmp_lt_f32_e64 s[14:15], 0, v218
	s_nop 1
	v_cndmask_b32_e64 v216, v216, v217, s[14:15]
	v_mul_f32_e32 v217, 0x37800000, v216
	v_cndmask_b32_e32 v216, v216, v217, vcc
	v_cmp_class_f32_e32 vcc, v214, v158
	s_nop 1
	v_cndmask_b32_e32 v214, v216, v214, vcc
	v_div_scale_f32 v215, s[14:15], v214, v214, 1.0
	v_rcp_f32_e32 v216, v215
	s_nop 1
	v_fma_f32 v217, -v215, v216, 1.0
	v_fmac_f32_e32 v216, v217, v216
	v_div_scale_f32 v217, vcc, 1.0, v214, 1.0
	v_mul_f32_e32 v218, v217, v216
	v_fma_f32 v219, -v215, v218, v217
	v_fmac_f32_e32 v218, v219, v216
	v_fma_f32 v217, -v215, v218, v217
	s_nop 1
	v_div_fmas_f32 v215, v217, v216, v218
	v_div_fixup_f32 v214, v215, v214, 1.0
	s_mov_b64 s[12:13], 0x100000
	v_lshl_add_u64 v[160:161], v[152:153], 0, s[12:13]
	v_pk_add_f32 v[100:101], v[100:101], v[16:17] op_sel_hi:[1,0] neg_lo:[0,1] neg_hi:[0,1]
	v_pk_mul_f32 v[100:101], v[100:101], v[214:215] op_sel_hi:[1,0]
	v_pk_fma_f32 v[100:101], v[224:225], v[100:101], v[136:137]
	v_pk_add_f32 v[102:103], v[102:103], v[16:17] op_sel_hi:[1,0] neg_lo:[0,1] neg_hi:[0,1]
	v_pk_mul_f32 v[102:103], v[102:103], v[214:215] op_sel_hi:[1,0]
	v_pk_fma_f32 v[102:103], v[226:227], v[102:103], v[138:139]
	global_store_dwordx4 v[160:161], v[100:103], off
	v_pk_add_f32 v[96:97], v[96:97], v[16:17] op_sel_hi:[1,0] neg_lo:[0,1] neg_hi:[0,1]
	v_pk_mul_f32 v[96:97], v[96:97], v[214:215] op_sel_hi:[1,0]
	v_pk_fma_f32 v[96:97], v[228:229], v[96:97], v[140:141]
	v_pk_add_f32 v[98:99], v[98:99], v[16:17] op_sel_hi:[1,0] neg_lo:[0,1] neg_hi:[0,1]
	v_pk_mul_f32 v[98:99], v[98:99], v[214:215] op_sel_hi:[1,0]
	v_pk_fma_f32 v[98:99], v[230:231], v[98:99], v[142:143]
	global_store_dwordx4 v[160:161], v[96:99], off offset:64
	v_pk_add_f32 v[28:29], v[28:29], v[16:17] op_sel_hi:[1,0] neg_lo:[0,1] neg_hi:[0,1]
	v_pk_mul_f32 v[28:29], v[28:29], v[214:215] op_sel_hi:[1,0]
	v_pk_fma_f32 v[28:29], v[232:233], v[28:29], v[144:145]
	v_pk_add_f32 v[30:31], v[30:31], v[16:17] op_sel_hi:[1,0] neg_lo:[0,1] neg_hi:[0,1]
	v_pk_mul_f32 v[30:31], v[30:31], v[214:215] op_sel_hi:[1,0]
	v_pk_fma_f32 v[30:31], v[234:235], v[30:31], v[146:147]
	global_store_dwordx4 v[160:161], v[28:31], off offset:512
	v_pk_add_f32 v[24:25], v[24:25], v[16:17] op_sel_hi:[1,0] neg_lo:[0,1] neg_hi:[0,1]
	v_pk_mul_f32 v[24:25], v[24:25], v[214:215] op_sel_hi:[1,0]
	v_pk_fma_f32 v[24:25], v[236:237], v[24:25], v[148:149]
	v_pk_add_f32 v[26:27], v[26:27], v[16:17] op_sel_hi:[1,0] neg_lo:[0,1] neg_hi:[0,1]
	v_pk_mul_f32 v[26:27], v[26:27], v[214:215] op_sel_hi:[1,0]
	v_pk_fma_f32 v[26:27], v[238:239], v[26:27], v[150:151]
	global_store_dwordx4 v[160:161], v[24:27], off offset:576
	v_add_u32_e32 v159, 0x2800, v156
	global_load_dwordx4 v[198:201], v159, s[10:11]
	global_load_dwordx4 v[202:205], v159, s[10:11] offset:16
	global_load_dwordx4 v[206:209], v159, s[10:11] offset:32
	global_load_dwordx4 v[210:213], v159, s[10:11] offset:48
	s_waitcnt vmcnt(8)
; __global__ void __launch_bounds__(512, 2) fwd_kernel(Args a) {
;     ...
;             for (int q = 0; q < 4; ++q) { float s_ = 0.f;
; #pragma unroll
;                 for (int j = 0; j < 8; ++j) s_ += (vr[q][j][0] + vr[q][j][1]) + (vr[q][j][2] + vr[q][j][3]);
;                 sm[q] = wave_sum(s_) * (1.0f / DMODEL); }
; #pragma unroll
;             for (int q = 0; q < 4; ++q) { float s2 = 0.f;
; #pragma unroll
;                 for (int j = 0; j < 8; ++j) { vr[q][j] = vr[q][j] - sm[q]; s2 += (vr[q][j][0] * vr[q][j][0] + vr[q][j][1] * vr[q][j][1]) + (vr[q][j][2] * vr[q][j][2] + vr[q][j][3] * vr[q][j][3]); }
;                 qq[q] = wave_sum(s2); rs[q] = 1.0f / sqrtf(qq[q] * (1.0f / DMODEL) + LN_EPS); }
; #pragma unroll
;             for (int q = 0; q < 4; ++q)
; #pragma unroll
;                 for (int j = 0; j < 8; ++j) __builtin_nontemporal_store(vr[q][j] * rs[q] * ggv[j] + bbv[j], xr + 512 * q + 64 * j); }
	v_add_f32_e32 v16, v0, v2
	v_add_f32_e32 v16, v16, v4
	v_add_f32_e32 v16, v16, v6
	v_add_f32_e32 v16, v16, v8
	v_add_f32_e32 v16, v16, v10
	v_add_f32_e32 v16, v16, v12
	v_add_f32_e32 v16, v16, v14
	v_mul_f32_e32 v16, 0x3a000000, v16
	v_add_f32_e32 v17, v1, v3
	v_add_f32_e32 v17, v17, v5
	v_add_f32_e32 v17, v17, v7
	v_add_f32_e32 v17, v17, v9
	v_add_f32_e32 v17, v17, v11
	v_add_f32_e32 v17, v17, v13
	v_add_f32_e32 v17, v17, v15
	v_fma_f32 v18, v0, s9, -v16
	v_mul_f32_e32 v18, v18, v18
	v_fmac_f32_e32 v17, 0x43800000, v18
	v_fma_f32 v18, v2, s9, -v16
	v_mul_f32_e32 v18, v18, v18
	v_fmac_f32_e32 v17, 0x43800000, v18
	v_fma_f32 v18, v4, s9, -v16
	v_mul_f32_e32 v18, v18, v18
	v_fmac_f32_e32 v17, 0x43800000, v18
	v_fma_f32 v18, v6, s9, -v16
	v_mul_f32_e32 v18, v18, v18
	v_fmac_f32_e32 v17, 0x43800000, v18
	v_fma_f32 v18, v8, s9, -v16
	v_mul_f32_e32 v18, v18, v18
	v_fmac_f32_e32 v17, 0x43800000, v18
	v_fma_f32 v18, v10, s9, -v16
	v_mul_f32_e32 v18, v18, v18
	v_fmac_f32_e32 v17, 0x43800000, v18
	v_fma_f32 v18, v12, s9, -v16
	v_mul_f32_e32 v18, v18, v18
	v_fmac_f32_e32 v17, 0x43800000, v18
	v_fma_f32 v18, v14, s9, -v16
	v_mul_f32_e32 v18, v18, v18
	v_fmac_f32_e32 v17, 0x43800000, v18
	v_fmamk_f32 v17, v17, 0x3a000000, v157
	v_mul_f32_e32 v18, 0x4f800000, v17
	v_cmp_gt_f32_e32 vcc, s3, v17
	s_nop 1
	v_cndmask_b32_e32 v214, v17, v18, vcc
	v_sqrt_f32_e32 v215, v214
	s_nop 1
	v_add_u32_e32 v216, -1, v215
	v_fma_f32 v217, -v216, v215, v214
	v_cmp_ge_f32_e64 s[14:15], 0, v217
	v_add_u32_e32 v217, 1, v215
	v_fma_f32 v218, -v217, v215, v214
	s_nop 0
	v_cndmask_b32_e64 v216, v215, v216, s[14:15]
	v_cmp_lt_f32_e64 s[14:15], 0, v218
	s_nop 1
	v_cndmask_b32_e64 v216, v216, v217, s[14:15]
	v_mul_f32_e32 v217, 0x37800000, v216
	v_cndmask_b32_e32 v216, v216, v217, vcc
	v_cmp_class_f32_e32 vcc, v214, v158
	s_nop 1
	v_cndmask_b32_e32 v214, v216, v214, vcc
	v_div_scale_f32 v215, s[14:15], v214, v214, 1.0
	v_rcp_f32_e32 v216, v215
	s_nop 1
	v_fma_f32 v217, -v215, v216, 1.0
	v_fmac_f32_e32 v216, v217, v216
	v_div_scale_f32 v217, vcc, 1.0, v214, 1.0
	v_mul_f32_e32 v218, v217, v216
	v_fma_f32 v219, -v215, v218, v217
	v_fmac_f32_e32 v218, v219, v216
	v_fma_f32 v217, -v215, v218, v217
	s_nop 1
	v_div_fmas_f32 v215, v217, v216, v218
	v_div_fixup_f32 v214, v215, v214, 1.0
	s_mov_b64 s[12:13], 0x120000
	v_lshl_add_u64 v[160:161], v[152:153], 0, s[12:13]
	v_pk_add_f32 v[92:93], v[92:93], v[16:17] op_sel_hi:[1,0] neg_lo:[0,1] neg_hi:[0,1]
	v_pk_mul_f32 v[92:93], v[92:93], v[214:215] op_sel_hi:[1,0]
	v_pk_fma_f32 v[92:93], v[224:225], v[92:93], v[136:137]
	v_pk_add_f32 v[94:95], v[94:95], v[16:17] op_sel_hi:[1,0] neg_lo:[0,1] neg_hi:[0,1]
	v_pk_mul_f32 v[94:95], v[94:95], v[214:215] op_sel_hi:[1,0]
	v_pk_fma_f32 v[94:95], v[226:227], v[94:95], v[138:139]
	global_store_dwordx4 v[160:161], v[92:95], off
	v_pk_add_f32 v[88:89], v[88:89], v[16:17] op_sel_hi:[1,0] neg_lo:[0,1] neg_hi:[0,1]
	v_pk_mul_f32 v[88:89], v[88:89], v[214:215] op_sel_hi:[1,0]
	v_pk_fma_f32 v[88:89], v[228:229], v[88:89], v[140:141]
	v_pk_add_f32 v[90:91], v[90:91], v[16:17] op_sel_hi:[1,0] neg_lo:[0,1] neg_hi:[0,1]
	v_pk_mul_f32 v[90:91], v[90:91], v[214:215] op_sel_hi:[1,0]
	v_pk_fma_f32 v[90:91], v[230:231], v[90:91], v[142:143]
	global_store_dwordx4 v[160:161], v[88:91], off offset:64
	v_pk_add_f32 v[20:21], v[20:21], v[16:17] op_sel_hi:[1,0] neg_lo:[0,1] neg_hi:[0,1]
	v_pk_mul_f32 v[20:21], v[20:21], v[214:215] op_sel_hi:[1,0]
	v_pk_fma_f32 v[20:21], v[232:233], v[20:21], v[144:145]
	v_pk_add_f32 v[22:23], v[22:23], v[16:17] op_sel_hi:[1,0] neg_lo:[0,1] neg_hi:[0,1]
	v_pk_mul_f32 v[22:23], v[22:23], v[214:215] op_sel_hi:[1,0]
	v_pk_fma_f32 v[22:23], v[234:235], v[22:23], v[146:147]
	global_store_dwordx4 v[160:161], v[20:23], off offset:512
	v_pk_add_f32 v[192:193], v[192:193], v[16:17] op_sel_hi:[1,0] neg_lo:[0,1] neg_hi:[0,1]
	v_pk_mul_f32 v[192:193], v[192:193], v[214:215] op_sel_hi:[1,0]
	v_pk_fma_f32 v[192:193], v[236:237], v[192:193], v[148:149]
	v_pk_add_f32 v[194:195], v[194:195], v[16:17] op_sel_hi:[1,0] neg_lo:[0,1] neg_hi:[0,1]
	v_pk_mul_f32 v[194:195], v[194:195], v[214:215] op_sel_hi:[1,0]
	v_pk_fma_f32 v[194:195], v[238:239], v[194:195], v[150:151]
	global_store_dwordx4 v[160:161], v[192:195], off offset:576
	v_add_u32_e32 v159, 0x2c00, v156
	global_load_dwordx4 v[0:3], v159, s[10:11]
	global_load_dwordx4 v[4:7], v159, s[10:11] offset:16
	global_load_dwordx4 v[8:11], v159, s[10:11] offset:32
	global_load_dwordx4 v[12:15], v159, s[10:11] offset:48
	s_waitcnt vmcnt(8)
; __global__ void __launch_bounds__(512, 2) fwd_kernel(Args a) {
;     ...
;             for (int q = 0; q < 4; ++q) { float s_ = 0.f;
; #pragma unroll
;                 for (int j = 0; j < 8; ++j) s_ += (vr[q][j][0] + vr[q][j][1]) + (vr[q][j][2] + vr[q][j][3]);
;                 sm[q] = wave_sum(s_) * (1.0f / DMODEL); }
; #pragma unroll
;             for (int q = 0; q < 4; ++q) { float s2 = 0.f;
; #pragma unroll
;                 for (int j = 0; j < 8; ++j) { vr[q][j] = vr[q][j] - sm[q]; s2 += (vr[q][j][0] * vr[q][j][0] + vr[q][j][1] * vr[q][j][1]) + (vr[q][j][2] * vr[q][j][2] + vr[q][j][3] * vr[q][j][3]); }
;                 qq[q] = wave_sum(s2); rs[q] = 1.0f / sqrtf(qq[q] * (1.0f / DMODEL) + LN_EPS); }
; #pragma unroll
;             for (int q = 0; q < 4; ++q)
; #pragma unroll
;                 for (int j = 0; j < 8; ++j) __builtin_nontemporal_store(vr[q][j] * rs[q] * ggv[j] + bbv[j], xr + 512 * q + 64 * j); }
	v_add_f32_e32 v16, v198, v200
	v_add_f32_e32 v16, v16, v202
	v_add_f32_e32 v16, v16, v204
	v_add_f32_e32 v16, v16, v206
	v_add_f32_e32 v16, v16, v208
	v_add_f32_e32 v16, v16, v210
	v_add_f32_e32 v16, v16, v212
	v_mul_f32_e32 v16, 0x3a000000, v16
	v_add_f32_e32 v17, v199, v201
	v_add_f32_e32 v17, v17, v203
	v_add_f32_e32 v17, v17, v205
	v_add_f32_e32 v17, v17, v207
	v_add_f32_e32 v17, v17, v209
	v_add_f32_e32 v17, v17, v211
	v_add_f32_e32 v17, v17, v213
	v_fma_f32 v18, v198, s9, -v16
	v_mul_f32_e32 v18, v18, v18
	v_fmac_f32_e32 v17, 0x43800000, v18
	v_fma_f32 v18, v200, s9, -v16
	v_mul_f32_e32 v18, v18, v18
	v_fmac_f32_e32 v17, 0x43800000, v18
	v_fma_f32 v18, v202, s9, -v16
	v_mul_f32_e32 v18, v18, v18
	v_fmac_f32_e32 v17, 0x43800000, v18
	v_fma_f32 v18, v204, s9, -v16
	v_mul_f32_e32 v18, v18, v18
	v_fmac_f32_e32 v17, 0x43800000, v18
	v_fma_f32 v18, v206, s9, -v16
	v_mul_f32_e32 v18, v18, v18
	v_fmac_f32_e32 v17, 0x43800000, v18
	v_fma_f32 v18, v208, s9, -v16
	v_mul_f32_e32 v18, v18, v18
	v_fmac_f32_e32 v17, 0x43800000, v18
	v_fma_f32 v18, v210, s9, -v16
	v_mul_f32_e32 v18, v18, v18
	v_fmac_f32_e32 v17, 0x43800000, v18
	v_fma_f32 v18, v212, s9, -v16
	v_mul_f32_e32 v18, v18, v18
	v_fmac_f32_e32 v17, 0x43800000, v18
	v_fmamk_f32 v17, v17, 0x3a000000, v157
	v_mul_f32_e32 v18, 0x4f800000, v17
	v_cmp_gt_f32_e32 vcc, s3, v17
	s_nop 1
	v_cndmask_b32_e32 v214, v17, v18, vcc
	v_sqrt_f32_e32 v215, v214
	s_nop 1
	v_add_u32_e32 v216, -1, v215
	v_fma_f32 v217, -v216, v215, v214
	v_cmp_ge_f32_e64 s[14:15], 0, v217
	v_add_u32_e32 v217, 1, v215
	v_fma_f32 v218, -v217, v215, v214
	s_nop 0
	v_cndmask_b32_e64 v216, v215, v216, s[14:15]
	v_cmp_lt_f32_e64 s[14:15], 0, v218
	s_nop 1
	v_cndmask_b32_e64 v216, v216, v217, s[14:15]
	v_mul_f32_e32 v217, 0x37800000, v216
	v_cndmask_b32_e32 v216, v216, v217, vcc
	v_cmp_class_f32_e32 vcc, v214, v158
	s_nop 1
	v_cndmask_b32_e32 v214, v216, v214, vcc
	v_div_scale_f32 v215, s[14:15], v214, v214, 1.0
	v_rcp_f32_e32 v216, v215
	s_nop 1
	v_fma_f32 v217, -v215, v216, 1.0
	v_fmac_f32_e32 v216, v217, v216
	v_div_scale_f32 v217, vcc, 1.0, v214, 1.0
	v_mul_f32_e32 v218, v217, v216
	v_fma_f32 v219, -v215, v218, v217
	v_fmac_f32_e32 v218, v219, v216
	v_fma_f32 v217, -v215, v218, v217
	s_nop 1
	v_div_fmas_f32 v215, v217, v216, v218
	v_div_fixup_f32 v214, v215, v214, 1.0
	s_mov_b64 s[12:13], 0x140000
	v_lshl_add_u64 v[160:161], v[152:153], 0, s[12:13]
	v_pk_add_f32 v[84:85], v[84:85], v[16:17] op_sel_hi:[1,0] neg_lo:[0,1] neg_hi:[0,1]
	v_pk_mul_f32 v[84:85], v[84:85], v[214:215] op_sel_hi:[1,0]
	v_pk_fma_f32 v[84:85], v[224:225], v[84:85], v[136:137]
	v_pk_add_f32 v[86:87], v[86:87], v[16:17] op_sel_hi:[1,0] neg_lo:[0,1] neg_hi:[0,1]
	v_pk_mul_f32 v[86:87], v[86:87], v[214:215] op_sel_hi:[1,0]
	v_pk_fma_f32 v[86:87], v[226:227], v[86:87], v[138:139]
	global_store_dwordx4 v[160:161], v[84:87], off
	v_pk_add_f32 v[80:81], v[80:81], v[16:17] op_sel_hi:[1,0] neg_lo:[0,1] neg_hi:[0,1]
	v_pk_mul_f32 v[80:81], v[80:81], v[214:215] op_sel_hi:[1,0]
	v_pk_fma_f32 v[80:81], v[228:229], v[80:81], v[140:141]
	v_pk_add_f32 v[82:83], v[82:83], v[16:17] op_sel_hi:[1,0] neg_lo:[0,1] neg_hi:[0,1]
	v_pk_mul_f32 v[82:83], v[82:83], v[214:215] op_sel_hi:[1,0]
	v_pk_fma_f32 v[82:83], v[230:231], v[82:83], v[142:143]
	global_store_dwordx4 v[160:161], v[80:83], off offset:64
	v_pk_add_f32 v[188:189], v[188:189], v[16:17] op_sel_hi:[1,0] neg_lo:[0,1] neg_hi:[0,1]
	v_pk_mul_f32 v[188:189], v[188:189], v[214:215] op_sel_hi:[1,0]
	v_pk_fma_f32 v[188:189], v[232:233], v[188:189], v[144:145]
	v_pk_add_f32 v[190:191], v[190:191], v[16:17] op_sel_hi:[1,0] neg_lo:[0,1] neg_hi:[0,1]
	v_pk_mul_f32 v[190:191], v[190:191], v[214:215] op_sel_hi:[1,0]
	v_pk_fma_f32 v[190:191], v[234:235], v[190:191], v[146:147]
	global_store_dwordx4 v[160:161], v[188:191], off offset:512
	v_pk_add_f32 v[184:185], v[184:185], v[16:17] op_sel_hi:[1,0] neg_lo:[0,1] neg_hi:[0,1]
	v_pk_mul_f32 v[184:185], v[184:185], v[214:215] op_sel_hi:[1,0]
	v_pk_fma_f32 v[184:185], v[236:237], v[184:185], v[148:149]
	v_pk_add_f32 v[186:187], v[186:187], v[16:17] op_sel_hi:[1,0] neg_lo:[0,1] neg_hi:[0,1]
	v_pk_mul_f32 v[186:187], v[186:187], v[214:215] op_sel_hi:[1,0]
	v_pk_fma_f32 v[186:187], v[238:239], v[186:187], v[150:151]
	global_store_dwordx4 v[160:161], v[184:187], off offset:576
	s_waitcnt vmcnt(4)
; __global__ void __launch_bounds__(512, 2) fwd_kernel(Args a) {
;     ...
;             for (int q = 0; q < 4; ++q) { float s_ = 0.f;
; #pragma unroll
;                 for (int j = 0; j < 8; ++j) s_ += (vr[q][j][0] + vr[q][j][1]) + (vr[q][j][2] + vr[q][j][3]);
;                 sm[q] = wave_sum(s_) * (1.0f / DMODEL); }
; #pragma unroll
;             for (int q = 0; q < 4; ++q) { float s2 = 0.f;
; #pragma unroll
;                 for (int j = 0; j < 8; ++j) { vr[q][j] = vr[q][j] - sm[q]; s2 += (vr[q][j][0] * vr[q][j][0] + vr[q][j][1] * vr[q][j][1]) + (vr[q][j][2] * vr[q][j][2] + vr[q][j][3] * vr[q][j][3]); }
;                 qq[q] = wave_sum(s2); rs[q] = 1.0f / sqrtf(qq[q] * (1.0f / DMODEL) + LN_EPS); }
; #pragma unroll
;             for (int q = 0; q < 4; ++q)
; #pragma unroll
;                 for (int j = 0; j < 8; ++j) __builtin_nontemporal_store(vr[q][j] * rs[q] * ggv[j] + bbv[j], xr + 512 * q + 64 * j); }
	v_add_f32_e32 v16, v0, v2
	v_add_f32_e32 v16, v16, v4
	v_add_f32_e32 v16, v16, v6
	v_add_f32_e32 v16, v16, v8
	v_add_f32_e32 v16, v16, v10
	v_add_f32_e32 v16, v16, v12
	v_add_f32_e32 v16, v16, v14
	v_mul_f32_e32 v16, 0x3a000000, v16
	v_add_f32_e32 v17, v1, v3
	v_add_f32_e32 v17, v17, v5
	v_add_f32_e32 v17, v17, v7
	v_add_f32_e32 v17, v17, v9
	v_add_f32_e32 v17, v17, v11
	v_add_f32_e32 v17, v17, v13
	v_add_f32_e32 v17, v17, v15
	v_fma_f32 v18, v0, s9, -v16
	v_mul_f32_e32 v18, v18, v18
	v_fmac_f32_e32 v17, 0x43800000, v18
	v_fma_f32 v18, v2, s9, -v16
	v_mul_f32_e32 v18, v18, v18
	v_fmac_f32_e32 v17, 0x43800000, v18
	v_fma_f32 v18, v4, s9, -v16
	v_mul_f32_e32 v18, v18, v18
	v_fmac_f32_e32 v17, 0x43800000, v18
	v_fma_f32 v18, v6, s9, -v16
	v_mul_f32_e32 v18, v18, v18
	v_fmac_f32_e32 v17, 0x43800000, v18
	v_fma_f32 v18, v8, s9, -v16
	v_mul_f32_e32 v18, v18, v18
	v_fmac_f32_e32 v17, 0x43800000, v18
	v_fma_f32 v18, v10, s9, -v16
	v_mul_f32_e32 v18, v18, v18
	v_fmac_f32_e32 v17, 0x43800000, v18
	v_fma_f32 v18, v12, s9, -v16
	v_mul_f32_e32 v18, v18, v18
	v_fmac_f32_e32 v17, 0x43800000, v18
	v_fma_f32 v18, v14, s9, -v16
	v_mul_f32_e32 v18, v18, v18
	v_fmac_f32_e32 v17, 0x43800000, v18
	v_fmamk_f32 v17, v17, 0x3a000000, v157
	v_mul_f32_e32 v18, 0x4f800000, v17
	v_cmp_gt_f32_e32 vcc, s3, v17
	s_nop 1
	v_cndmask_b32_e32 v214, v17, v18, vcc
	v_sqrt_f32_e32 v215, v214
	s_nop 1
	v_add_u32_e32 v216, -1, v215
	v_fma_f32 v217, -v216, v215, v214
	v_cmp_ge_f32_e64 s[14:15], 0, v217
	v_add_u32_e32 v217, 1, v215
	v_fma_f32 v218, -v217, v215, v214
	s_nop 0
	v_cndmask_b32_e64 v216, v215, v216, s[14:15]
	v_cmp_lt_f32_e64 s[14:15], 0, v218
	s_nop 1
	v_cndmask_b32_e64 v216, v216, v217, s[14:15]
	v_mul_f32_e32 v217, 0x37800000, v216
	v_cndmask_b32_e32 v216, v216, v217, vcc
	v_cmp_class_f32_e32 vcc, v214, v158
	s_nop 1
	v_cndmask_b32_e32 v214, v216, v214, vcc
	v_div_scale_f32 v215, s[14:15], v214, v214, 1.0
	v_rcp_f32_e32 v216, v215
	s_nop 1
	v_fma_f32 v217, -v215, v216, 1.0
	v_fmac_f32_e32 v216, v217, v216
	v_div_scale_f32 v217, vcc, 1.0, v214, 1.0
	v_mul_f32_e32 v218, v217, v216
	v_fma_f32 v219, -v215, v218, v217
	v_fmac_f32_e32 v218, v219, v216
	v_fma_f32 v217, -v215, v218, v217
	s_nop 1
	v_div_fmas_f32 v215, v217, v216, v218
	v_div_fixup_f32 v214, v215, v214, 1.0
	s_mov_b64 s[12:13], 0x160000
	v_lshl_add_u64 v[160:161], v[152:153], 0, s[12:13]
	v_pk_add_f32 v[76:77], v[76:77], v[16:17] op_sel_hi:[1,0] neg_lo:[0,1] neg_hi:[0,1]
	v_pk_mul_f32 v[76:77], v[76:77], v[214:215] op_sel_hi:[1,0]
	v_pk_fma_f32 v[76:77], v[224:225], v[76:77], v[136:137]
	v_pk_add_f32 v[78:79], v[78:79], v[16:17] op_sel_hi:[1,0] neg_lo:[0,1] neg_hi:[0,1]
	v_pk_mul_f32 v[78:79], v[78:79], v[214:215] op_sel_hi:[1,0]
	v_pk_fma_f32 v[78:79], v[226:227], v[78:79], v[138:139]
	global_store_dwordx4 v[160:161], v[76:79], off
	v_pk_add_f32 v[72:73], v[72:73], v[16:17] op_sel_hi:[1,0] neg_lo:[0,1] neg_hi:[0,1]
	v_pk_mul_f32 v[72:73], v[72:73], v[214:215] op_sel_hi:[1,0]
	v_pk_fma_f32 v[72:73], v[228:229], v[72:73], v[140:141]
	v_pk_add_f32 v[74:75], v[74:75], v[16:17] op_sel_hi:[1,0] neg_lo:[0,1] neg_hi:[0,1]
	v_pk_mul_f32 v[74:75], v[74:75], v[214:215] op_sel_hi:[1,0]
	v_pk_fma_f32 v[74:75], v[230:231], v[74:75], v[142:143]
	global_store_dwordx4 v[160:161], v[72:75], off offset:64
	v_pk_add_f32 v[180:181], v[180:181], v[16:17] op_sel_hi:[1,0] neg_lo:[0,1] neg_hi:[0,1]
	v_pk_mul_f32 v[180:181], v[180:181], v[214:215] op_sel_hi:[1,0]
	v_pk_fma_f32 v[180:181], v[232:233], v[180:181], v[144:145]
	v_pk_add_f32 v[182:183], v[182:183], v[16:17] op_sel_hi:[1,0] neg_lo:[0,1] neg_hi:[0,1]
	v_pk_mul_f32 v[182:183], v[182:183], v[214:215] op_sel_hi:[1,0]
	v_pk_fma_f32 v[182:183], v[234:235], v[182:183], v[146:147]
	global_store_dwordx4 v[160:161], v[180:183], off offset:512
	v_pk_add_f32 v[176:177], v[176:177], v[16:17] op_sel_hi:[1,0] neg_lo:[0,1] neg_hi:[0,1]
	v_pk_mul_f32 v[176:177], v[176:177], v[214:215] op_sel_hi:[1,0]
	v_pk_fma_f32 v[176:177], v[236:237], v[176:177], v[148:149]
	v_pk_add_f32 v[178:179], v[178:179], v[16:17] op_sel_hi:[1,0] neg_lo:[0,1] neg_hi:[0,1]
	v_pk_mul_f32 v[178:179], v[178:179], v[214:215] op_sel_hi:[1,0]
	v_pk_fma_f32 v[178:179], v[238:239], v[178:179], v[150:151]
	global_store_dwordx4 v[160:161], v[176:179], off offset:576
